# fast rsq/rcp in epilogues+retB, LDS-staged row scales for up-GEMM epilogues, unrolled dil_combine
# speedup vs baseline: 1.0111x; 1.0095x over previous
.LBB0_292:
	s_waitcnt vmcnt(0)
	v_fmamk_f32 v176, v178, 0x3a800000, v230
	v_mov_b32_e32 v217, v216
	s_nop 0
	v_rsq_f32_e32 v176, v176
	s_mov_b64 s[0:1], -1
	v_pk_fma_f32 v[142:143], v[142:143], v[176:177], 0 op_sel_hi:[1,0,0]
	v_pk_fma_f32 v[140:141], v[140:141], v[176:177], 0 op_sel_hi:[1,0,0]
	v_pk_fma_f32 v[138:139], v[138:139], v[176:177], 0 op_sel_hi:[1,0,0]
	v_pk_fma_f32 v[136:137], v[136:137], v[176:177], 0 op_sel_hi:[1,0,0]
	v_pk_fma_f32 v[134:135], v[134:135], v[176:177], 0 op_sel_hi:[1,0,0]
	v_pk_fma_f32 v[132:133], v[132:133], v[176:177], 0 op_sel_hi:[1,0,0]
	v_pk_fma_f32 v[130:131], v[130:131], v[176:177], 0 op_sel_hi:[1,0,0]
	v_pk_fma_f32 v[128:129], v[128:129], v[176:177], 0 op_sel_hi:[1,0,0]
	s_and_b64 vcc, exec, s[2:3]
	s_cbranch_vccz .LBB0_296
	v_mov_b64_e32 v[178:179], v[142:143]
	v_mov_b64_e32 v[190:191], v[138:139]
	v_mov_b64_e32 v[182:183], v[134:135]
	v_mov_b64_e32 v[186:187], v[130:131]
	s_and_b64 vcc, exec, s[10:11]
	v_mov_b64_e32 v[176:177], v[140:141]
	v_mov_b64_e32 v[188:189], v[136:137]
	v_mov_b64_e32 v[180:181], v[132:133]
	v_mov_b64_e32 v[184:185], v[128:129]
	s_cbranch_vccnz .LBB0_295
	v_pk_mul_f32 v[176:177], v[142:143], v[142:143]
	v_pk_mul_f32 v[178:179], v[140:141], v[140:141]
	s_nop 0
	v_pk_mov_b32 v[180:181], v[178:179], v[176:177] op_sel:[1,0]
	v_mov_b32_e32 v179, v177
	v_pk_add_f32 v[176:177], v[180:181], v[178:179]
	v_pk_mul_f32 v[178:179], v[138:139], v[138:139]
	v_pk_add_f32 v[176:177], v[176:177], v[176:177] op_sel_hi:[0,1]
	v_pk_mul_f32 v[180:181], v[136:137], v[136:137]
	v_mul_f32_e32 v176, v132, v132
	v_pk_mov_b32 v[182:183], v[180:181], v[178:179] op_sel:[1,0]
	v_mov_b32_e32 v181, v179
	v_pk_add_f32 v[178:179], v[182:183], v[180:181]
	v_pk_fma_f32 v[180:181], v[132:133], v[132:133], v[176:177] op_sel_hi:[1,1,0]
	v_mul_f32_e32 v176, v134, v134
	v_pk_add_f32 v[178:179], v[178:179], v[178:179] op_sel_hi:[0,1]
	v_pk_fma_f32 v[182:183], v[134:135], v[134:135], v[176:177] op_sel_hi:[1,1,0]
	v_mul_f32_e32 v180, v128, v128
	v_mul_f32_e32 v182, v129, v129
	v_mul_f32_e32 v176, v130, v130
	v_mul_f32_e32 v178, v131, v131
	v_pk_add_f32 v[180:181], v[180:181], v[182:183]
	v_pk_add_f32 v[176:177], v[176:177], v[178:179]
	v_and_b32_e32 v178, 64, v234
	v_pk_add_f32 v[176:177], v[180:181], v[176:177]
	v_add_u32_e32 v178, 64, v178
	v_add_f32_e32 v176, v176, v177
	v_xor_b32_e32 v177, 16, v234
	v_cmp_lt_i32_e32 vcc, v177, v178
	s_nop 1
	v_cndmask_b32_e32 v177, v234, v177, vcc
	v_lshlrev_b32_e32 v190, 2, v177
	ds_bpermute_b32 v177, v190, v176
	s_waitcnt lgkmcnt(0)
	v_add_f32_e32 v176, v176, v177
	v_xor_b32_e32 v177, 32, v234
	v_cmp_lt_i32_e32 vcc, v177, v178
	s_nop 1
	v_cndmask_b32_e32 v177, v234, v177, vcc
	v_lshlrev_b32_e32 v177, 2, v177
	ds_bpermute_b32 v177, v177, v176
	s_waitcnt lgkmcnt(0)
	v_add_f32_e32 v176, v176, v177
	v_fmamk_f32 v176, v176, 0x3c800000, v230
	v_rsq_f32_e32 v176, v176
	s_nop 0
	v_pk_mul_f32 v[178:179], v[140:141], v[176:177] op_sel_hi:[1,0]
	v_pk_mul_f32 v[188:189], v[132:133], v[176:177] op_sel_hi:[1,0]
	v_pk_mul_f32 v[180:181], v[142:143], v[176:177] op_sel_hi:[1,0]
	v_pk_mul_f32 v[178:179], v[36:37], v[178:179]
	v_pk_mul_f32 v[182:183], v[136:137], v[176:177] op_sel_hi:[1,0]
	v_pk_mul_f32 v[184:185], v[138:139], v[176:177] op_sel_hi:[1,0]
	v_pk_mul_f32 v[186:187], v[134:135], v[176:177] op_sel_hi:[1,0]
	v_pk_mul_f32 v[236:237], v[44:45], v[188:189]
	v_pk_mul_f32 v[188:189], v[130:131], v[176:177] op_sel_hi:[1,0]
	v_pk_mul_f32 v[176:177], v[128:129], v[176:177] op_sel_hi:[1,0]
	ds_bpermute_b32 v191, v190, v178
	v_pk_mul_f32 v[238:239], v[40:41], v[176:177]
	ds_bpermute_b32 v177, v190, v179
	v_pk_mul_f32 v[180:181], v[38:39], v[180:181]
	v_pk_mul_f32 v[182:183], v[32:33], v[182:183]
	s_waitcnt lgkmcnt(1)
	v_mul_f32_e32 v176, v164, v191
	v_cndmask_b32_e64 v176, v176, -v176, s[4:5]
	s_waitcnt lgkmcnt(0)
	v_mul_f32_e32 v177, v165, v177
	v_cndmask_b32_e64 v177, v177, -v177, s[4:5]
	v_fmac_f32_e32 v176, v160, v178
	v_fmac_f32_e32 v177, v161, v179
	v_cndmask_b32_e64 v176, v178, v176, s[6:7]
	ds_bpermute_b32 v178, v190, v180
	v_cndmask_b32_e64 v177, v179, v177, s[6:7]
	ds_bpermute_b32 v179, v190, v181
	v_pk_mul_f32 v[184:185], v[34:35], v[184:185]
	v_pk_mul_f32 v[186:187], v[46:47], v[186:187]
	s_waitcnt lgkmcnt(1)
	v_mul_f32_e32 v178, v166, v178
	v_cndmask_b32_e64 v178, v178, -v178, s[4:5]
	s_waitcnt lgkmcnt(0)
	v_mul_f32_e32 v179, v167, v179
	v_cndmask_b32_e64 v179, v179, -v179, s[4:5]
	v_fmac_f32_e32 v178, v162, v180
	v_fmac_f32_e32 v179, v163, v181
	v_cndmask_b32_e64 v178, v180, v178, s[6:7]
	ds_bpermute_b32 v180, v190, v182
	v_cndmask_b32_e64 v179, v181, v179, s[6:7]
	ds_bpermute_b32 v181, v190, v183
	v_pk_mul_f32 v[240:241], v[42:43], v[188:189]
	v_pk_mul_f32 v[176:177], v[216:217], v[176:177]
	s_waitcnt lgkmcnt(1)
	v_mul_f32_e32 v180, v172, v180
	v_cndmask_b32_e64 v180, v180, -v180, s[4:5]
	s_waitcnt lgkmcnt(0)
	v_mul_f32_e32 v181, v173, v181
	v_cndmask_b32_e64 v181, v181, -v181, s[4:5]
	v_fmac_f32_e32 v180, v168, v182
	v_fmac_f32_e32 v181, v169, v183
	v_cndmask_b32_e64 v180, v182, v180, s[6:7]
	ds_bpermute_b32 v182, v190, v184
	v_cndmask_b32_e64 v181, v183, v181, s[6:7]
	ds_bpermute_b32 v183, v190, v185
	v_pk_mul_f32 v[188:189], v[216:217], v[180:181]
	v_pk_mul_f32 v[180:181], v[216:217], v[236:237]
	s_waitcnt lgkmcnt(1)
	v_mul_f32_e32 v182, v174, v182
	v_cndmask_b32_e64 v182, v182, -v182, s[4:5]
	s_waitcnt lgkmcnt(0)
	v_mul_f32_e32 v183, v175, v183
	v_cndmask_b32_e64 v183, v183, -v183, s[4:5]
	v_fmac_f32_e32 v182, v170, v184
	v_fmac_f32_e32 v183, v171, v185
	v_cndmask_b32_e64 v182, v184, v182, s[6:7]
	v_cndmask_b32_e64 v183, v185, v183, s[6:7]
	v_mov_b32_e32 v184, v216
	v_mov_b32_e32 v185, v216
	v_pk_mul_f32 v[178:179], v[184:185], v[178:179]
	v_pk_mul_f32 v[190:191], v[184:185], v[182:183]
	v_pk_mul_f32 v[182:183], v[184:185], v[186:187]
	v_pk_mul_f32 v[186:187], v[184:185], v[240:241]
	v_pk_mul_f32 v[184:185], v[216:217], v[238:239]

.LBB0_298:
	v_fmamk_f32 v134, v200, 0x3a800000, v230
	s_lshl_b32 s36, s27, 6
	v_mov_b64_e32 v[128:129], s[18:19]
	v_rsq_f32_e32 v134, v134
	s_ashr_i32 s37, s36, 31
	v_mad_i64_i32 v[128:129], s[0:1], v218, s57, v[128:129]
	v_lshl_add_u64 v[128:129], s[36:37], 1, v[128:129]
	v_mov_b32_e32 v215, v201
	v_lshl_add_u64 v[132:133], v[128:129], 0, v[214:215]
	v_cvt_pk_bf16_f32 v128, v176, v177
	v_cvt_pk_bf16_f32 v129, v178, v179
	v_cvt_pk_bf16_f32 v130, v188, v189
	v_cvt_pk_bf16_f32 v131, v190, v191
	global_store_dwordx4 v[132:133], v[128:131], off
	s_nop 1
	v_cvt_pk_bf16_f32 v128, v180, v181
	v_cvt_pk_bf16_f32 v129, v182, v183
	s_nop 0
	v_cvt_pk_bf16_f32 v131, v186, v187
	s_nop 0
	v_cvt_pk_bf16_f32 v130, v184, v185
	global_store_dwordx4 v[132:133], v[128:131], off offset:64
	s_mov_b64 s[0:1], -1
	s_nop 0
	v_mov_b32_e32 v128, v134
	v_pk_fma_f32 v[126:127], v[126:127], v[128:129], 0 op_sel_hi:[1,0,0]
	v_pk_fma_f32 v[124:125], v[124:125], v[128:129], 0 op_sel_hi:[1,0,0]
	v_pk_fma_f32 v[122:123], v[122:123], v[128:129], 0 op_sel_hi:[1,0,0]
	v_pk_fma_f32 v[120:121], v[120:121], v[128:129], 0 op_sel_hi:[1,0,0]
	v_pk_fma_f32 v[118:119], v[118:119], v[128:129], 0 op_sel_hi:[1,0,0]
	v_pk_fma_f32 v[116:117], v[116:117], v[128:129], 0 op_sel_hi:[1,0,0]
	v_pk_fma_f32 v[114:115], v[114:115], v[128:129], 0 op_sel_hi:[1,0,0]
	v_pk_fma_f32 v[112:113], v[112:113], v[128:129], 0 op_sel_hi:[1,0,0]
	s_and_b64 vcc, exec, s[12:13]
	s_cbranch_vccnz .LBB0_302
	v_mov_b64_e32 v[130:131], v[126:127]
	v_mov_b64_e32 v[138:139], v[122:123]
	v_mov_b64_e32 v[134:135], v[118:119]
	v_mov_b64_e32 v[142:143], v[114:115]
	s_and_b64 vcc, exec, s[10:11]
	v_mov_b64_e32 v[128:129], v[124:125]
	v_mov_b64_e32 v[136:137], v[120:121]
	v_mov_b64_e32 v[132:133], v[116:117]
	v_mov_b64_e32 v[140:141], v[112:113]
	s_cbranch_vccnz .LBB0_301
	v_pk_mul_f32 v[128:129], v[126:127], v[126:127]
	v_pk_mul_f32 v[130:131], v[124:125], v[124:125]
	s_nop 0
	v_pk_mov_b32 v[132:133], v[130:131], v[128:129] op_sel:[1,0]
	v_mov_b32_e32 v131, v129
	v_pk_add_f32 v[128:129], v[132:133], v[130:131]
	v_pk_mul_f32 v[130:131], v[122:123], v[122:123]
	v_pk_add_f32 v[128:129], v[128:129], v[128:129] op_sel_hi:[0,1]
	v_pk_mul_f32 v[132:133], v[120:121], v[120:121]
	v_mul_f32_e32 v128, v116, v116
	v_pk_mov_b32 v[134:135], v[132:133], v[130:131] op_sel:[1,0]
	v_mov_b32_e32 v133, v131
	v_pk_add_f32 v[130:131], v[134:135], v[132:133]
	v_pk_fma_f32 v[132:133], v[116:117], v[116:117], v[128:129] op_sel_hi:[1,1,0]
	v_mul_f32_e32 v128, v118, v118
	v_pk_add_f32 v[130:131], v[130:131], v[130:131] op_sel_hi:[0,1]
	v_pk_fma_f32 v[134:135], v[118:119], v[118:119], v[128:129] op_sel_hi:[1,1,0]
	v_mul_f32_e32 v132, v112, v112
	v_mul_f32_e32 v134, v113, v113
	v_mul_f32_e32 v128, v114, v114
	v_mul_f32_e32 v130, v115, v115
	v_pk_add_f32 v[132:133], v[132:133], v[134:135]
	v_pk_add_f32 v[128:129], v[128:129], v[130:131]
	v_and_b32_e32 v130, 64, v234
	v_pk_add_f32 v[128:129], v[132:133], v[128:129]
	v_add_u32_e32 v130, 64, v130
	v_add_f32_e32 v128, v128, v129
	v_xor_b32_e32 v129, 16, v234
	v_cmp_lt_i32_e32 vcc, v129, v130
	s_nop 1
	v_cndmask_b32_e32 v129, v234, v129, vcc
	v_lshlrev_b32_e32 v164, 2, v129
	ds_bpermute_b32 v129, v164, v128
	s_waitcnt lgkmcnt(0)
	v_add_f32_e32 v128, v128, v129
	v_xor_b32_e32 v129, 32, v234
	v_cmp_lt_i32_e32 vcc, v129, v130
	s_nop 1
	v_cndmask_b32_e32 v129, v234, v129, vcc
	v_lshlrev_b32_e32 v129, 2, v129
	ds_bpermute_b32 v129, v129, v128
	s_waitcnt lgkmcnt(0)
	v_add_f32_e32 v128, v128, v129
	v_fmamk_f32 v128, v128, 0x3c800000, v230
	v_rsq_f32_e32 v128, v128
	s_nop 0
	v_pk_mul_f32 v[130:131], v[124:125], v[128:129] op_sel_hi:[1,0]
	v_pk_mul_f32 v[138:139], v[118:119], v[128:129] op_sel_hi:[1,0]
	v_pk_mul_f32 v[132:133], v[126:127], v[128:129] op_sel_hi:[1,0]
	v_pk_mul_f32 v[130:131], v[36:37], v[130:131]
	v_pk_mul_f32 v[134:135], v[120:121], v[128:129] op_sel_hi:[1,0]
	v_pk_mul_f32 v[136:137], v[122:123], v[128:129] op_sel_hi:[1,0]
	v_pk_mul_f32 v[140:141], v[116:117], v[128:129] op_sel_hi:[1,0]
	v_pk_mul_f32 v[142:143], v[46:47], v[138:139]
	v_pk_mul_f32 v[138:139], v[114:115], v[128:129] op_sel_hi:[1,0]
	v_pk_mul_f32 v[128:129], v[112:113], v[128:129] op_sel_hi:[1,0]
	ds_bpermute_b32 v165, v164, v130
	v_pk_mul_f32 v[160:161], v[40:41], v[128:129]
	ds_bpermute_b32 v129, v164, v131
	v_pk_mul_f32 v[132:133], v[38:39], v[132:133]
	v_pk_mul_f32 v[134:135], v[32:33], v[134:135]
	s_waitcnt lgkmcnt(1)
	v_mul_f32_e32 v128, v148, v165
	v_cndmask_b32_e64 v128, v128, -v128, s[4:5]
	s_waitcnt lgkmcnt(0)
	v_mul_f32_e32 v129, v149, v129
	v_cndmask_b32_e64 v129, v129, -v129, s[4:5]
	v_fmac_f32_e32 v128, v144, v130
	v_fmac_f32_e32 v129, v145, v131
	v_cndmask_b32_e64 v128, v130, v128, s[6:7]
	ds_bpermute_b32 v130, v164, v132
	v_cndmask_b32_e64 v129, v131, v129, s[6:7]
	ds_bpermute_b32 v131, v164, v133
	v_pk_mul_f32 v[136:137], v[34:35], v[136:137]
	v_pk_mul_f32 v[140:141], v[44:45], v[140:141]
	s_waitcnt lgkmcnt(1)
	v_mul_f32_e32 v130, v150, v130
	v_cndmask_b32_e64 v130, v130, -v130, s[4:5]
	s_waitcnt lgkmcnt(0)
	v_mul_f32_e32 v131, v151, v131
	v_cndmask_b32_e64 v131, v131, -v131, s[4:5]
	v_fmac_f32_e32 v130, v146, v132
	v_fmac_f32_e32 v131, v147, v133
	v_cndmask_b32_e64 v130, v132, v130, s[6:7]
	ds_bpermute_b32 v132, v164, v134
	v_cndmask_b32_e64 v131, v133, v131, s[6:7]
	ds_bpermute_b32 v133, v164, v135
	v_pk_mul_f32 v[162:163], v[42:43], v[138:139]
	v_mov_b32_e32 v165, v216
	s_waitcnt lgkmcnt(1)
	v_mul_f32_e32 v132, v156, v132
	v_cndmask_b32_e64 v132, v132, -v132, s[4:5]
	s_waitcnt lgkmcnt(0)
	v_mul_f32_e32 v133, v157, v133
	v_cndmask_b32_e64 v133, v133, -v133, s[4:5]
	v_fmac_f32_e32 v132, v152, v134
	v_fmac_f32_e32 v133, v153, v135
	v_cndmask_b32_e64 v132, v134, v132, s[6:7]
	ds_bpermute_b32 v134, v164, v136
	v_cndmask_b32_e64 v133, v135, v133, s[6:7]
	ds_bpermute_b32 v135, v164, v137
	v_mov_b32_e32 v164, v216
	v_pk_mul_f32 v[130:131], v[164:165], v[130:131]
	s_waitcnt lgkmcnt(1)
	v_mul_f32_e32 v134, v158, v134
	v_cndmask_b32_e64 v134, v134, -v134, s[4:5]
	s_waitcnt lgkmcnt(0)
	v_mul_f32_e32 v135, v159, v135
	v_cndmask_b32_e64 v135, v135, -v135, s[4:5]
	v_fmac_f32_e32 v134, v154, v136
	v_fmac_f32_e32 v135, v155, v137
	v_cndmask_b32_e64 v134, v136, v134, s[6:7]
	v_cndmask_b32_e64 v135, v137, v135, s[6:7]
	v_pk_mul_f32 v[128:129], v[216:217], v[128:129]
	v_pk_mul_f32 v[138:139], v[164:165], v[134:135]
	v_pk_mul_f32 v[136:137], v[216:217], v[132:133]
	v_pk_mul_f32 v[134:135], v[164:165], v[142:143]
	v_pk_mul_f32 v[132:133], v[216:217], v[140:141]
	v_pk_mul_f32 v[142:143], v[164:165], v[162:163]
	v_pk_mul_f32 v[140:141], v[216:217], v[160:161]

.LBB0_324:
	s_waitcnt vmcnt(1)
	v_fmamk_f32 v144, v146, 0x3a800000, v230
	v_rsq_f32_e32 v144, v144
	s_mov_b64 s[0:1], -1
	v_pk_fma_f32 v[110:111], v[110:111], v[144:145], 0 op_sel_hi:[1,0,0]
	v_pk_fma_f32 v[108:109], v[108:109], v[144:145], 0 op_sel_hi:[1,0,0]
	v_pk_fma_f32 v[106:107], v[106:107], v[144:145], 0 op_sel_hi:[1,0,0]
	v_pk_fma_f32 v[104:105], v[104:105], v[144:145], 0 op_sel_hi:[1,0,0]
	v_pk_fma_f32 v[102:103], v[102:103], v[144:145], 0 op_sel_hi:[1,0,0]
	v_pk_fma_f32 v[100:101], v[100:101], v[144:145], 0 op_sel_hi:[1,0,0]
	v_pk_fma_f32 v[98:99], v[98:99], v[144:145], 0 op_sel_hi:[1,0,0]
	v_pk_fma_f32 v[96:97], v[96:97], v[144:145], 0 op_sel_hi:[1,0,0]
	s_and_b64 vcc, exec, s[12:13]
	s_cbranch_vccnz .LBB0_328
	v_mov_b64_e32 v[146:147], v[110:111]
	v_mov_b64_e32 v[158:159], v[106:107]
	v_mov_b64_e32 v[150:151], v[102:103]
	v_mov_b64_e32 v[154:155], v[98:99]
	s_and_b64 vcc, exec, s[10:11]
	v_mov_b64_e32 v[144:145], v[108:109]
	v_mov_b64_e32 v[156:157], v[104:105]
	v_mov_b64_e32 v[148:149], v[100:101]
	v_mov_b64_e32 v[152:153], v[96:97]
	s_cbranch_vccnz .LBB0_327
	v_pk_mul_f32 v[144:145], v[110:111], v[110:111]
	v_pk_mul_f32 v[146:147], v[108:109], v[108:109]
	s_nop 0
	v_pk_mov_b32 v[148:149], v[146:147], v[144:145] op_sel:[1,0]
	v_mov_b32_e32 v147, v145
	v_pk_add_f32 v[144:145], v[148:149], v[146:147]
	v_pk_mul_f32 v[146:147], v[106:107], v[106:107]
	v_pk_add_f32 v[144:145], v[144:145], v[144:145] op_sel_hi:[0,1]
	v_pk_mul_f32 v[148:149], v[104:105], v[104:105]
	v_mul_f32_e32 v144, v100, v100
	v_pk_mov_b32 v[150:151], v[148:149], v[146:147] op_sel:[1,0]
	v_mov_b32_e32 v149, v147
	v_pk_add_f32 v[146:147], v[150:151], v[148:149]
	v_pk_fma_f32 v[148:149], v[100:101], v[100:101], v[144:145] op_sel_hi:[1,1,0]
	v_mul_f32_e32 v144, v102, v102
	v_pk_add_f32 v[146:147], v[146:147], v[146:147] op_sel_hi:[0,1]
	v_pk_fma_f32 v[150:151], v[102:103], v[102:103], v[144:145] op_sel_hi:[1,1,0]
	v_mul_f32_e32 v148, v96, v96
	v_mul_f32_e32 v150, v97, v97
	v_mul_f32_e32 v144, v98, v98
	v_mul_f32_e32 v146, v99, v99
	v_pk_add_f32 v[148:149], v[148:149], v[150:151]
	v_pk_add_f32 v[144:145], v[144:145], v[146:147]
	v_and_b32_e32 v146, 64, v234
	v_pk_add_f32 v[144:145], v[148:149], v[144:145]
	v_add_u32_e32 v146, 64, v146
	v_add_f32_e32 v144, v144, v145
	v_xor_b32_e32 v145, 16, v234
	v_cmp_lt_i32_e32 vcc, v145, v146
	s_nop 1
	v_cndmask_b32_e32 v145, v234, v145, vcc
	v_lshlrev_b32_e32 v158, 2, v145
	ds_bpermute_b32 v145, v158, v144
	s_waitcnt lgkmcnt(0)
	v_add_f32_e32 v144, v144, v145
	v_xor_b32_e32 v145, 32, v234
	v_cmp_lt_i32_e32 vcc, v145, v146
	s_nop 1
	v_cndmask_b32_e32 v145, v234, v145, vcc
	v_lshlrev_b32_e32 v145, 2, v145
	ds_bpermute_b32 v145, v145, v144
	s_waitcnt lgkmcnt(0)
	v_add_f32_e32 v144, v144, v145
	v_fmamk_f32 v144, v144, 0x3c800000, v230
	v_rsq_f32_e32 v144, v144
	s_nop 0
	v_pk_mul_f32 v[146:147], v[108:109], v[144:145] op_sel_hi:[1,0]
	v_pk_mul_f32 v[156:157], v[100:101], v[144:145] op_sel_hi:[1,0]
	v_pk_mul_f32 v[148:149], v[110:111], v[144:145] op_sel_hi:[1,0]
	v_pk_mul_f32 v[146:147], v[36:37], v[146:147]
	v_pk_mul_f32 v[150:151], v[104:105], v[144:145] op_sel_hi:[1,0]
	v_pk_mul_f32 v[152:153], v[106:107], v[144:145] op_sel_hi:[1,0]
	v_pk_mul_f32 v[154:155], v[102:103], v[144:145] op_sel_hi:[1,0]
	v_pk_mul_f32 v[164:165], v[44:45], v[156:157]
	v_pk_mul_f32 v[156:157], v[98:99], v[144:145] op_sel_hi:[1,0]
	v_pk_mul_f32 v[144:145], v[96:97], v[144:145] op_sel_hi:[1,0]
	ds_bpermute_b32 v159, v158, v146
	v_pk_mul_f32 v[166:167], v[40:41], v[144:145]
	ds_bpermute_b32 v145, v158, v147
	v_pk_mul_f32 v[148:149], v[38:39], v[148:149]
	v_pk_mul_f32 v[150:151], v[32:33], v[150:151]
	s_waitcnt lgkmcnt(1)
	v_mul_f32_e32 v144, v132, v159
	v_cndmask_b32_e64 v144, v144, -v144, s[4:5]
	s_waitcnt lgkmcnt(0)
	v_mul_f32_e32 v145, v133, v145
	v_cndmask_b32_e64 v145, v145, -v145, s[4:5]
	v_fmac_f32_e32 v144, v128, v146
	v_fmac_f32_e32 v145, v129, v147
	v_cndmask_b32_e64 v144, v146, v144, s[6:7]
	ds_bpermute_b32 v146, v158, v148
	v_cndmask_b32_e64 v145, v147, v145, s[6:7]
	ds_bpermute_b32 v147, v158, v149
	v_pk_mul_f32 v[152:153], v[34:35], v[152:153]
	v_pk_mul_f32 v[154:155], v[46:47], v[154:155]
	s_waitcnt lgkmcnt(1)
	v_mul_f32_e32 v146, v134, v146
	v_cndmask_b32_e64 v146, v146, -v146, s[4:5]
	s_waitcnt lgkmcnt(0)
	v_mul_f32_e32 v147, v135, v147
	v_cndmask_b32_e64 v147, v147, -v147, s[4:5]
	v_fmac_f32_e32 v146, v130, v148
	v_fmac_f32_e32 v147, v131, v149
	v_cndmask_b32_e64 v146, v148, v146, s[6:7]
	ds_bpermute_b32 v148, v158, v150
	v_cndmask_b32_e64 v147, v149, v147, s[6:7]
	ds_bpermute_b32 v149, v158, v151
	v_pk_mul_f32 v[168:169], v[42:43], v[156:157]
	v_pk_mul_f32 v[144:145], v[216:217], v[144:145]
	s_waitcnt lgkmcnt(1)
	v_mul_f32_e32 v148, v140, v148
	v_cndmask_b32_e64 v148, v148, -v148, s[4:5]
	s_waitcnt lgkmcnt(0)
	v_mul_f32_e32 v149, v141, v149
	v_cndmask_b32_e64 v149, v149, -v149, s[4:5]
	v_fmac_f32_e32 v148, v136, v150
	v_fmac_f32_e32 v149, v137, v151
	v_cndmask_b32_e64 v148, v150, v148, s[6:7]
	ds_bpermute_b32 v150, v158, v152
	v_cndmask_b32_e64 v149, v151, v149, s[6:7]
	ds_bpermute_b32 v151, v158, v153
	v_pk_mul_f32 v[156:157], v[216:217], v[148:149]
	v_pk_mul_f32 v[148:149], v[216:217], v[164:165]
	s_waitcnt lgkmcnt(1)
	v_mul_f32_e32 v150, v142, v150
	v_cndmask_b32_e64 v150, v150, -v150, s[4:5]
	s_waitcnt lgkmcnt(0)
	v_mul_f32_e32 v151, v143, v151
	v_cndmask_b32_e64 v151, v151, -v151, s[4:5]
	v_fmac_f32_e32 v150, v138, v152
	v_fmac_f32_e32 v151, v139, v153
	v_cndmask_b32_e64 v150, v152, v150, s[6:7]
	v_cndmask_b32_e64 v151, v153, v151, s[6:7]
	v_mov_b32_e32 v152, v216
	v_mov_b32_e32 v153, v216
	v_pk_mul_f32 v[146:147], v[152:153], v[146:147]
	v_pk_mul_f32 v[158:159], v[152:153], v[150:151]
	v_pk_mul_f32 v[150:151], v[152:153], v[154:155]
	v_pk_mul_f32 v[154:155], v[152:153], v[168:169]
	v_pk_mul_f32 v[152:153], v[216:217], v[166:167]

.LBB0_330:
	s_waitcnt vmcnt(0)
	v_fmamk_f32 v102, v163, 0x3a800000, v230
	v_mov_b64_e32 v[96:97], s[18:19]
	v_mad_i64_i32 v[96:97], s[0:1], v162, s57, v[96:97]
	v_rsq_f32_e32 v102, v102
	v_lshl_add_u64 v[96:97], s[36:37], 1, v[96:97]
	v_mov_b32_e32 v215, v201
	v_lshl_add_u64 v[100:101], v[96:97], 0, v[214:215]
	v_cvt_pk_bf16_f32 v96, v144, v145
	v_cvt_pk_bf16_f32 v97, v146, v147
	v_cvt_pk_bf16_f32 v98, v156, v157
	v_cvt_pk_bf16_f32 v99, v158, v159
	global_store_dwordx4 v[100:101], v[96:99], off
	s_nop 1
	v_cvt_pk_bf16_f32 v96, v148, v149
	v_cvt_pk_bf16_f32 v97, v150, v151
	s_nop 0
	v_cvt_pk_bf16_f32 v99, v154, v155
	s_nop 0
	v_cvt_pk_bf16_f32 v98, v152, v153
	global_store_dwordx4 v[100:101], v[96:99], off offset:64
	s_mov_b64 s[0:1], -1
	s_nop 0
	v_mov_b32_e32 v96, v102
	v_pk_fma_f32 v[94:95], v[94:95], v[96:97], 0 op_sel_hi:[1,0,0]
	v_pk_fma_f32 v[92:93], v[92:93], v[96:97], 0 op_sel_hi:[1,0,0]
	v_pk_fma_f32 v[90:91], v[90:91], v[96:97], 0 op_sel_hi:[1,0,0]
	v_pk_fma_f32 v[88:89], v[88:89], v[96:97], 0 op_sel_hi:[1,0,0]
	v_pk_fma_f32 v[86:87], v[86:87], v[96:97], 0 op_sel_hi:[1,0,0]
	v_pk_fma_f32 v[84:85], v[84:85], v[96:97], 0 op_sel_hi:[1,0,0]
	v_pk_fma_f32 v[82:83], v[82:83], v[96:97], 0 op_sel_hi:[1,0,0]
	v_pk_fma_f32 v[80:81], v[80:81], v[96:97], 0 op_sel_hi:[1,0,0]
	s_and_b64 vcc, exec, s[12:13]
	s_cbranch_vccnz .LBB0_334
	v_mov_b64_e32 v[98:99], v[94:95]
	v_mov_b64_e32 v[106:107], v[90:91]
	v_mov_b64_e32 v[102:103], v[86:87]
	v_mov_b64_e32 v[110:111], v[82:83]
	s_and_b64 vcc, exec, s[10:11]
	v_mov_b64_e32 v[96:97], v[92:93]
	v_mov_b64_e32 v[104:105], v[88:89]
	v_mov_b64_e32 v[100:101], v[84:85]
	v_mov_b64_e32 v[108:109], v[80:81]
	s_cbranch_vccnz .LBB0_333
	v_pk_mul_f32 v[96:97], v[94:95], v[94:95]
	v_pk_mul_f32 v[98:99], v[92:93], v[92:93]
	s_nop 0
	v_pk_mov_b32 v[100:101], v[98:99], v[96:97] op_sel:[1,0]
	v_mov_b32_e32 v99, v97
	v_pk_add_f32 v[96:97], v[100:101], v[98:99]
	v_pk_mul_f32 v[98:99], v[90:91], v[90:91]
	v_pk_add_f32 v[96:97], v[96:97], v[96:97] op_sel_hi:[0,1]
	v_pk_mul_f32 v[100:101], v[88:89], v[88:89]
	v_mul_f32_e32 v96, v84, v84
	v_pk_mov_b32 v[102:103], v[100:101], v[98:99] op_sel:[1,0]
	v_mov_b32_e32 v101, v99
	v_pk_add_f32 v[98:99], v[102:103], v[100:101]
	v_pk_fma_f32 v[100:101], v[84:85], v[84:85], v[96:97] op_sel_hi:[1,1,0]
	v_mul_f32_e32 v96, v86, v86
	v_pk_add_f32 v[98:99], v[98:99], v[98:99] op_sel_hi:[0,1]
	v_pk_fma_f32 v[102:103], v[86:87], v[86:87], v[96:97] op_sel_hi:[1,1,0]
	v_mul_f32_e32 v100, v80, v80
	v_mul_f32_e32 v102, v81, v81
	v_mul_f32_e32 v96, v82, v82
	v_mul_f32_e32 v98, v83, v83
	v_pk_add_f32 v[100:101], v[100:101], v[102:103]
	v_pk_add_f32 v[96:97], v[96:97], v[98:99]
	v_and_b32_e32 v98, 64, v234
	v_pk_add_f32 v[96:97], v[100:101], v[96:97]
	v_add_u32_e32 v98, 64, v98
	v_add_f32_e32 v96, v96, v97
	v_xor_b32_e32 v97, 16, v234
	v_cmp_lt_i32_e32 vcc, v97, v98
	s_nop 1
	v_cndmask_b32_e32 v97, v234, v97, vcc
	v_lshlrev_b32_e32 v132, 2, v97
	ds_bpermute_b32 v97, v132, v96
	s_waitcnt lgkmcnt(0)
	v_add_f32_e32 v96, v96, v97
	v_xor_b32_e32 v97, 32, v234
	v_cmp_lt_i32_e32 vcc, v97, v98
	s_nop 1
	v_cndmask_b32_e32 v97, v234, v97, vcc
	v_lshlrev_b32_e32 v97, 2, v97
	ds_bpermute_b32 v97, v97, v96
	s_waitcnt lgkmcnt(0)
	v_add_f32_e32 v96, v96, v97
	v_fmamk_f32 v96, v96, 0x3c800000, v230
	v_rsq_f32_e32 v96, v96
	s_nop 0
	v_pk_mul_f32 v[98:99], v[92:93], v[96:97] op_sel_hi:[1,0]
	v_pk_mul_f32 v[106:107], v[86:87], v[96:97] op_sel_hi:[1,0]
	v_pk_mul_f32 v[100:101], v[94:95], v[96:97] op_sel_hi:[1,0]
	v_pk_mul_f32 v[98:99], v[36:37], v[98:99]
	v_pk_mul_f32 v[102:103], v[88:89], v[96:97] op_sel_hi:[1,0]
	v_pk_mul_f32 v[104:105], v[90:91], v[96:97] op_sel_hi:[1,0]
	v_pk_mul_f32 v[108:109], v[84:85], v[96:97] op_sel_hi:[1,0]
	v_pk_mul_f32 v[110:111], v[46:47], v[106:107]
	v_pk_mul_f32 v[106:107], v[82:83], v[96:97] op_sel_hi:[1,0]
	v_pk_mul_f32 v[96:97], v[80:81], v[96:97] op_sel_hi:[1,0]
	ds_bpermute_b32 v133, v132, v98
	v_pk_mul_f32 v[128:129], v[40:41], v[96:97]
	ds_bpermute_b32 v97, v132, v99
	v_pk_mul_f32 v[100:101], v[38:39], v[100:101]
	v_pk_mul_f32 v[102:103], v[32:33], v[102:103]
	s_waitcnt lgkmcnt(1)
	v_mul_f32_e32 v96, v116, v133
	v_cndmask_b32_e64 v96, v96, -v96, s[4:5]
	s_waitcnt lgkmcnt(0)
	v_mul_f32_e32 v97, v117, v97
	v_cndmask_b32_e64 v97, v97, -v97, s[4:5]
	v_fmac_f32_e32 v96, v112, v98
	v_fmac_f32_e32 v97, v113, v99
	v_cndmask_b32_e64 v96, v98, v96, s[6:7]
	ds_bpermute_b32 v98, v132, v100
	v_cndmask_b32_e64 v97, v99, v97, s[6:7]
	ds_bpermute_b32 v99, v132, v101
	v_pk_mul_f32 v[104:105], v[34:35], v[104:105]
	v_pk_mul_f32 v[108:109], v[44:45], v[108:109]
	s_waitcnt lgkmcnt(1)
	v_mul_f32_e32 v98, v118, v98
	v_cndmask_b32_e64 v98, v98, -v98, s[4:5]
	s_waitcnt lgkmcnt(0)
	v_mul_f32_e32 v99, v119, v99
	v_cndmask_b32_e64 v99, v99, -v99, s[4:5]
	v_fmac_f32_e32 v98, v114, v100
	v_fmac_f32_e32 v99, v115, v101
	v_cndmask_b32_e64 v98, v100, v98, s[6:7]
	ds_bpermute_b32 v100, v132, v102
	v_cndmask_b32_e64 v99, v101, v99, s[6:7]
	ds_bpermute_b32 v101, v132, v103
	v_pk_mul_f32 v[130:131], v[42:43], v[106:107]
	v_mov_b32_e32 v133, v216
	s_waitcnt lgkmcnt(1)
	v_mul_f32_e32 v100, v124, v100
	v_cndmask_b32_e64 v100, v100, -v100, s[4:5]
	s_waitcnt lgkmcnt(0)
	v_mul_f32_e32 v101, v125, v101
	v_cndmask_b32_e64 v101, v101, -v101, s[4:5]
	v_fmac_f32_e32 v100, v120, v102
	v_fmac_f32_e32 v101, v121, v103
	v_cndmask_b32_e64 v100, v102, v100, s[6:7]
	ds_bpermute_b32 v102, v132, v104
	v_cndmask_b32_e64 v101, v103, v101, s[6:7]
	ds_bpermute_b32 v103, v132, v105
	v_mov_b32_e32 v132, v216
	v_pk_mul_f32 v[98:99], v[132:133], v[98:99]
	s_waitcnt lgkmcnt(1)
	v_mul_f32_e32 v102, v126, v102
	v_cndmask_b32_e64 v102, v102, -v102, s[4:5]
	s_waitcnt lgkmcnt(0)
	v_mul_f32_e32 v103, v127, v103
	v_cndmask_b32_e64 v103, v103, -v103, s[4:5]
	v_fmac_f32_e32 v102, v122, v104
	v_fmac_f32_e32 v103, v123, v105
	v_cndmask_b32_e64 v102, v104, v102, s[6:7]
	v_cndmask_b32_e64 v103, v105, v103, s[6:7]
	v_pk_mul_f32 v[96:97], v[216:217], v[96:97]
	v_pk_mul_f32 v[106:107], v[132:133], v[102:103]
	v_pk_mul_f32 v[104:105], v[216:217], v[100:101]
	v_pk_mul_f32 v[102:103], v[132:133], v[110:111]
	v_pk_mul_f32 v[100:101], v[216:217], v[108:109]
	v_pk_mul_f32 v[110:111], v[132:133], v[130:131]
	v_pk_mul_f32 v[108:109], v[216:217], v[128:129]

.LBB0_356:
	s_waitcnt vmcnt(1)
	v_fmamk_f32 v112, v114, 0x3a800000, v230
	v_rsq_f32_e32 v112, v112
	s_mov_b64 s[0:1], -1
	v_pk_fma_f32 v[78:79], v[78:79], v[112:113], 0 op_sel_hi:[1,0,0]
	v_pk_fma_f32 v[76:77], v[76:77], v[112:113], 0 op_sel_hi:[1,0,0]
	v_pk_fma_f32 v[74:75], v[74:75], v[112:113], 0 op_sel_hi:[1,0,0]
	v_pk_fma_f32 v[72:73], v[72:73], v[112:113], 0 op_sel_hi:[1,0,0]
	v_pk_fma_f32 v[70:71], v[70:71], v[112:113], 0 op_sel_hi:[1,0,0]
	v_pk_fma_f32 v[68:69], v[68:69], v[112:113], 0 op_sel_hi:[1,0,0]
	v_pk_fma_f32 v[66:67], v[66:67], v[112:113], 0 op_sel_hi:[1,0,0]
	v_pk_fma_f32 v[64:65], v[64:65], v[112:113], 0 op_sel_hi:[1,0,0]
	s_and_b64 vcc, exec, s[12:13]
	s_cbranch_vccnz .LBB0_360
	v_mov_b64_e32 v[114:115], v[78:79]
	v_mov_b64_e32 v[126:127], v[74:75]
	v_mov_b64_e32 v[118:119], v[70:71]
	v_mov_b64_e32 v[122:123], v[66:67]
	s_and_b64 vcc, exec, s[10:11]
	v_mov_b64_e32 v[112:113], v[76:77]
	v_mov_b64_e32 v[124:125], v[72:73]
	v_mov_b64_e32 v[116:117], v[68:69]
	v_mov_b64_e32 v[120:121], v[64:65]
	s_cbranch_vccnz .LBB0_359
	v_pk_mul_f32 v[112:113], v[78:79], v[78:79]
	v_pk_mul_f32 v[114:115], v[76:77], v[76:77]
	s_nop 0
	v_pk_mov_b32 v[116:117], v[114:115], v[112:113] op_sel:[1,0]
	v_mov_b32_e32 v115, v113
	v_pk_add_f32 v[112:113], v[116:117], v[114:115]
	v_pk_mul_f32 v[114:115], v[74:75], v[74:75]
	v_pk_add_f32 v[112:113], v[112:113], v[112:113] op_sel_hi:[0,1]
	v_pk_mul_f32 v[116:117], v[72:73], v[72:73]
	v_mul_f32_e32 v112, v68, v68
	v_pk_mov_b32 v[118:119], v[116:117], v[114:115] op_sel:[1,0]
	v_mov_b32_e32 v117, v115
	v_pk_add_f32 v[114:115], v[118:119], v[116:117]
	v_pk_fma_f32 v[116:117], v[68:69], v[68:69], v[112:113] op_sel_hi:[1,1,0]
	v_mul_f32_e32 v112, v70, v70
	v_pk_add_f32 v[114:115], v[114:115], v[114:115] op_sel_hi:[0,1]
	v_pk_fma_f32 v[118:119], v[70:71], v[70:71], v[112:113] op_sel_hi:[1,1,0]
	v_mul_f32_e32 v116, v64, v64
	v_mul_f32_e32 v118, v65, v65
	v_mul_f32_e32 v112, v66, v66
	v_mul_f32_e32 v114, v67, v67
	v_pk_add_f32 v[116:117], v[116:117], v[118:119]
	v_pk_add_f32 v[112:113], v[112:113], v[114:115]
	v_and_b32_e32 v114, 64, v234
	v_pk_add_f32 v[112:113], v[116:117], v[112:113]
	v_add_u32_e32 v114, 64, v114
	v_add_f32_e32 v112, v112, v113
	v_xor_b32_e32 v113, 16, v234
	v_cmp_lt_i32_e32 vcc, v113, v114
	s_nop 1
	v_cndmask_b32_e32 v113, v234, v113, vcc
	v_lshlrev_b32_e32 v126, 2, v113
	ds_bpermute_b32 v113, v126, v112
	s_waitcnt lgkmcnt(0)
	v_add_f32_e32 v112, v112, v113
	v_xor_b32_e32 v113, 32, v234
	v_cmp_lt_i32_e32 vcc, v113, v114
	s_nop 1
	v_cndmask_b32_e32 v113, v234, v113, vcc
	v_lshlrev_b32_e32 v113, 2, v113
	ds_bpermute_b32 v113, v113, v112
	s_waitcnt lgkmcnt(0)
	v_add_f32_e32 v112, v112, v113
	v_fmamk_f32 v112, v112, 0x3c800000, v230
	v_rsq_f32_e32 v112, v112
	s_nop 0
	v_pk_mul_f32 v[114:115], v[76:77], v[112:113] op_sel_hi:[1,0]
	v_pk_mul_f32 v[124:125], v[68:69], v[112:113] op_sel_hi:[1,0]
	v_pk_mul_f32 v[116:117], v[78:79], v[112:113] op_sel_hi:[1,0]
	v_pk_mul_f32 v[114:115], v[36:37], v[114:115]
	v_pk_mul_f32 v[118:119], v[72:73], v[112:113] op_sel_hi:[1,0]
	v_pk_mul_f32 v[120:121], v[74:75], v[112:113] op_sel_hi:[1,0]
	v_pk_mul_f32 v[122:123], v[70:71], v[112:113] op_sel_hi:[1,0]
	v_pk_mul_f32 v[132:133], v[44:45], v[124:125]
	v_pk_mul_f32 v[124:125], v[66:67], v[112:113] op_sel_hi:[1,0]
	v_pk_mul_f32 v[112:113], v[64:65], v[112:113] op_sel_hi:[1,0]
	ds_bpermute_b32 v127, v126, v114
	v_pk_mul_f32 v[134:135], v[40:41], v[112:113]
	ds_bpermute_b32 v113, v126, v115
	v_pk_mul_f32 v[116:117], v[38:39], v[116:117]
	v_pk_mul_f32 v[118:119], v[32:33], v[118:119]
	s_waitcnt lgkmcnt(1)
	v_mul_f32_e32 v112, v100, v127
	v_cndmask_b32_e64 v112, v112, -v112, s[4:5]
	s_waitcnt lgkmcnt(0)
	v_mul_f32_e32 v113, v101, v113
	v_cndmask_b32_e64 v113, v113, -v113, s[4:5]
	v_fmac_f32_e32 v112, v96, v114
	v_fmac_f32_e32 v113, v97, v115
	v_cndmask_b32_e64 v112, v114, v112, s[6:7]
	ds_bpermute_b32 v114, v126, v116
	v_cndmask_b32_e64 v113, v115, v113, s[6:7]
	ds_bpermute_b32 v115, v126, v117
	v_pk_mul_f32 v[120:121], v[34:35], v[120:121]
	v_pk_mul_f32 v[122:123], v[46:47], v[122:123]
	s_waitcnt lgkmcnt(1)
	v_mul_f32_e32 v114, v102, v114
	v_cndmask_b32_e64 v114, v114, -v114, s[4:5]
	s_waitcnt lgkmcnt(0)
	v_mul_f32_e32 v115, v103, v115
	v_cndmask_b32_e64 v115, v115, -v115, s[4:5]
	v_fmac_f32_e32 v114, v98, v116
	v_fmac_f32_e32 v115, v99, v117
	v_cndmask_b32_e64 v114, v116, v114, s[6:7]
	ds_bpermute_b32 v116, v126, v118
	v_cndmask_b32_e64 v115, v117, v115, s[6:7]
	ds_bpermute_b32 v117, v126, v119
	v_pk_mul_f32 v[136:137], v[42:43], v[124:125]
	v_pk_mul_f32 v[112:113], v[216:217], v[112:113]
	s_waitcnt lgkmcnt(1)
	v_mul_f32_e32 v116, v108, v116
	v_cndmask_b32_e64 v116, v116, -v116, s[4:5]
	s_waitcnt lgkmcnt(0)
	v_mul_f32_e32 v117, v109, v117
	v_cndmask_b32_e64 v117, v117, -v117, s[4:5]
	v_fmac_f32_e32 v116, v104, v118
	v_fmac_f32_e32 v117, v105, v119
	v_cndmask_b32_e64 v116, v118, v116, s[6:7]
	ds_bpermute_b32 v118, v126, v120
	v_cndmask_b32_e64 v117, v119, v117, s[6:7]
	ds_bpermute_b32 v119, v126, v121
	v_pk_mul_f32 v[124:125], v[216:217], v[116:117]
	v_pk_mul_f32 v[116:117], v[216:217], v[132:133]
	s_waitcnt lgkmcnt(1)
	v_mul_f32_e32 v118, v110, v118
	v_cndmask_b32_e64 v118, v118, -v118, s[4:5]
	s_waitcnt lgkmcnt(0)
	v_mul_f32_e32 v119, v111, v119
	v_cndmask_b32_e64 v119, v119, -v119, s[4:5]
	v_fmac_f32_e32 v118, v106, v120
	v_fmac_f32_e32 v119, v107, v121
	v_cndmask_b32_e64 v118, v120, v118, s[6:7]
	v_cndmask_b32_e64 v119, v121, v119, s[6:7]
	v_mov_b32_e32 v120, v216
	v_mov_b32_e32 v121, v216
	v_pk_mul_f32 v[114:115], v[120:121], v[114:115]
	v_pk_mul_f32 v[126:127], v[120:121], v[118:119]
	v_pk_mul_f32 v[118:119], v[120:121], v[122:123]
	v_pk_mul_f32 v[122:123], v[120:121], v[136:137]
	v_pk_mul_f32 v[120:121], v[216:217], v[134:135]

.LBB0_362:
	s_waitcnt vmcnt(0)
	v_fmamk_f32 v70, v131, 0x3a800000, v230
	v_mov_b64_e32 v[64:65], s[18:19]
	v_mad_i64_i32 v[64:65], s[0:1], v130, s57, v[64:65]
	v_rsq_f32_e32 v70, v70
	v_lshl_add_u64 v[64:65], s[36:37], 1, v[64:65]
	v_mov_b32_e32 v215, v201
	v_lshl_add_u64 v[68:69], v[64:65], 0, v[214:215]
	v_cvt_pk_bf16_f32 v64, v112, v113
	v_cvt_pk_bf16_f32 v65, v114, v115
	v_cvt_pk_bf16_f32 v66, v124, v125
	v_cvt_pk_bf16_f32 v67, v126, v127
	global_store_dwordx4 v[68:69], v[64:67], off
	s_nop 1
	v_cvt_pk_bf16_f32 v64, v116, v117
	v_cvt_pk_bf16_f32 v65, v118, v119
	s_nop 0
	v_cvt_pk_bf16_f32 v67, v122, v123
	s_nop 0
	v_cvt_pk_bf16_f32 v66, v120, v121
	global_store_dwordx4 v[68:69], v[64:67], off offset:64
	s_mov_b64 s[0:1], -1
	s_nop 0
	v_mov_b32_e32 v64, v70
	v_pk_fma_f32 v[62:63], v[62:63], v[64:65], 0 op_sel_hi:[1,0,0]
	v_pk_fma_f32 v[60:61], v[60:61], v[64:65], 0 op_sel_hi:[1,0,0]
	v_pk_fma_f32 v[58:59], v[58:59], v[64:65], 0 op_sel_hi:[1,0,0]
	v_pk_fma_f32 v[56:57], v[56:57], v[64:65], 0 op_sel_hi:[1,0,0]
	v_pk_fma_f32 v[54:55], v[54:55], v[64:65], 0 op_sel_hi:[1,0,0]
	v_pk_fma_f32 v[52:53], v[52:53], v[64:65], 0 op_sel_hi:[1,0,0]
	v_pk_fma_f32 v[50:51], v[50:51], v[64:65], 0 op_sel_hi:[1,0,0]
	v_pk_fma_f32 v[48:49], v[48:49], v[64:65], 0 op_sel_hi:[1,0,0]
	s_and_b64 vcc, exec, s[12:13]
	s_cbranch_vccnz .LBB0_366
	v_mov_b64_e32 v[66:67], v[62:63]
	v_mov_b64_e32 v[74:75], v[58:59]
	v_mov_b64_e32 v[70:71], v[54:55]
	v_mov_b64_e32 v[78:79], v[50:51]
	s_and_b64 vcc, exec, s[10:11]
	v_mov_b64_e32 v[64:65], v[60:61]
	v_mov_b64_e32 v[72:73], v[56:57]
	v_mov_b64_e32 v[68:69], v[52:53]
	v_mov_b64_e32 v[76:77], v[48:49]
	s_cbranch_vccnz .LBB0_365
	v_pk_mul_f32 v[64:65], v[62:63], v[62:63]
	v_pk_mul_f32 v[66:67], v[60:61], v[60:61]
	s_nop 0
	v_pk_mov_b32 v[68:69], v[66:67], v[64:65] op_sel:[1,0]
	v_mov_b32_e32 v67, v65
	v_pk_add_f32 v[64:65], v[68:69], v[66:67]
	v_pk_mul_f32 v[66:67], v[58:59], v[58:59]
	v_pk_add_f32 v[64:65], v[64:65], v[64:65] op_sel_hi:[0,1]
	v_pk_mul_f32 v[68:69], v[56:57], v[56:57]
	v_mul_f32_e32 v64, v52, v52
	v_pk_mov_b32 v[70:71], v[68:69], v[66:67] op_sel:[1,0]
	v_mov_b32_e32 v69, v67
	v_pk_add_f32 v[66:67], v[70:71], v[68:69]
	v_pk_fma_f32 v[68:69], v[52:53], v[52:53], v[64:65] op_sel_hi:[1,1,0]
	v_mul_f32_e32 v64, v54, v54
	v_pk_add_f32 v[66:67], v[66:67], v[66:67] op_sel_hi:[0,1]
	v_pk_fma_f32 v[70:71], v[54:55], v[54:55], v[64:65] op_sel_hi:[1,1,0]
	v_mul_f32_e32 v68, v48, v48
	v_mul_f32_e32 v70, v49, v49
	v_mul_f32_e32 v64, v50, v50
	v_mul_f32_e32 v66, v51, v51
	v_pk_add_f32 v[68:69], v[68:69], v[70:71]
	v_pk_add_f32 v[64:65], v[64:65], v[66:67]
	v_and_b32_e32 v66, 64, v234
	v_pk_add_f32 v[64:65], v[68:69], v[64:65]
	v_add_u32_e32 v66, 64, v66
	v_add_f32_e32 v64, v64, v65
	v_xor_b32_e32 v65, 16, v234
	v_cmp_lt_i32_e32 vcc, v65, v66
	s_nop 1
	v_cndmask_b32_e32 v65, v234, v65, vcc
	v_lshlrev_b32_e32 v100, 2, v65
	ds_bpermute_b32 v65, v100, v64
	s_waitcnt lgkmcnt(0)
	v_add_f32_e32 v64, v64, v65
	v_xor_b32_e32 v65, 32, v234
	v_cmp_lt_i32_e32 vcc, v65, v66
	s_nop 1
	v_cndmask_b32_e32 v65, v234, v65, vcc
	v_lshlrev_b32_e32 v65, 2, v65
	ds_bpermute_b32 v65, v65, v64
	s_waitcnt lgkmcnt(0)
	v_add_f32_e32 v64, v64, v65
	v_fmamk_f32 v64, v64, 0x3c800000, v230
	v_rsq_f32_e32 v64, v64
	s_nop 0
	v_pk_mul_f32 v[66:67], v[60:61], v[64:65] op_sel_hi:[1,0]
	v_pk_mul_f32 v[74:75], v[54:55], v[64:65] op_sel_hi:[1,0]
	v_pk_mul_f32 v[68:69], v[62:63], v[64:65] op_sel_hi:[1,0]
	v_pk_mul_f32 v[66:67], v[36:37], v[66:67]
	v_pk_mul_f32 v[70:71], v[56:57], v[64:65] op_sel_hi:[1,0]
	v_pk_mul_f32 v[72:73], v[58:59], v[64:65] op_sel_hi:[1,0]
	v_pk_mul_f32 v[76:77], v[52:53], v[64:65] op_sel_hi:[1,0]
	v_pk_mul_f32 v[78:79], v[46:47], v[74:75]
	v_pk_mul_f32 v[74:75], v[50:51], v[64:65] op_sel_hi:[1,0]
	v_pk_mul_f32 v[64:65], v[48:49], v[64:65] op_sel_hi:[1,0]
	ds_bpermute_b32 v101, v100, v66
	v_pk_mul_f32 v[96:97], v[40:41], v[64:65]
	ds_bpermute_b32 v65, v100, v67
	v_pk_mul_f32 v[68:69], v[38:39], v[68:69]
	v_pk_mul_f32 v[70:71], v[32:33], v[70:71]
	s_waitcnt lgkmcnt(1)
	v_mul_f32_e32 v64, v84, v101
	v_cndmask_b32_e64 v64, v64, -v64, s[4:5]
	s_waitcnt lgkmcnt(0)
	v_mul_f32_e32 v65, v85, v65
	v_cndmask_b32_e64 v65, v65, -v65, s[4:5]
	v_fmac_f32_e32 v64, v80, v66
	v_fmac_f32_e32 v65, v81, v67
	v_cndmask_b32_e64 v64, v66, v64, s[6:7]
	ds_bpermute_b32 v66, v100, v68
	v_cndmask_b32_e64 v65, v67, v65, s[6:7]
	ds_bpermute_b32 v67, v100, v69
	v_pk_mul_f32 v[72:73], v[34:35], v[72:73]
	v_pk_mul_f32 v[76:77], v[44:45], v[76:77]
	s_waitcnt lgkmcnt(1)
	v_mul_f32_e32 v66, v86, v66
	v_cndmask_b32_e64 v66, v66, -v66, s[4:5]
	s_waitcnt lgkmcnt(0)
	v_mul_f32_e32 v67, v87, v67
	v_cndmask_b32_e64 v67, v67, -v67, s[4:5]
	v_fmac_f32_e32 v66, v82, v68
	v_fmac_f32_e32 v67, v83, v69
	v_cndmask_b32_e64 v66, v68, v66, s[6:7]
	ds_bpermute_b32 v68, v100, v70
	v_cndmask_b32_e64 v67, v69, v67, s[6:7]
	ds_bpermute_b32 v69, v100, v71
	v_pk_mul_f32 v[98:99], v[42:43], v[74:75]
	v_mov_b32_e32 v101, v216
	s_waitcnt lgkmcnt(1)
	v_mul_f32_e32 v68, v92, v68
	v_cndmask_b32_e64 v68, v68, -v68, s[4:5]
	s_waitcnt lgkmcnt(0)
	v_mul_f32_e32 v69, v93, v69
	v_cndmask_b32_e64 v69, v69, -v69, s[4:5]
	v_fmac_f32_e32 v68, v88, v70
	v_fmac_f32_e32 v69, v89, v71
	v_cndmask_b32_e64 v68, v70, v68, s[6:7]
	ds_bpermute_b32 v70, v100, v72
	v_cndmask_b32_e64 v69, v71, v69, s[6:7]
	ds_bpermute_b32 v71, v100, v73
	v_mov_b32_e32 v100, v216
	v_pk_mul_f32 v[66:67], v[100:101], v[66:67]
	s_waitcnt lgkmcnt(1)
	v_mul_f32_e32 v70, v94, v70
	v_cndmask_b32_e64 v70, v70, -v70, s[4:5]
	s_waitcnt lgkmcnt(0)
	v_mul_f32_e32 v71, v95, v71
	v_cndmask_b32_e64 v71, v71, -v71, s[4:5]
	v_fmac_f32_e32 v70, v90, v72
	v_fmac_f32_e32 v71, v91, v73
	v_cndmask_b32_e64 v70, v72, v70, s[6:7]
	v_cndmask_b32_e64 v71, v73, v71, s[6:7]
	v_pk_mul_f32 v[64:65], v[216:217], v[64:65]
	v_pk_mul_f32 v[74:75], v[100:101], v[70:71]
	v_pk_mul_f32 v[72:73], v[216:217], v[68:69]
	v_pk_mul_f32 v[70:71], v[100:101], v[78:79]
	v_pk_mul_f32 v[68:69], v[216:217], v[76:77]
	v_pk_mul_f32 v[78:79], v[100:101], v[98:99]
	v_pk_mul_f32 v[76:77], v[216:217], v[96:97]

.LBB0_388:
	s_waitcnt vmcnt(1)
	v_fmamk_f32 v80, v82, 0x3a800000, v230
	v_rsq_f32_e32 v80, v80
	s_mov_b64 s[0:1], -1
	v_pk_fma_f32 v[30:31], v[30:31], v[80:81], 0 op_sel_hi:[1,0,0]
	v_pk_fma_f32 v[28:29], v[28:29], v[80:81], 0 op_sel_hi:[1,0,0]
	v_pk_fma_f32 v[26:27], v[26:27], v[80:81], 0 op_sel_hi:[1,0,0]
	v_pk_fma_f32 v[24:25], v[24:25], v[80:81], 0 op_sel_hi:[1,0,0]
	v_pk_fma_f32 v[22:23], v[22:23], v[80:81], 0 op_sel_hi:[1,0,0]
	v_pk_fma_f32 v[20:21], v[20:21], v[80:81], 0 op_sel_hi:[1,0,0]
	v_pk_fma_f32 v[18:19], v[18:19], v[80:81], 0 op_sel_hi:[1,0,0]
	v_pk_fma_f32 v[16:17], v[16:17], v[80:81], 0 op_sel_hi:[1,0,0]
	s_and_b64 vcc, exec, s[12:13]
	s_cbranch_vccnz .LBB0_392
	v_mov_b64_e32 v[82:83], v[30:31]
	v_mov_b64_e32 v[94:95], v[26:27]
	v_mov_b64_e32 v[86:87], v[22:23]
	v_mov_b64_e32 v[90:91], v[18:19]
	s_and_b64 vcc, exec, s[10:11]
	v_mov_b64_e32 v[80:81], v[28:29]
	v_mov_b64_e32 v[92:93], v[24:25]
	v_mov_b64_e32 v[84:85], v[20:21]
	v_mov_b64_e32 v[88:89], v[16:17]
	s_cbranch_vccnz .LBB0_391
	v_pk_mul_f32 v[80:81], v[30:31], v[30:31]
	v_pk_mul_f32 v[82:83], v[28:29], v[28:29]
	s_nop 0
	v_pk_mov_b32 v[84:85], v[82:83], v[80:81] op_sel:[1,0]
	v_mov_b32_e32 v83, v81
	v_pk_add_f32 v[80:81], v[84:85], v[82:83]
	v_pk_mul_f32 v[82:83], v[26:27], v[26:27]
	v_pk_add_f32 v[80:81], v[80:81], v[80:81] op_sel_hi:[0,1]
	v_pk_mul_f32 v[84:85], v[24:25], v[24:25]
	v_mul_f32_e32 v80, v20, v20
	v_pk_mov_b32 v[86:87], v[84:85], v[82:83] op_sel:[1,0]
	v_mov_b32_e32 v85, v83
	v_pk_add_f32 v[82:83], v[86:87], v[84:85]
	v_pk_fma_f32 v[84:85], v[20:21], v[20:21], v[80:81] op_sel_hi:[1,1,0]
	v_mul_f32_e32 v80, v22, v22
	v_pk_add_f32 v[82:83], v[82:83], v[82:83] op_sel_hi:[0,1]
	v_pk_fma_f32 v[86:87], v[22:23], v[22:23], v[80:81] op_sel_hi:[1,1,0]
	v_mul_f32_e32 v84, v16, v16
	v_mul_f32_e32 v86, v17, v17
	v_mul_f32_e32 v80, v18, v18
	v_mul_f32_e32 v82, v19, v19
	v_pk_add_f32 v[84:85], v[84:85], v[86:87]
	v_pk_add_f32 v[80:81], v[80:81], v[82:83]
	v_and_b32_e32 v82, 64, v234
	v_pk_add_f32 v[80:81], v[84:85], v[80:81]
	v_add_u32_e32 v82, 64, v82
	v_add_f32_e32 v80, v80, v81
	v_xor_b32_e32 v81, 16, v234
	v_cmp_lt_i32_e32 vcc, v81, v82
	s_nop 1
	v_cndmask_b32_e32 v81, v234, v81, vcc
	v_lshlrev_b32_e32 v94, 2, v81
	ds_bpermute_b32 v81, v94, v80
	s_waitcnt lgkmcnt(0)
	v_add_f32_e32 v80, v80, v81
	v_xor_b32_e32 v81, 32, v234
	v_cmp_lt_i32_e32 vcc, v81, v82
	s_nop 1
	v_cndmask_b32_e32 v81, v234, v81, vcc
	v_lshlrev_b32_e32 v81, 2, v81
	ds_bpermute_b32 v81, v81, v80
	s_waitcnt lgkmcnt(0)
	v_add_f32_e32 v80, v80, v81
	v_fmamk_f32 v80, v80, 0x3c800000, v230
	v_rsq_f32_e32 v80, v80
	s_nop 0
	v_pk_mul_f32 v[82:83], v[28:29], v[80:81] op_sel_hi:[1,0]
	v_pk_mul_f32 v[92:93], v[20:21], v[80:81] op_sel_hi:[1,0]
	v_pk_mul_f32 v[84:85], v[30:31], v[80:81] op_sel_hi:[1,0]
	v_pk_mul_f32 v[82:83], v[36:37], v[82:83]
	v_pk_mul_f32 v[86:87], v[24:25], v[80:81] op_sel_hi:[1,0]
	v_pk_mul_f32 v[88:89], v[26:27], v[80:81] op_sel_hi:[1,0]
	v_pk_mul_f32 v[90:91], v[22:23], v[80:81] op_sel_hi:[1,0]
	v_pk_mul_f32 v[100:101], v[44:45], v[92:93]
	v_pk_mul_f32 v[92:93], v[18:19], v[80:81] op_sel_hi:[1,0]
	v_pk_mul_f32 v[80:81], v[16:17], v[80:81] op_sel_hi:[1,0]
	ds_bpermute_b32 v95, v94, v82
	v_pk_mul_f32 v[102:103], v[40:41], v[80:81]
	ds_bpermute_b32 v81, v94, v83
	v_pk_mul_f32 v[84:85], v[38:39], v[84:85]
	v_pk_mul_f32 v[86:87], v[32:33], v[86:87]
	s_waitcnt lgkmcnt(1)
	v_mul_f32_e32 v80, v68, v95
	v_cndmask_b32_e64 v80, v80, -v80, s[4:5]
	s_waitcnt lgkmcnt(0)
	v_mul_f32_e32 v81, v69, v81
	v_cndmask_b32_e64 v81, v81, -v81, s[4:5]
	v_fmac_f32_e32 v80, v64, v82
	v_fmac_f32_e32 v81, v65, v83
	v_cndmask_b32_e64 v80, v82, v80, s[6:7]
	ds_bpermute_b32 v82, v94, v84
	v_cndmask_b32_e64 v81, v83, v81, s[6:7]
	ds_bpermute_b32 v83, v94, v85
	v_pk_mul_f32 v[88:89], v[34:35], v[88:89]
	v_pk_mul_f32 v[90:91], v[46:47], v[90:91]
	s_waitcnt lgkmcnt(1)
	v_mul_f32_e32 v82, v70, v82
	v_cndmask_b32_e64 v82, v82, -v82, s[4:5]
	s_waitcnt lgkmcnt(0)
	v_mul_f32_e32 v83, v71, v83
	v_cndmask_b32_e64 v83, v83, -v83, s[4:5]
	v_fmac_f32_e32 v82, v66, v84
	v_fmac_f32_e32 v83, v67, v85
	v_cndmask_b32_e64 v82, v84, v82, s[6:7]
	ds_bpermute_b32 v84, v94, v86
	v_cndmask_b32_e64 v83, v85, v83, s[6:7]
	ds_bpermute_b32 v85, v94, v87
	v_pk_mul_f32 v[104:105], v[42:43], v[92:93]
	v_pk_mul_f32 v[80:81], v[216:217], v[80:81]
	s_waitcnt lgkmcnt(1)
	v_mul_f32_e32 v84, v76, v84
	v_cndmask_b32_e64 v84, v84, -v84, s[4:5]
	s_waitcnt lgkmcnt(0)
	v_mul_f32_e32 v85, v77, v85
	v_cndmask_b32_e64 v85, v85, -v85, s[4:5]
	v_fmac_f32_e32 v84, v72, v86
	v_fmac_f32_e32 v85, v73, v87
	v_cndmask_b32_e64 v84, v86, v84, s[6:7]
	ds_bpermute_b32 v86, v94, v88
	v_cndmask_b32_e64 v85, v87, v85, s[6:7]
	ds_bpermute_b32 v87, v94, v89
	v_pk_mul_f32 v[92:93], v[216:217], v[84:85]
	v_pk_mul_f32 v[84:85], v[216:217], v[100:101]
	s_waitcnt lgkmcnt(1)
	v_mul_f32_e32 v86, v78, v86
	v_cndmask_b32_e64 v86, v86, -v86, s[4:5]
	s_waitcnt lgkmcnt(0)
	v_mul_f32_e32 v87, v79, v87
	v_cndmask_b32_e64 v87, v87, -v87, s[4:5]
	v_fmac_f32_e32 v86, v74, v88
	v_fmac_f32_e32 v87, v75, v89
	v_cndmask_b32_e64 v86, v88, v86, s[6:7]
	v_cndmask_b32_e64 v87, v89, v87, s[6:7]
	v_mov_b32_e32 v88, v216
	v_mov_b32_e32 v89, v216
	v_pk_mul_f32 v[82:83], v[88:89], v[82:83]
	v_pk_mul_f32 v[94:95], v[88:89], v[86:87]
	v_pk_mul_f32 v[86:87], v[88:89], v[90:91]
	v_pk_mul_f32 v[90:91], v[88:89], v[104:105]
	v_pk_mul_f32 v[88:89], v[216:217], v[102:103]

.LBB0_394:
	s_waitcnt vmcnt(0)
	v_fmamk_f32 v22, v99, 0x3a800000, v230
	v_mov_b64_e32 v[16:17], s[18:19]
	v_mad_i64_i32 v[16:17], s[0:1], v98, s57, v[16:17]
	v_rsq_f32_e32 v22, v22
	v_lshl_add_u64 v[16:17], s[36:37], 1, v[16:17]
	v_mov_b32_e32 v215, v201
	v_lshl_add_u64 v[20:21], v[16:17], 0, v[214:215]
	v_cvt_pk_bf16_f32 v16, v80, v81
	v_cvt_pk_bf16_f32 v17, v82, v83
	v_cvt_pk_bf16_f32 v18, v92, v93
	v_cvt_pk_bf16_f32 v19, v94, v95
	global_store_dwordx4 v[20:21], v[16:19], off
	s_nop 1
	v_cvt_pk_bf16_f32 v16, v84, v85
	v_cvt_pk_bf16_f32 v17, v86, v87
	s_nop 0
	v_cvt_pk_bf16_f32 v19, v90, v91
	s_nop 0
	v_cvt_pk_bf16_f32 v18, v88, v89
	global_store_dwordx4 v[20:21], v[16:19], off offset:64
	s_mov_b64 s[0:1], -1
	s_nop 0
	v_mov_b32_e32 v16, v22
	v_pk_fma_f32 v[14:15], v[14:15], v[16:17], 0 op_sel_hi:[1,0,0]
	v_pk_fma_f32 v[12:13], v[12:13], v[16:17], 0 op_sel_hi:[1,0,0]
	v_pk_fma_f32 v[10:11], v[10:11], v[16:17], 0 op_sel_hi:[1,0,0]
	v_pk_fma_f32 v[8:9], v[8:9], v[16:17], 0 op_sel_hi:[1,0,0]
	v_pk_fma_f32 v[6:7], v[6:7], v[16:17], 0 op_sel_hi:[1,0,0]
	v_pk_fma_f32 v[4:5], v[4:5], v[16:17], 0 op_sel_hi:[1,0,0]
	v_pk_fma_f32 v[2:3], v[2:3], v[16:17], 0 op_sel_hi:[1,0,0]
	v_pk_fma_f32 v[0:1], v[0:1], v[16:17], 0 op_sel_hi:[1,0,0]
	s_and_b64 vcc, exec, s[12:13]
	s_cbranch_vccnz .LBB0_398
	v_mov_b64_e32 v[18:19], v[14:15]
	v_mov_b64_e32 v[26:27], v[10:11]
	v_mov_b64_e32 v[22:23], v[6:7]
	v_mov_b64_e32 v[30:31], v[2:3]
	s_and_b64 vcc, exec, s[10:11]
	v_mov_b64_e32 v[16:17], v[12:13]
	v_mov_b64_e32 v[24:25], v[8:9]
	v_mov_b64_e32 v[20:21], v[4:5]
	v_mov_b64_e32 v[28:29], v[0:1]
	s_cbranch_vccnz .LBB0_397
	v_pk_mul_f32 v[16:17], v[14:15], v[14:15]
	v_pk_mul_f32 v[18:19], v[12:13], v[12:13]
	s_nop 0
	v_pk_mov_b32 v[20:21], v[18:19], v[16:17] op_sel:[1,0]
	v_mov_b32_e32 v19, v17
	v_pk_add_f32 v[16:17], v[20:21], v[18:19]
	v_pk_mul_f32 v[18:19], v[10:11], v[10:11]
	v_pk_add_f32 v[16:17], v[16:17], v[16:17] op_sel_hi:[0,1]
	v_pk_mul_f32 v[20:21], v[8:9], v[8:9]
	v_mul_f32_e32 v16, v4, v4
	v_pk_mov_b32 v[22:23], v[20:21], v[18:19] op_sel:[1,0]
	v_mov_b32_e32 v21, v19
	v_pk_add_f32 v[18:19], v[22:23], v[20:21]
	v_pk_fma_f32 v[20:21], v[4:5], v[4:5], v[16:17] op_sel_hi:[1,1,0]
	v_mul_f32_e32 v16, v6, v6
	v_pk_add_f32 v[18:19], v[18:19], v[18:19] op_sel_hi:[0,1]
	v_pk_fma_f32 v[22:23], v[6:7], v[6:7], v[16:17] op_sel_hi:[1,1,0]
	v_mul_f32_e32 v20, v0, v0
	v_mul_f32_e32 v22, v1, v1
	v_mul_f32_e32 v16, v2, v2
	v_mul_f32_e32 v18, v3, v3
	v_pk_add_f32 v[20:21], v[20:21], v[22:23]
	v_pk_add_f32 v[16:17], v[16:17], v[18:19]
	v_and_b32_e32 v18, 64, v234
	v_pk_add_f32 v[16:17], v[20:21], v[16:17]
	v_add_u32_e32 v18, 64, v18
	v_add_f32_e32 v16, v16, v17
	v_xor_b32_e32 v17, 16, v234
	v_cmp_lt_i32_e32 vcc, v17, v18
	s_nop 1
	v_cndmask_b32_e32 v17, v234, v17, vcc
	v_lshlrev_b32_e32 v64, 2, v17
	ds_bpermute_b32 v17, v64, v16
	s_waitcnt lgkmcnt(0)
	v_add_f32_e32 v16, v16, v17
	v_xor_b32_e32 v17, 32, v234
	v_cmp_lt_i32_e32 vcc, v17, v18
	s_nop 1
	v_cndmask_b32_e32 v17, v234, v17, vcc
	v_lshlrev_b32_e32 v17, 2, v17
	ds_bpermute_b32 v17, v17, v16
	s_waitcnt lgkmcnt(0)
	v_add_f32_e32 v16, v16, v17
	v_fmamk_f32 v16, v16, 0x3c800000, v230
	v_rsq_f32_e32 v16, v16
	s_nop 0
	v_pk_mul_f32 v[18:19], v[12:13], v[16:17] op_sel_hi:[1,0]
	v_pk_mul_f32 v[26:27], v[6:7], v[16:17] op_sel_hi:[1,0]
	v_pk_mul_f32 v[20:21], v[14:15], v[16:17] op_sel_hi:[1,0]
	v_pk_mul_f32 v[18:19], v[36:37], v[18:19]
	v_pk_mul_f32 v[22:23], v[8:9], v[16:17] op_sel_hi:[1,0]
	v_pk_mul_f32 v[24:25], v[10:11], v[16:17] op_sel_hi:[1,0]
	v_pk_mul_f32 v[28:29], v[4:5], v[16:17] op_sel_hi:[1,0]
	v_pk_mul_f32 v[30:31], v[46:47], v[26:27]
	v_pk_mul_f32 v[26:27], v[2:3], v[16:17] op_sel_hi:[1,0]
	v_pk_mul_f32 v[16:17], v[0:1], v[16:17] op_sel_hi:[1,0]
	v_pk_mul_f32 v[22:23], v[32:33], v[22:23]
	ds_bpermute_b32 v36, v64, v18
	v_pk_mul_f32 v[32:33], v[40:41], v[16:17]
	ds_bpermute_b32 v17, v64, v19
	v_pk_mul_f32 v[20:21], v[38:39], v[20:21]
	v_pk_mul_f32 v[24:25], v[34:35], v[24:25]
	s_waitcnt lgkmcnt(1)
	v_mul_f32_e32 v16, v52, v36
	v_cndmask_b32_e64 v16, v16, -v16, s[4:5]
	s_waitcnt lgkmcnt(0)
	v_mul_f32_e32 v17, v53, v17
	v_cndmask_b32_e64 v17, v17, -v17, s[4:5]
	v_fmac_f32_e32 v16, v48, v18
	v_fmac_f32_e32 v17, v49, v19
	v_cndmask_b32_e64 v16, v18, v16, s[6:7]
	ds_bpermute_b32 v18, v64, v20
	v_cndmask_b32_e64 v17, v19, v17, s[6:7]
	ds_bpermute_b32 v19, v64, v21
	v_pk_mul_f32 v[28:29], v[44:45], v[28:29]
	v_pk_mul_f32 v[34:35], v[42:43], v[26:27]
	s_waitcnt lgkmcnt(1)
	v_mul_f32_e32 v18, v54, v18
	v_cndmask_b32_e64 v18, v18, -v18, s[4:5]
	s_waitcnt lgkmcnt(0)
	v_mul_f32_e32 v19, v55, v19
	v_cndmask_b32_e64 v19, v19, -v19, s[4:5]
	v_fmac_f32_e32 v18, v50, v20
	v_fmac_f32_e32 v19, v51, v21
	v_cndmask_b32_e64 v18, v20, v18, s[6:7]
	ds_bpermute_b32 v20, v64, v22
	v_cndmask_b32_e64 v19, v21, v19, s[6:7]
	ds_bpermute_b32 v21, v64, v23
	v_mov_b32_e32 v36, v216
	v_mov_b32_e32 v37, v216
	s_waitcnt lgkmcnt(1)
	v_mul_f32_e32 v20, v60, v20
	v_cndmask_b32_e64 v20, v20, -v20, s[4:5]
	s_waitcnt lgkmcnt(0)
	v_mul_f32_e32 v21, v61, v21
	v_cndmask_b32_e64 v21, v21, -v21, s[4:5]
	v_fmac_f32_e32 v20, v56, v22
	v_fmac_f32_e32 v21, v57, v23
	v_cndmask_b32_e64 v20, v22, v20, s[6:7]
	ds_bpermute_b32 v22, v64, v24
	v_cndmask_b32_e64 v21, v23, v21, s[6:7]
	ds_bpermute_b32 v23, v64, v25
	v_pk_mul_f32 v[18:19], v[36:37], v[18:19]
	v_pk_mul_f32 v[16:17], v[216:217], v[16:17]
	s_waitcnt lgkmcnt(1)
	v_mul_f32_e32 v22, v62, v22
	v_cndmask_b32_e64 v22, v22, -v22, s[4:5]
	s_waitcnt lgkmcnt(0)
	v_mul_f32_e32 v23, v63, v23
	v_cndmask_b32_e64 v23, v23, -v23, s[4:5]
	v_fmac_f32_e32 v22, v58, v24
	v_fmac_f32_e32 v23, v59, v25
	v_cndmask_b32_e64 v22, v24, v22, s[6:7]
	v_cndmask_b32_e64 v23, v25, v23, s[6:7]
	v_pk_mul_f32 v[26:27], v[36:37], v[22:23]
	v_pk_mul_f32 v[24:25], v[216:217], v[20:21]
	v_pk_mul_f32 v[22:23], v[36:37], v[30:31]
	v_pk_mul_f32 v[20:21], v[216:217], v[28:29]
	v_pk_mul_f32 v[30:31], v[36:37], v[34:35]
	v_pk_mul_f32 v[28:29], v[216:217], v[32:33]

.LBB0_509:
	v_cndmask_b32_e64 v16, v16, v225, s[38:39]
	v_cndmask_b32_e64 v17, v225, v17, s[4:5]
	v_exp_f32_e32 v240, v16
	v_cndmask_b32_e64 v18, v18, v225, s[40:41]
	v_exp_f32_e32 v239, v17
	v_cndmask_b32_e64 v19, v19, v225, s[42:43]
	v_exp_f32_e32 v238, v18
	v_cndmask_b32_e64 v20, v20, v225, s[44:45]
	v_exp_f32_e32 v237, v19
	v_cndmask_b32_e64 v21, v21, v225, s[46:47]
	v_exp_f32_e32 v236, v20
	v_add_f32_e32 v16, v240, v178
	v_cndmask_b32_e64 v22, v22, v225, s[48:49]
	v_exp_f32_e32 v235, v21
	v_add_f32_e32 v16, v239, v16
	v_cndmask_b32_e64 v23, v23, v225, s[50:51]
	v_exp_f32_e32 v234, v22
	v_add_f32_e32 v16, v238, v16
	v_cndmask_b32_e64 v24, v24, v225, s[52:53]
	v_exp_f32_e32 v233, v23
	v_add_f32_e32 v16, v237, v16
	v_cndmask_b32_e64 v25, v25, v225, s[54:55]
	v_exp_f32_e32 v232, v24
	v_add_f32_e32 v16, v236, v16
	v_cndmask_b32_e64 v26, v26, v225, s[56:57]
	v_exp_f32_e32 v231, v25
	v_add_f32_e32 v16, v235, v16
	v_cndmask_b32_e64 v27, v27, v225, s[58:59]
	v_exp_f32_e32 v230, v26
	v_add_f32_e32 v16, v234, v16
	v_cndmask_b32_e64 v28, v28, v225, s[60:61]
	v_exp_f32_e32 v229, v27
	v_add_f32_e32 v16, v233, v16
	v_cndmask_b32_e64 v29, v29, v225, s[62:63]
	v_exp_f32_e32 v185, v28
	v_add_f32_e32 v16, v232, v16
	v_cndmask_b32_e64 v30, v30, v225, s[64:65]
	v_exp_f32_e32 v183, v29
	v_add_f32_e32 v16, v231, v16
	v_cndmask_b32_e64 v31, v31, v225, s[66:67]
	v_exp_f32_e32 v181, v30
	v_add_f32_e32 v16, v230, v16
	v_exp_f32_e32 v179, v31
	v_add_f32_e32 v16, v229, v16
	v_add_f32_e32 v16, v185, v16
	v_add_f32_e32 v16, v183, v16
	v_add_f32_e32 v16, v181, v16
	v_and_b32_e32 v17, 64, v228
	v_add_f32_e32 v60, v179, v16
	v_xor_b32_e32 v16, 32, v228
	v_add_u32_e32 v17, 64, v17
	v_cmp_lt_i32_e32 vcc, v16, v17
	v_cvt_pk_bf16_f32 v17, v164, v165
	v_cvt_pk_bf16_f32 v18, v167, v170
	v_cndmask_b32_e32 v16, v228, v16, vcc
	v_lshlrev_b32_e32 v178, 2, v16
	v_cvt_pk_bf16_f32 v16, v106, v107
	v_cvt_pk_bf16_f32 v19, v172, v174
	ds_read_b64_tr_b16 v[24:25], v188
	ds_read_b64_tr_b16 v[26:27], v188 offset:512
	ds_read_b64_tr_b16 v[20:21], v195
	ds_read_b64_tr_b16 v[22:23], v195 offset:512
	s_waitcnt lgkmcnt(0)
	v_cvt_pk_bf16_f32 v164, v166, v168
	v_cvt_pk_bf16_f32 v165, v169, v171
	v_mfma_f32_32x32x16_bf16 v[32:47], v[24:27], v[16:19], 0
	v_cvt_pk_bf16_f32 v166, v173, v175
	v_cvt_pk_bf16_f32 v167, v176, v177
	ds_read_b64_tr_b16 v[172:173], v196
	ds_read_b64_tr_b16 v[174:175], v196 offset:512
	ds_read_b64_tr_b16 v[168:169], v197
	ds_read_b64_tr_b16 v[170:171], v197 offset:512
	s_waitcnt lgkmcnt(0)
	v_cvt_pk_bf16_f32 v80, v105, v80
	v_cvt_pk_bf16_f32 v81, v81, v82
	v_cvt_pk_bf16_f32 v82, v83, v84
	v_cvt_pk_bf16_f32 v83, v85, v86
	v_mfma_f32_32x32x16_bf16 v[16:31], v[20:23], v[16:19], 0
	v_cvt_pk_bf16_f32 v66, v65, v66
	v_cvt_pk_bf16_f32 v67, v67, v68
	v_cvt_pk_bf16_f32 v68, v69, v70
	v_cvt_pk_bf16_f32 v69, v71, v72
	v_cvt_pk_bf16_f32 v48, v48, v49
	v_cvt_pk_bf16_f32 v49, v50, v51
	v_cvt_pk_bf16_f32 v50, v52, v53
	v_mfma_f32_32x32x16_bf16 v[32:47], v[172:175], v[164:167], v[32:47]
	v_cvt_pk_bf16_f32 v51, v54, v55
	s_ashr_i32 s95, s94, 31
	v_mfma_f32_32x32x16_bf16 v[16:31], v[168:171], v[164:167], v[16:31]
	ds_read_b64_tr_b16 v[168:169], v198
	ds_read_b64_tr_b16 v[170:171], v198 offset:512
	ds_read_b64_tr_b16 v[164:165], v199
	ds_read_b64_tr_b16 v[166:167], v199 offset:512
	s_waitcnt lgkmcnt(0)
	s_nop 0
	v_mfma_f32_32x32x16_bf16 v[32:47], v[168:171], v[80:83], v[32:47]
	v_mfma_f32_32x32x16_bf16 v[16:31], v[164:167], v[80:83], v[16:31]
	ds_read_b64_tr_b16 v[164:165], v200
	ds_read_b64_tr_b16 v[166:167], v200 offset:512
	ds_read_b64_tr_b16 v[80:81], v201
	ds_read_b64_tr_b16 v[82:83], v201 offset:512
	s_waitcnt lgkmcnt(0)
	s_nop 0
	v_mfma_f32_32x32x16_bf16 v[32:47], v[164:167], v[66:69], v[32:47]
	v_mfma_f32_32x32x16_bf16 v[16:31], v[80:83], v[66:69], v[16:31]
	v_cvt_pk_bf16_f32 v66, v73, v74
	v_cvt_pk_bf16_f32 v67, v75, v76
	v_cvt_pk_bf16_f32 v68, v77, v78
	v_cvt_pk_bf16_f32 v69, v79, v87
	ds_read_b64_tr_b16 v[74:75], v202
	ds_read_b64_tr_b16 v[76:77], v202 offset:512
	ds_read_b64_tr_b16 v[70:71], v203
	ds_read_b64_tr_b16 v[72:73], v203 offset:512
	s_waitcnt lgkmcnt(0)
	s_nop 1
	v_mfma_f32_32x32x16_bf16 v[32:47], v[74:77], v[66:69], v[32:47]
	v_mfma_f32_32x32x16_bf16 v[16:31], v[70:73], v[66:69], v[16:31]
	ds_read_b64_tr_b16 v[66:67], v204
	ds_read_b64_tr_b16 v[68:69], v204 offset:512
	ds_read_b64_tr_b16 v[52:53], v205
	ds_read_b64_tr_b16 v[54:55], v205 offset:512
	s_waitcnt lgkmcnt(0)
	s_nop 0
	v_mfma_f32_32x32x16_bf16 v[32:47], v[66:69], v[48:51], v[32:47]
	v_mfma_f32_32x32x16_bf16 v[16:31], v[52:55], v[48:51], v[16:31]
	v_cvt_pk_bf16_f32 v48, v64, v56
	v_cvt_pk_bf16_f32 v49, v57, v58
	v_cvt_pk_bf16_f32 v50, v61, v63
	v_cvt_pk_bf16_f32 v51, v89, v91
	ds_read_b64_tr_b16 v[64:65], v206
	ds_read_b64_tr_b16 v[66:67], v206 offset:512
	ds_read_b64_tr_b16 v[52:53], v207
	ds_read_b64_tr_b16 v[54:55], v207 offset:512
	s_waitcnt lgkmcnt(0)
	s_nop 1
	v_mfma_f32_32x32x16_bf16 v[32:47], v[64:67], v[48:51], v[32:47]
	v_mfma_f32_32x32x16_bf16 v[16:31], v[52:55], v[48:51], v[16:31]
	v_cvt_pk_bf16_f32 v48, v59, v62
	v_cvt_pk_bf16_f32 v49, v88, v90
	v_cvt_pk_bf16_f32 v50, v92, v93
	v_cvt_pk_bf16_f32 v51, v94, v95
	ds_read_b64_tr_b16 v[56:57], v208
	ds_read_b64_tr_b16 v[58:59], v208 offset:512
	ds_read_b64_tr_b16 v[52:53], v209
	ds_read_b64_tr_b16 v[54:55], v209 offset:512
	s_waitcnt lgkmcnt(0)
	s_nop 1
	v_mfma_f32_32x32x16_bf16 v[32:47], v[56:59], v[48:51], v[32:47]
	v_mfma_f32_32x32x16_bf16 v[16:31], v[52:55], v[48:51], v[16:31]
	v_cvt_pk_bf16_f32 v48, v240, v239
	v_cvt_pk_bf16_f32 v49, v238, v237
	v_cvt_pk_bf16_f32 v50, v236, v235
	v_cvt_pk_bf16_f32 v51, v234, v233
	ds_read_b64_tr_b16 v[56:57], v210
	ds_read_b64_tr_b16 v[58:59], v210 offset:512
	ds_read_b64_tr_b16 v[52:53], v211
	ds_read_b64_tr_b16 v[54:55], v211 offset:512
	s_waitcnt lgkmcnt(0)
	s_nop 1
	v_mfma_f32_32x32x16_bf16 v[32:47], v[56:59], v[48:51], v[32:47]
	v_mfma_f32_32x32x16_bf16 v[16:31], v[52:55], v[48:51], v[16:31]
	v_cvt_pk_bf16_f32 v48, v232, v231
	v_cvt_pk_bf16_f32 v49, v230, v229
	v_cvt_pk_bf16_f32 v50, v185, v183
	v_cvt_pk_bf16_f32 v51, v181, v179
	ds_read_b64_tr_b16 v[56:57], v212
	ds_read_b64_tr_b16 v[58:59], v212 offset:512
	ds_read_b64_tr_b16 v[52:53], v213
	ds_read_b64_tr_b16 v[54:55], v213 offset:512
	s_waitcnt lgkmcnt(0)
	v_mov_b32_e32 v185, v104
	s_nop 0
	v_mfma_f32_32x32x16_bf16 v[32:47], v[56:59], v[48:51], v[32:47]
	v_mfma_f32_32x32x16_bf16 v[16:31], v[52:55], v[48:51], v[16:31]
	ds_bpermute_b32 v48, v178, v60
	s_waitcnt lgkmcnt(0)
	v_add_f32_e32 v50, v60, v48
	s_lshl_b64 s[6:7], s[94:95], 12
	s_add_u32 s6, s6, s77
	s_addc_u32 s7, s7, 0
	v_rcp_f32_e32 v52, v50
	s_nop 0
	v_lshl_add_u32 v48, s93, 8, v194
	v_ashrrev_i32_e32 v49, 31, v48
	v_lshlrev_b64 v[48:49], s8, v[48:49]
	s_ashr_i32 s77, s76, 31
	v_lshl_add_u64 v[48:49], s[6:7], 0, v[48:49]
	s_lshl_b64 s[6:7], s[76:77], 24
	s_add_u32 s6, s9, s6
	s_addc_u32 s7, s33, s7
	v_lshlrev_b64 v[54:55], 10, v[48:49]
	v_lshl_add_u64 v[54:55], s[6:7], 0, v[54:55]
	s_lshl_b32 s6, s92, 7
	s_mov_b32 s7, s71
	v_lshl_add_u64 v[54:55], v[54:55], 0, s[6:7]
	v_pk_mul_f32 v[32:33], v[32:33], v[52:53] op_sel_hi:[1,0]
	v_pk_mul_f32 v[34:35], v[34:35], v[52:53] op_sel_hi:[1,0]
	v_pk_mul_f32 v[16:17], v[16:17], v[52:53] op_sel_hi:[1,0]
	v_pk_mul_f32 v[18:19], v[18:19], v[52:53] op_sel_hi:[1,0]
	v_lshl_add_u64 v[54:55], v[54:55], 0, v[184:185]
	v_cvt_pk_bf16_f32 v32, v32, v33
	v_cvt_pk_bf16_f32 v33, v34, v35
	v_cvt_pk_bf16_f32 v16, v16, v17
	v_cvt_pk_bf16_f32 v17, v18, v19
	global_store_dwordx2 v[54:55], v[32:33], off
	v_pk_mul_f32 v[32:33], v[36:37], v[52:53] op_sel_hi:[1,0]
	v_pk_mul_f32 v[34:35], v[38:39], v[52:53] op_sel_hi:[1,0]
	global_store_dwordx2 v[54:55], v[16:17], off offset:64
	v_pk_mul_f32 v[16:17], v[20:21], v[52:53] op_sel_hi:[1,0]
	v_pk_mul_f32 v[18:19], v[22:23], v[52:53] op_sel_hi:[1,0]
	v_cvt_pk_bf16_f32 v32, v32, v33
	v_cvt_pk_bf16_f32 v33, v34, v35
	v_cvt_pk_bf16_f32 v16, v16, v17
	v_cvt_pk_bf16_f32 v17, v18, v19
	global_store_dwordx2 v[54:55], v[32:33], off offset:16
	v_pk_mul_f32 v[32:33], v[40:41], v[52:53] op_sel_hi:[1,0]
	v_pk_mul_f32 v[34:35], v[42:43], v[52:53] op_sel_hi:[1,0]
	global_store_dwordx2 v[54:55], v[16:17], off offset:80
	v_pk_mul_f32 v[16:17], v[24:25], v[52:53] op_sel_hi:[1,0]
	v_pk_mul_f32 v[18:19], v[26:27], v[52:53] op_sel_hi:[1,0]
	v_cvt_pk_bf16_f32 v32, v32, v33
	v_cvt_pk_bf16_f32 v33, v34, v35
	v_cvt_pk_bf16_f32 v16, v16, v17
	v_cvt_pk_bf16_f32 v17, v18, v19
	global_store_dwordx2 v[54:55], v[32:33], off offset:32
	v_pk_mul_f32 v[32:33], v[44:45], v[52:53] op_sel_hi:[1,0]
	v_pk_mul_f32 v[34:35], v[46:47], v[52:53] op_sel_hi:[1,0]
	global_store_dwordx2 v[54:55], v[16:17], off offset:96
	v_pk_mul_f32 v[16:17], v[28:29], v[52:53] op_sel_hi:[1,0]
	v_pk_mul_f32 v[18:19], v[30:31], v[52:53] op_sel_hi:[1,0]
	v_cvt_pk_bf16_f32 v32, v32, v33
	v_cvt_pk_bf16_f32 v33, v34, v35
	v_cvt_pk_bf16_f32 v16, v16, v17
	v_cvt_pk_bf16_f32 v17, v18, v19
	global_store_dwordx2 v[54:55], v[32:33], off offset:48
	global_store_dwordx2 v[54:55], v[16:17], off offset:112
	s_and_saveexec_b64 s[6:7], s[68:69]
	s_cbranch_execz .LBB0_490
	v_log_f32_e32 v16, v50
	s_lshl_b64 s[74:75], s[76:77], 19
	s_add_u32 s74, s10, s74
	s_addc_u32 s75, s11, s75
	v_add_f32_e32 v16, v187, v16
	v_mul_f32_e32 v18, 0x3f317218, v16
	v_lshlrev_b64 v[16:17], 5, v[48:49]
	s_mov_b32 s93, s71
	v_lshl_add_u64 v[16:17], s[74:75], 0, v[16:17]
	v_lshl_add_u64 v[16:17], s[92:93], 2, v[16:17]
	global_store_dword v[16:17], v18, off
	s_branch .LBB0_490

.LBB0_586:
	v_add_u32_e32 v157, v161, v127
	v_sub_u32_e32 v158, v127, v89
	v_sub_u32_e32 v193, v127, v88
	v_sub_u32_e32 v204, v127, v91
	v_sub_u32_e32 v210, v127, v90
	v_sub_u32_e32 v211, v127, v93
	v_sub_u32_e32 v212, v127, v92
	v_sub_u32_e32 v213, v127, v95
	v_sub_u32_e32 v214, v127, v94
	v_cvt_f32_u32_e32 v39, v157
	v_cvt_f32_u32_e32 v40, v193
	v_cvt_f32_u32_e32 v41, v158
	v_cvt_f32_u32_e32 v42, v210
	v_cvt_f32_u32_e32 v43, v204
	v_cvt_f32_u32_e32 v44, v212
	v_cvt_f32_u32_e32 v45, v211
	v_cvt_f32_u32_e32 v46, v214
	v_cvt_f32_u32_e32 v47, v213
	ds_read_b128 v[32:35], v115
	ds_read_b128 v[172:175], v115 offset:32
	ds_read_b128 v[176:179], v115 offset:64
	ds_read_b128 v[180:183], v115 offset:96
	v_add_u32_e32 v36, 0xffffdc00, v156
	v_add_u32_e32 v37, 0xfffffc00, v156
	v_add_u32_e32 v38, 0xffffe000, v156
	ds_read_b64_tr_b16 v[188:189], v36
	ds_read_b64_tr_b16 v[190:191], v36 offset:512
	ds_read_b64_tr_b16 v[184:185], v37
	ds_read_b64_tr_b16 v[186:187], v37 offset:512
	s_waitcnt lgkmcnt(0)
	ds_read_b64_tr_b16 v[198:199], v38
	ds_read_b64_tr_b16 v[200:201], v38 offset:512
	ds_read_b64_tr_b16 v[194:195], v156
	ds_read_b64_tr_b16 v[196:197], v156 offset:512
	s_waitcnt lgkmcnt(0)
	v_mul_f32_e32 v223, v151, v39
	v_mul_f32_e32 v224, v151, v40
	v_mul_f32_e32 v225, v151, v41
	v_mul_f32_e32 v231, v151, v42
	v_mul_f32_e32 v232, v151, v43
	v_mul_f32_e32 v233, v151, v44
	v_mul_f32_e32 v234, v151, v45
	v_mul_f32_e32 v235, v151, v46
	v_mul_f32_e32 v236, v151, v47
	s_waitcnt lgkmcnt(3)
	v_mfma_f32_32x32x16_bf16 v[32:47], v[32:35], v[72:75], 0
	v_add_u32_e32 v221, -1, v157
	v_sub_u32_e32 v215, v127, v97
	v_sub_u32_e32 v216, v127, v96
	v_sub_u32_e32 v217, v127, v99
	v_sub_u32_e32 v218, v127, v98
	v_sub_u32_e32 v219, v127, v101
	v_sub_u32_e32 v220, v127, v100
	s_waitcnt lgkmcnt(2)
	v_mfma_f32_32x32x16_bf16 v[32:47], v[172:175], v[76:79], v[32:47]
	v_cvt_f32_u32_e32 v222, v221
	v_cvt_f32_u32_e32 v202, v216
	v_cvt_f32_u32_e32 v203, v215
	v_cvt_f32_u32_e32 v206, v218
	v_cvt_f32_u32_e32 v207, v217
	v_cvt_f32_u32_e32 v208, v220
	v_cvt_f32_u32_e32 v209, v219
	s_waitcnt lgkmcnt(1)
	v_mfma_f32_32x32x16_bf16 v[32:47], v[176:179], v[80:83], v[32:47]
	v_mul_f32_e32 v222, v151, v222
	v_mul_f32_e32 v237, v151, v202
	v_mul_f32_e32 v238, v151, v203
	v_mul_f32_e32 v239, v151, v206
	v_mul_f32_e32 v240, v151, v207
	v_mul_f32_e32 v208, v151, v208
	v_mul_f32_e32 v209, v151, v209
	s_waitcnt lgkmcnt(0)
	v_mfma_f32_32x32x16_bf16 v[32:47], v[180:183], v[84:87], v[32:47]
	v_exp_f32_e32 v223, v223
	v_exp_f32_e32 v202, v224
	v_exp_f32_e32 v203, v225
	v_exp_f32_e32 v172, v231
	v_exp_f32_e32 v173, v232
	v_exp_f32_e32 v174, v233
	v_exp_f32_e32 v175, v234
	v_exp_f32_e32 v222, v222
	v_exp_f32_e32 v206, v235
	v_exp_f32_e32 v207, v236
	v_exp_f32_e32 v176, v237
	v_exp_f32_e32 v177, v238
	v_exp_f32_e32 v178, v239
	v_exp_f32_e32 v179, v240
	v_exp_f32_e32 v208, v208
	v_exp_f32_e32 v209, v209
	v_mul_f32_e32 v180, v223, v32
	v_mul_f32_e32 v181, v222, v33
	v_cmp_lt_i32_e32 vcc, -1, v221
	v_pk_mul_f32 v[32:33], v[202:203], v[34:35]
	v_pk_mul_f32 v[34:35], v[172:173], v[36:37]
	v_pk_mul_f32 v[36:37], v[174:175], v[38:39]
	v_pk_mul_f32 v[38:39], v[206:207], v[40:41]
	v_pk_mul_f32 v[40:41], v[176:177], v[42:43]
	v_pk_mul_f32 v[42:43], v[178:179], v[44:45]
	v_pk_mul_f32 v[44:45], v[208:209], v[46:47]
	v_cmp_lt_i32_e64 s[0:1], -1, v157
	v_cndmask_b32_e32 v47, 0, v181, vcc
	v_cvt_pk_bf16_f32 v33, v32, v33
	v_cmp_lt_i32_e32 vcc, -1, v193
	v_cvt_pk_bf16_f32 v34, v34, v35
	v_cvt_pk_bf16_f32 v35, v36, v37
	v_cndmask_b32_e64 v46, 0, v180, s[0:1]
	v_cmp_lt_i32_e64 s[0:1], -1, v210
	v_cmp_lt_i32_e64 s[4:5], -1, v212
	v_cvt_pk_bf16_f32 v36, v38, v39
	v_cvt_pk_bf16_f32 v37, v40, v41
	v_cvt_pk_bf16_f32 v39, v44, v45
	v_lshrrev_b32_e32 v40, 16, v34
	v_cmp_lt_i32_e64 s[14:15], -1, v204
	v_lshrrev_b32_e32 v41, 16, v35
	v_cmp_lt_i32_e64 s[16:17], -1, v211
	v_cndmask_b32_e32 v45, 0, v33, vcc
	v_lshrrev_b32_e32 v33, 16, v33
	v_cmp_lt_i32_e32 vcc, -1, v158
	v_cndmask_b32_e64 v34, 0, v34, s[0:1]
	v_cndmask_b32_e64 v35, 0, v35, s[4:5]
	v_cndmask_b32_e32 v33, 0, v33, vcc
	v_cndmask_b32_e64 v40, 0, v40, s[14:15]
	v_cndmask_b32_e64 v41, 0, v41, s[16:17]
	v_cvt_pk_bf16_f32 v32, v46, v47
	v_perm_b32 v33, v33, v45, s29
	v_perm_b32 v34, v40, v34, s29
	v_perm_b32 v35, v41, v35, s29
	v_cmp_lt_i32_e64 s[6:7], -1, v214
	v_cvt_pk_bf16_f32 v38, v42, v43
	v_mfma_f32_32x32x16_bf16 v[0:15], v[188:191], v[32:35], v[0:15]
	v_cmp_lt_i32_e64 s[8:9], -1, v216
	v_cmp_lt_i32_e64 s[10:11], -1, v218
	v_cmp_lt_i32_e64 s[12:13], -1, v220
	v_lshrrev_b32_e32 v42, 16, v37
	v_cmp_lt_i32_e64 s[18:19], -1, v215
	v_lshrrev_b32_e32 v43, 16, v38
	v_cmp_lt_i32_e64 s[20:21], -1, v217
	v_mfma_f32_32x32x16_bf16 v[16:31], v[184:187], v[32:35], v[16:31]
	v_lshrrev_b32_e32 v44, 16, v39
	v_cmp_lt_i32_e64 s[22:23], -1, v219
	v_cndmask_b32_e64 v40, 0, v36, s[6:7]
	v_lshrrev_b32_e32 v36, 16, v36
	v_cmp_lt_i32_e32 vcc, -1, v213
	v_cndmask_b32_e64 v37, 0, v37, s[8:9]
	v_cndmask_b32_e64 v38, 0, v38, s[10:11]
	v_cndmask_b32_e64 v39, 0, v39, s[12:13]
	v_cndmask_b32_e32 v36, 0, v36, vcc
	v_cndmask_b32_e64 v33, 0, v42, s[18:19]
	v_cndmask_b32_e64 v34, 0, v43, s[20:21]
	v_cndmask_b32_e64 v35, 0, v44, s[22:23]
	v_perm_b32 v32, v36, v40, s29
	v_perm_b32 v33, v33, v37, s29
	v_perm_b32 v34, v34, v38, s29
	v_perm_b32 v35, v35, v39, s29
	s_add_i32 s33, s33, -1
	v_subrev_u32_e32 v127, 32, v127
	v_mfma_f32_32x32x16_bf16 v[0:15], v[198:201], v[32:35], v[0:15]
	v_add_u32_e32 v115, 0x1200, v115
	s_cmp_lg_u32 s33, 0
	v_add_u32_e32 v156, 0x800, v156
	v_mfma_f32_32x32x16_bf16 v[16:31], v[194:197], v[32:35], v[16:31]
	s_cbranch_scc1 .LBB0_586
	v_or_b32_e32 v32, s41, v228
	s_movk_i32 s0, 0x204
	v_mul_lo_u32 v32, v32, s0
	s_lshl_b32 s0, s3, 8
	s_add_i32 s0, s0, 0
	v_add_u32_e32 v32, s0, v32
	v_add_u32_e32 v172, v32, v126
	s_waitcnt lgkmcnt(0)
	s_barrier
	ds_write2_b32 v172, v0, v1 offset1:1
	ds_write2_b32 v172, v2, v3 offset0:2 offset1:3
	ds_write2_b32 v172, v4, v5 offset0:8 offset1:9
	ds_write2_b32 v172, v6, v7 offset0:10 offset1:11
	ds_write2_b32 v172, v8, v9 offset0:16 offset1:17
	ds_write2_b32 v172, v10, v11 offset0:18 offset1:19
	ds_write2_b32 v172, v12, v13 offset0:24 offset1:25
	ds_write2_b32 v172, v14, v15 offset0:26 offset1:27
	ds_write2_b32 v172, v16, v17 offset0:32 offset1:33
	ds_write2_b32 v172, v18, v19 offset0:34 offset1:35
	ds_write2_b32 v172, v20, v21 offset0:40 offset1:41
	ds_write2_b32 v172, v22, v23 offset0:42 offset1:43
	ds_write2_b32 v172, v24, v25 offset0:48 offset1:49
	ds_write2_b32 v172, v26, v27 offset0:50 offset1:51
	ds_write2_b32 v172, v28, v29 offset0:56 offset1:57
	ds_write2_b32 v172, v30, v31 offset0:58 offset1:59
	v_mul_u32_u24_e32 v0, 0x204, v112
	v_lshlrev_b32_e32 v32, 2, v121
	v_add3_u32 v158, 0, v0, v32
	v_mbcnt_lo_u32_b32 v0, -1, 0
	v_mbcnt_hi_u32_b32 v182, -1, v0
	v_and_b32_e32 v1, 64, v182
	v_xor_b32_e32 v0, 1, v182
	v_add_u32_e32 v183, 64, v1
	v_cmp_lt_i32_e32 vcc, v0, v183
	s_lshl_b32 s0, s36, 2
	s_add_u32 s0, s72, s0
	v_cndmask_b32_e32 v0, v182, v0, vcc
	v_lshlrev_b32_e32 v157, 2, v0
	v_xor_b32_e32 v0, 2, v182
	v_cmp_lt_i32_e32 vcc, v0, v183
	s_waitcnt lgkmcnt(0)
	s_barrier
	s_addc_u32 s1, s73, 0
	v_cndmask_b32_e32 v0, v182, v0, vcc
	v_mov_b32_e32 v33, 0
	v_readlane_b32 s4, v254, 0
	v_lshlrev_b32_e32 v156, 2, v0
	v_lshl_add_u64 v[80:81], s[0:1], 0, v[32:33]
	global_load_dwordx4 v[16:19], v32, s[0:1] offset:48
	global_load_dwordx4 v[20:23], v32, s[0:1] offset:32
	global_load_dwordx4 v[24:27], v32, s[0:1] offset:16
	global_load_dwordx4 v[28:31], v32, s[0:1]
	global_load_dwordx4 v[0:3], v32, s[0:1] offset:112
	global_load_dwordx4 v[4:7], v32, s[0:1] offset:96
	global_load_dwordx4 v[8:11], v32, s[0:1] offset:80
	global_load_dwordx4 v[12:15], v32, s[0:1] offset:64
	s_lshl_b64 s[0:1], s[34:35], 12
	v_readlane_b32 s6, v254, 2
	v_readlane_b32 s7, v254, 3
	s_add_u32 s0, s6, s0
	v_lshlrev_b32_e32 v32, 11, v119
	s_addc_u32 s1, s7, s1
	v_and_b32_e32 v32, 0x7f800, v32
	v_lshl_add_u64 v[34:35], s[0:1], 0, v[32:33]
	v_lshlrev_b32_e32 v32, 16, v70
	v_and_b32_e32 v38, 0xffff0000, v70
	v_mul_f32_e32 v36, 0xbfb8aa3b, v32
	v_mul_f32_e32 v37, 0xbfb8aa3b, v38
	v_exp_f32_e32 v36, v36
	v_exp_f32_e32 v37, v37
	v_lshlrev_b32_e32 v45, 16, v69
	v_and_b32_e32 v46, 0xffff0000, v69
	v_lshlrev_b32_e32 v74, 16, v71
	v_pk_add_f32 v[36:37], v[36:37], 1.0 op_sel_hi:[1,0]
	v_and_b32_e32 v44, 0xffff0000, v71
	v_lshlrev_b32_e32 v79, 16, v66
	v_and_b32_e32 v66, 0xffff0000, v66
	v_lshlrev_b32_e32 v119, 16, v67
	v_rcp_f32_e32 v39, v37
	s_nop 0
	v_mul_f32_e32 v37, v38, v39
	v_mul_f32_e32 v39, 0xbfb8aa3b, v46
	v_mul_f32_e32 v38, 0xbfb8aa3b, v45
	v_exp_f32_e32 v38, v38
	v_exp_f32_e32 v39, v39
	s_nop 0
	v_pk_add_f32 v[38:39], v[38:39], 1.0 op_sel_hi:[1,0]
	v_rcp_f32_e32 v40, v36
	s_nop 0
	v_mul_f32_e32 v36, v32, v40
	v_and_b32_e32 v86, 0xffff0000, v67
	v_rcp_f32_e32 v32, v39
	s_nop 0
	v_mul_f32_e32 v39, v46, v32
	v_lshlrev_b32_e32 v87, 16, v65
	v_lshlrev_b32_e32 v42, 16, v68
	v_and_b32_e32 v43, 0xffff0000, v68
	v_mul_f32_e32 v40, 0xbfb8aa3b, v42
	v_mul_f32_e32 v41, 0xbfb8aa3b, v43
	v_exp_f32_e32 v40, v40
	v_exp_f32_e32 v41, v41
	v_rcp_f32_e32 v32, v38
	s_nop 0
	v_mul_f32_e32 v38, v45, v32
	v_and_b32_e32 v65, 0xffff0000, v65
	v_lshlrev_b32_e32 v121, 16, v64
	v_pk_add_f32 v[40:41], v[40:41], 1.0 op_sel_hi:[1,0]
	v_and_b32_e32 v126, 0xffff0000, v64
	v_mul_f32_e32 v64, 0xbfb8aa3b, v121
	v_lshlrev_b32_e32 v174, 16, v62
	v_and_b32_e32 v62, 0xffff0000, v62
	v_rcp_f32_e32 v45, v41
	s_nop 0
	v_mul_f32_e32 v41, v43, v45
	v_lshlrev_b32_e32 v184, 16, v60
	v_rcp_f32_e32 v43, v40
	s_nop 0
	v_mul_f32_e32 v40, v42, v43
	v_mul_f32_e32 v42, 0xbfb8aa3b, v74
	v_mul_f32_e32 v43, 0xbfb8aa3b, v44
	v_exp_f32_e32 v42, v42
	v_exp_f32_e32 v43, v43
	ds_read2_b32 v[46:47], v158 offset0:6 offset1:7
	ds_read2_b32 v[68:69], v158 offset0:4 offset1:5
	ds_read2_b32 v[70:71], v158 offset0:2 offset1:3
	ds_read2_b32 v[72:73], v158 offset1:1
	v_readlane_b32 s5, v254, 1
	s_mov_b32 s37, 0
	v_pk_add_f32 v[42:43], v[42:43], 1.0 op_sel_hi:[1,0]
	s_lshl_b32 s36, s36, 1
	s_waitcnt lgkmcnt(0)
	v_add_f32_e32 v32, 0, v72
	v_add_f32_e32 v32, v32, v73
	v_add_f32_e32 v32, v32, v70
	v_rcp_f32_e32 v45, v43
	s_nop 0
	v_mul_f32_e32 v43, v44, v45
	v_mul_f32_e32 v44, 0xbfb8aa3b, v79
	v_mul_f32_e32 v45, 0xbfb8aa3b, v66
	v_exp_f32_e32 v44, v44
	v_exp_f32_e32 v45, v45
	v_rcp_f32_e32 v75, v42
	s_nop 0
	v_mul_f32_e32 v42, v74, v75
	v_pk_add_f32 v[44:45], v[44:45], 1.0 op_sel_hi:[1,0]
	v_add_f32_e32 v32, v32, v71
	v_add_f32_e32 v32, v32, v68
	v_add_f32_e32 v32, v32, v69
	v_add_f32_e32 v32, v32, v46
	v_rcp_f32_e32 v67, v45
	s_nop 0
	v_mul_f32_e32 v45, v66, v67
	v_mul_f32_e32 v67, 0xbfb8aa3b, v65
	v_mul_f32_e32 v66, 0xbfb8aa3b, v87
	v_exp_f32_e32 v66, v66
	v_exp_f32_e32 v67, v67
	s_nop 0
	v_pk_add_f32 v[66:67], v[66:67], 1.0 op_sel_hi:[1,0]
	v_rcp_f32_e32 v74, v44
	s_nop 0
	v_mul_f32_e32 v44, v79, v74
	v_add_f32_e32 v32, v32, v47
	v_rcp_f32_e32 v74, v67
	s_nop 0
	v_mul_f32_e32 v65, v65, v74
	v_lshl_add_u64 v[34:35], v[34:35], 0, s[36:37]
	v_exp_f32_e32 v74, v64
	v_mul_f32_e32 v64, 0xbfb8aa3b, v126
	v_exp_f32_e32 v75, v64
	v_rcp_f32_e32 v64, v66
	s_nop 0
	v_mul_f32_e32 v64, v87, v64
	ds_read2_b32 v[76:77], v158 offset0:14 offset1:15
	ds_read2_b32 v[78:79], v158 offset0:12 offset1:13
	ds_read2_b32 v[82:83], v158 offset0:10 offset1:11
	ds_read2_b32 v[84:85], v158 offset0:8 offset1:9
	v_mov_b32_e32 v115, v33
	v_pk_add_f32 v[74:75], v[74:75], 1.0 op_sel_hi:[1,0]
	v_lshl_add_u64 v[34:35], v[34:35], 0, v[114:115]
	s_waitcnt lgkmcnt(0)
	v_add_f32_e32 v32, v32, v84
	v_add_f32_e32 v32, v32, v85
	v_add_f32_e32 v32, v32, v82
	v_rcp_f32_e32 v67, v75
	s_nop 0
	v_mul_f32_e32 v67, v126, v67
	v_add_f32_e32 v32, v32, v83
	v_rcp_f32_e32 v66, v74
	s_nop 0
	v_mul_f32_e32 v66, v121, v66
	v_mul_f32_e32 v74, 0xbfb8aa3b, v119
	v_mul_f32_e32 v75, 0xbfb8aa3b, v86
	v_exp_f32_e32 v74, v74
	v_exp_f32_e32 v75, v75
	v_add_f32_e32 v32, v32, v78
	v_add_f32_e32 v32, v32, v79
	v_add_f32_e32 v32, v32, v76
	v_pk_add_f32 v[74:75], v[74:75], 1.0 op_sel_hi:[1,0]
	v_add_f32_e32 v32, v32, v77
	s_bitset1_b32 s34, 7
	s_movk_i32 s3, 0x1800
	v_rcp_f32_e32 v87, v75
	s_nop 0
	v_mul_f32_e32 v75, v86, v87
	v_mul_f32_e32 v86, 0xbfb8aa3b, v174
	v_mul_f32_e32 v87, 0xbfb8aa3b, v62
	v_exp_f32_e32 v86, v86
	v_exp_f32_e32 v87, v87
	v_rcp_f32_e32 v121, v74
	s_nop 0
	v_mul_f32_e32 v74, v119, v121
	v_pk_add_f32 v[86:87], v[86:87], 1.0 op_sel_hi:[1,0]
	v_lshlrev_b32_e32 v119, 16, v63
	v_and_b32_e32 v121, 0xffff0000, v63
	v_lshlrev_b32_e32 v173, 16, v61
	v_and_b32_e32 v61, 0xffff0000, v61
	v_mul_f32_e32 v126, 0xbfb8aa3b, v173
	v_mul_f32_e32 v127, 0xbfb8aa3b, v61
	v_rcp_f32_e32 v63, v87
	s_nop 0
	v_mul_f32_e32 v63, v62, v63
	v_exp_f32_e32 v126, v126
	v_exp_f32_e32 v127, v127
	s_nop 0
	v_pk_add_f32 v[126:127], v[126:127], 1.0 op_sel_hi:[1,0]
	v_rcp_f32_e32 v62, v86
	s_nop 0
	v_mul_f32_e32 v62, v174, v62
	v_rcp_f32_e32 v87, v127
	s_nop 0
	v_mul_f32_e32 v87, v61, v87
	v_and_b32_e32 v127, 0xffff0000, v60
	v_mul_f32_e32 v60, 0xbfb8aa3b, v184
	v_mul_f32_e32 v61, 0xbfb8aa3b, v127
	v_exp_f32_e32 v60, v60
	v_exp_f32_e32 v61, v61
	v_rcp_f32_e32 v86, v126
	s_nop 0
	v_mul_f32_e32 v86, v173, v86
	ds_read2_b32 v[174:175], v158 offset0:22 offset1:23
	ds_read2_b32 v[176:177], v158 offset0:20 offset1:21
	ds_read2_b32 v[178:179], v158 offset0:18 offset1:19
	ds_read2_b32 v[180:181], v158 offset0:16 offset1:17
	v_pk_add_f32 v[60:61], v[60:61], 1.0 op_sel_hi:[1,0]
	s_nop 0
	s_waitcnt lgkmcnt(0)
	v_add_f32_e32 v32, v32, v180
	v_add_f32_e32 v32, v32, v181
	v_add_f32_e32 v32, v32, v178
	v_rcp_f32_e32 v126, v61
	s_nop 0
	v_mul_f32_e32 v127, v127, v126
	v_add_f32_e32 v32, v32, v179
	v_rcp_f32_e32 v126, v60
	s_nop 0
	v_mul_f32_e32 v126, v184, v126
	v_mul_f32_e32 v60, 0xbfb8aa3b, v119
	v_mul_f32_e32 v61, 0xbfb8aa3b, v121
	v_exp_f32_e32 v60, v60
	v_exp_f32_e32 v61, v61
	v_add_f32_e32 v32, v32, v176
	v_add_f32_e32 v32, v32, v177
	v_add_f32_e32 v32, v32, v174
	v_pk_add_f32 v[184:185], v[60:61], 1.0 op_sel_hi:[1,0]
	ds_read2_b32 v[186:187], v158 offset0:30 offset1:31
	ds_read2_b32 v[60:61], v158 offset0:28 offset1:29
	ds_read2_b32 v[188:189], v158 offset0:26 offset1:27
	ds_read2_b32 v[190:191], v158 offset0:24 offset1:25
	v_add_f32_e32 v32, v32, v175
	s_waitcnt lgkmcnt(0)
	v_add_f32_e32 v32, v32, v190
	v_add_f32_e32 v32, v32, v191
	v_add_f32_e32 v32, v32, v188
	v_add_f32_e32 v32, v32, v189
	v_add_f32_e32 v32, v32, v60
	v_add_f32_e32 v32, v32, v61
	v_add_f32_e32 v32, v32, v186
	v_add_f32_e32 v32, v32, v187
	ds_bpermute_b32 v194, v157, v32
	s_waitcnt lgkmcnt(0)
	v_add_f32_e32 v32, v32, v194
	ds_bpermute_b32 v194, v156, v32
	v_rcp_f32_e32 v173, v185
	s_nop 0
	v_mul_f32_e32 v185, v121, v173
	s_waitcnt lgkmcnt(0)
	v_add_f32_e32 v32, v32, v194
	v_mul_f32_e32 v32, 0x3c000000, v32
	v_pk_add_f32 v[72:73], v[72:73], v[32:33] op_sel_hi:[1,0] neg_lo:[0,1] neg_hi:[0,1]
	v_pk_add_f32 v[70:71], v[70:71], v[32:33] op_sel_hi:[1,0] neg_lo:[0,1] neg_hi:[0,1]
	v_pk_mul_f32 v[194:195], v[72:73], v[72:73]
	v_pk_mul_f32 v[196:197], v[70:71], v[70:71]
	v_pk_add_f32 v[198:199], v[68:69], v[32:33] op_sel_hi:[1,0] neg_lo:[0,1] neg_hi:[0,1]
	v_pk_add_f32 v[202:203], v[46:47], v[32:33] op_sel_hi:[1,0] neg_lo:[0,1] neg_hi:[0,1]
	v_pk_add_f32 v[84:85], v[84:85], v[32:33] op_sel_hi:[1,0] neg_lo:[0,1] neg_hi:[0,1]
	v_pk_add_f32 v[82:83], v[82:83], v[32:33] op_sel_hi:[1,0] neg_lo:[0,1] neg_hi:[0,1]
	v_pk_add_f32 v[78:79], v[78:79], v[32:33] op_sel_hi:[1,0] neg_lo:[0,1] neg_hi:[0,1]
	v_pk_add_f32 v[76:77], v[76:77], v[32:33] op_sel_hi:[1,0] neg_lo:[0,1] neg_hi:[0,1]
	v_pk_add_f32 v[180:181], v[180:181], v[32:33] op_sel_hi:[1,0] neg_lo:[0,1] neg_hi:[0,1]
	v_pk_add_f32 v[178:179], v[178:179], v[32:33] op_sel_hi:[1,0] neg_lo:[0,1] neg_hi:[0,1]
	v_pk_add_f32 v[176:177], v[176:177], v[32:33] op_sel_hi:[1,0] neg_lo:[0,1] neg_hi:[0,1]
	v_pk_add_f32 v[174:175], v[174:175], v[32:33] op_sel_hi:[1,0] neg_lo:[0,1] neg_hi:[0,1]
	v_pk_add_f32 v[190:191], v[190:191], v[32:33] op_sel_hi:[1,0] neg_lo:[0,1] neg_hi:[0,1]
	v_pk_add_f32 v[68:69], v[188:189], v[32:33] op_sel_hi:[1,0] neg_lo:[0,1] neg_hi:[0,1]
	v_pk_add_f32 v[60:61], v[60:61], v[32:33] op_sel_hi:[1,0] neg_lo:[0,1] neg_hi:[0,1]
	v_pk_add_f32 v[46:47], v[186:187], v[32:33] op_sel_hi:[1,0] neg_lo:[0,1] neg_hi:[0,1]
	v_add_f32_e32 v32, v194, v195
	v_add_f32_e32 v32, v196, v32
	v_pk_mul_f32 v[200:201], v[198:199], v[198:199]
	v_add_f32_e32 v32, v197, v32
	v_add_f32_e32 v32, v200, v32
	v_pk_mul_f32 v[206:207], v[202:203], v[202:203]
	v_add_f32_e32 v32, v201, v32
	v_add_f32_e32 v32, v206, v32
	v_pk_mul_f32 v[208:209], v[84:85], v[84:85]
	v_add_f32_e32 v32, v207, v32
	v_add_f32_e32 v32, v208, v32
	v_pk_mul_f32 v[210:211], v[82:83], v[82:83]
	v_add_f32_e32 v32, v209, v32
	v_add_f32_e32 v32, v210, v32
	v_pk_mul_f32 v[212:213], v[78:79], v[78:79]
	v_add_f32_e32 v32, v211, v32
	v_add_f32_e32 v32, v212, v32
	v_pk_mul_f32 v[214:215], v[76:77], v[76:77]
	v_add_f32_e32 v32, v213, v32
	v_add_f32_e32 v32, v214, v32
	v_pk_mul_f32 v[216:217], v[180:181], v[180:181]
	v_add_f32_e32 v32, v215, v32
	v_add_f32_e32 v32, v216, v32
	v_pk_mul_f32 v[218:219], v[178:179], v[178:179]
	v_add_f32_e32 v32, v217, v32
	v_add_f32_e32 v32, v218, v32
	v_pk_mul_f32 v[220:221], v[176:177], v[176:177]
	v_add_f32_e32 v32, v219, v32
	v_add_f32_e32 v32, v220, v32
	v_pk_mul_f32 v[222:223], v[174:175], v[174:175]
	v_add_f32_e32 v32, v221, v32
	v_add_f32_e32 v32, v222, v32
	v_pk_mul_f32 v[224:225], v[190:191], v[190:191]
	v_add_f32_e32 v32, v223, v32
	v_add_f32_e32 v32, v224, v32
	v_pk_mul_f32 v[188:189], v[68:69], v[68:69]
	v_add_f32_e32 v32, v225, v32
	v_add_f32_e32 v32, v188, v32
	v_pk_mul_f32 v[232:233], v[60:61], v[60:61]
	v_add_f32_e32 v32, v189, v32
	v_add_f32_e32 v32, v232, v32
	v_pk_mul_f32 v[186:187], v[46:47], v[46:47]
	v_add_f32_e32 v32, v233, v32
	v_add_f32_e32 v32, v186, v32
	v_add_f32_e32 v32, v187, v32
	ds_bpermute_b32 v186, v157, v32
	s_mov_b32 s0, 0xf800000
	s_waitcnt lgkmcnt(0)
	v_add_f32_e32 v32, v32, v186
	ds_bpermute_b32 v173, v156, v32
	s_waitcnt lgkmcnt(0)
	v_add_f32_e32 v32, v32, v173
	v_mov_b32_e32 v173, 0x358637bd
	v_fmac_f32_e32 v173, 0x3c000000, v32
	v_mul_f32_e32 v32, 0x4f800000, v173
	v_cmp_gt_f32_e64 s[0:1], s0, v173
	s_nop 1
	v_cndmask_b32_e64 v32, v173, v32, s[0:1]
	v_sqrt_f32_e32 v173, v32
	s_nop 0
	v_add_u32_e32 v187, -1, v173
	v_fma_f32 v188, -v187, v173, v32
	v_cmp_ge_f32_e64 s[4:5], 0, v188
	v_add_u32_e32 v188, 1, v173
	v_rcp_f32_e32 v121, v184
	s_nop 0
	v_mul_f32_e32 v184, v119, v121
	v_cndmask_b32_e64 v187, v173, v187, s[4:5]
	v_fma_f32 v173, -v188, v173, v32
	v_cmp_lt_f32_e64 s[4:5], 0, v173
	s_nop 1
	v_cndmask_b32_e64 v173, v187, v188, s[4:5]
	v_mul_f32_e32 v187, 0x37800000, v173
	v_cndmask_b32_e64 v173, v173, v187, s[0:1]
	v_mov_b32_e32 v187, 0x260
	v_cmp_class_f32_e64 s[0:1], v32, v187
	s_nop 1
	v_cndmask_b32_e64 v32, v173, v32, s[0:1]
	v_rcp_f32_e32 v32, v32
	s_nop 0
	v_pk_mul_f32 v[72:73], v[72:73], v[32:33] op_sel_hi:[1,0]
	v_mov_b32_e32 v119, v33
	s_waitcnt vmcnt(4)
	v_pk_mul_f32 v[28:29], v[28:29], v[72:73]
	v_mov_b32_e32 v121, v33
	v_pk_mul_f32 v[28:29], v[40:41], v[28:29]
	v_pk_mul_f32 v[40:41], v[70:71], v[32:33] op_sel_hi:[1,0]
	s_nop 0
	v_pk_mul_f32 v[30:31], v[30:31], v[40:41]
	v_lshlrev_b32_e32 v40, 16, v50
	v_pk_mul_f32 v[30:31], v[38:39], v[30:31]
	v_pk_mul_f32 v[38:39], v[198:199], v[32:33] op_sel_hi:[1,0]
	v_and_b32_e32 v41, 0xffff0000, v50
	v_pk_mul_f32 v[24:25], v[24:25], v[38:39]
	v_pk_fma_f32 v[40:41], v[124:125], v[146:147], v[40:41] op_sel_hi:[0,1,1]
	v_pk_mul_f32 v[36:37], v[36:37], v[24:25]
	v_pk_mul_f32 v[24:25], v[202:203], v[32:33] op_sel_hi:[1,0]
	s_nop 0
	v_pk_mul_f32 v[24:25], v[26:27], v[24:25]
	v_cvt_pk_bf16_f32 v26, v36, v37
	v_pk_mul_f32 v[38:39], v[42:43], v[24:25]
	v_cvt_pk_bf16_f32 v24, v28, v29
	v_cvt_pk_bf16_f32 v25, v30, v31
	v_cvt_pk_bf16_f32 v27, v38, v39
	global_store_dwordx4 v[34:35], v[24:27], off
	v_mov_b32_e32 v28, 0x1800
	v_and_b32_e32 v29, 0xffff0000, v52
	v_pk_mul_f32 v[24:25], v[84:85], v[32:33] op_sel_hi:[1,0]
	v_lshlrev_b32_e32 v30, 16, v53
	v_pk_mul_f32 v[20:21], v[20:21], v[24:25]
	v_pk_mul_f32 v[24:25], v[82:83], v[32:33] op_sel_hi:[1,0]
	v_pk_mul_f32 v[20:21], v[66:67], v[20:21]
	v_pk_mul_f32 v[22:23], v[22:23], v[24:25]
	v_pk_mul_f32 v[24:25], v[78:79], v[32:33] op_sel_hi:[1,0]
	v_pk_mul_f32 v[22:23], v[64:65], v[22:23]
	v_pk_mul_f32 v[16:17], v[16:17], v[24:25]
	v_lshl_add_u64 v[82:83], s[34:35], 0, v[112:113]
	v_pk_mul_f32 v[24:25], v[44:45], v[16:17]
	v_pk_mul_f32 v[16:17], v[76:77], v[32:33] op_sel_hi:[1,0]
	v_and_b32_e32 v31, 0xffff0000, v53
	v_pk_mul_f32 v[16:17], v[18:19], v[16:17]
	v_cvt_pk_bf16_f32 v18, v24, v25
	v_pk_mul_f32 v[26:27], v[74:75], v[16:17]
	v_cvt_pk_bf16_f32 v16, v20, v21
	v_cvt_pk_bf16_f32 v17, v22, v23
	v_cvt_pk_bf16_f32 v19, v26, v27
	global_store_dwordx4 v[34:35], v[16:19], off offset:16
	v_lshlrev_b32_e32 v20, 16, v56
	v_and_b32_e32 v21, 0xffff0000, v56
	v_pk_mul_f32 v[16:17], v[180:181], v[32:33] op_sel_hi:[1,0]
	v_mov_b64_e32 v[24:25], s[26:27]
	s_waitcnt vmcnt(2)
	v_pk_mul_f32 v[12:13], v[12:13], v[16:17]
	v_pk_mul_f32 v[16:17], v[178:179], v[32:33] op_sel_hi:[1,0]
	v_pk_mul_f32 v[12:13], v[126:127], v[12:13]
	v_pk_mul_f32 v[14:15], v[14:15], v[16:17]
	v_pk_mul_f32 v[16:17], v[176:177], v[32:33] op_sel_hi:[1,0]
	v_pk_mul_f32 v[14:15], v[86:87], v[14:15]
	v_pk_mul_f32 v[8:9], v[8:9], v[16:17]
	v_lshlrev_b32_e32 v36, 16, v48
	v_pk_mul_f32 v[16:17], v[62:63], v[8:9]
	v_pk_mul_f32 v[8:9], v[174:175], v[32:33] op_sel_hi:[1,0]
	v_and_b32_e32 v37, 0xffff0000, v48
	v_pk_mul_f32 v[8:9], v[10:11], v[8:9]
	v_mul_f32_e32 v10, 0xbfb8aa3b, v20
	v_mul_f32_e32 v11, 0xbfb8aa3b, v21
	v_exp_f32_e32 v10, v10
	v_exp_f32_e32 v11, v11
	v_pk_mul_f32 v[18:19], v[184:185], v[8:9]
	v_cvt_pk_bf16_f32 v8, v12, v13
	v_cvt_pk_bf16_f32 v9, v14, v15
	v_pk_add_f32 v[12:13], v[10:11], 1.0 op_sel_hi:[1,0]
	v_cvt_pk_bf16_f32 v10, v16, v17
	v_cvt_pk_bf16_f32 v11, v18, v19
	global_store_dwordx4 v[34:35], v[8:11], off offset:32
	v_and_b32_e32 v16, 0xffff0000, v57
	v_lshlrev_b32_e32 v38, 16, v49
	v_rcp_f32_e32 v9, v13
	s_nop 0
	v_mul_f32_e32 v9, v21, v9
	v_lshlrev_b32_e32 v15, 16, v57
	v_mul_f32_e32 v10, 0xbfb8aa3b, v15
	v_mul_f32_e32 v11, 0xbfb8aa3b, v16
	v_exp_f32_e32 v10, v10
	v_exp_f32_e32 v11, v11
	v_rcp_f32_e32 v8, v12
	s_nop 0
	v_mul_f32_e32 v8, v20, v8
	v_pk_mul_f32 v[12:13], v[190:191], v[32:33] op_sel_hi:[1,0]
	v_pk_add_f32 v[10:11], v[10:11], 1.0 op_sel_hi:[1,0]
	v_pk_mul_f32 v[4:5], v[4:5], v[12:13]
	v_pk_mul_f32 v[4:5], v[8:9], v[4:5]
	v_lshl_add_u64 v[20:21], s[34:35], 0, v[116:117]
	v_mad_u64_u32 v[22:23], s[4:5], v20, s3, v[24:25]
	v_rcp_f32_e32 v9, v11
	s_nop 0
	v_mul_f32_e32 v9, v16, v9
	v_lshlrev_b32_e32 v16, 16, v58
	v_and_b32_e32 v17, 0xffff0000, v58
	v_mul_f32_e32 v12, 0xbfb8aa3b, v16
	v_mul_f32_e32 v13, 0xbfb8aa3b, v17
	v_exp_f32_e32 v12, v12
	v_exp_f32_e32 v13, v13
	v_rcp_f32_e32 v8, v10
	s_nop 0
	v_mul_f32_e32 v8, v15, v8
	v_mad_u32_u24 v23, v21, s3, v23
	v_pk_add_f32 v[10:11], v[12:13], 1.0 op_sel_hi:[1,0]
	v_pk_mul_f32 v[12:13], v[68:69], v[32:33] op_sel_hi:[1,0]
	v_pk_mul_f32 v[6:7], v[6:7], v[12:13]
	v_and_b32_e32 v39, 0xffff0000, v49
	v_pk_mul_f32 v[6:7], v[8:9], v[6:7]
	v_rcp_f32_e32 v9, v11
	s_nop 0
	v_mul_f32_e32 v9, v17, v9
	v_lshlrev_b32_e32 v15, 16, v59
	v_and_b32_e32 v17, 0xffff0000, v59
	v_mul_f32_e32 v12, 0xbfb8aa3b, v15
	v_mul_f32_e32 v13, 0xbfb8aa3b, v17
	v_exp_f32_e32 v12, v12
	v_exp_f32_e32 v13, v13
	v_rcp_f32_e32 v8, v10
	s_nop 0
	v_mul_f32_e32 v8, v16, v8
	v_pk_fma_f32 v[30:31], v[124:125], v[136:137], v[30:31] op_sel_hi:[0,1,1]
	v_pk_add_f32 v[10:11], v[12:13], 1.0 op_sel_hi:[1,0]
	v_pk_mul_f32 v[12:13], v[60:61], v[32:33] op_sel_hi:[1,0]
	v_pk_mul_f32 v[0:1], v[0:1], v[12:13]
	v_pk_fma_f32 v[36:37], v[124:125], v[142:143], v[36:37] op_sel_hi:[0,1,1]
	v_pk_mul_f32 v[8:9], v[8:9], v[0:1]
	v_rcp_f32_e32 v1, v11
	s_nop 0
	v_mul_f32_e32 v1, v17, v1
	v_rcp_f32_e32 v0, v10
	s_nop 0
	v_mul_f32_e32 v0, v15, v0
	v_pk_mul_f32 v[10:11], v[46:47], v[32:33] op_sel_hi:[1,0]
	v_or_b32_e32 v16, s34, v205
	v_pk_mul_f32 v[2:3], v[2:3], v[10:11]
	v_mad_u64_u32 v[16:17], s[0:1], v16, s3, v[24:25]
	v_pk_mul_f32 v[10:11], v[0:1], v[2:3]
	v_cvt_pk_bf16_f32 v0, v4, v5
	v_cvt_pk_bf16_f32 v1, v6, v7
	v_cvt_pk_bf16_f32 v2, v8, v9
	v_cvt_pk_bf16_f32 v3, v10, v11
	global_store_dwordx4 v[34:35], v[0:3], off offset:48
	v_or_b32_e32 v8, s34, v154
	v_lshl_add_u64 v[10:11], s[34:35], 0, v[122:123]
	v_or_b32_e32 v0, s34, v152
	v_or_b32_e32 v2, s34, v153
	v_mad_u64_u32 v[0:1], s[0:1], v0, s3, v[24:25]
	v_mad_u64_u32 v[2:3], s[0:1], v2, s3, v[24:25]
	v_mad_u64_u32 v[8:9], s[0:1], v8, s3, v[24:25]
	v_mad_u64_u32 v[12:13], s[0:1], v10, s3, v[24:25]
	v_mad_u32_u24 v1, s35, v28, v1
	v_mad_u32_u24 v3, s35, v28, v3
	v_mad_u32_u24 v9, s35, v28, v9
	v_mad_u32_u24 v13, v11, s3, v13
	v_lshl_add_u64 v[0:1], v[0:1], 0, s[36:37]
	v_lshl_add_u64 v[2:3], v[2:3], 0, s[36:37]
	v_lshl_add_u64 v[8:9], v[8:9], 0, s[36:37]
	v_lshl_add_u64 v[10:11], v[12:13], 0, s[36:37]
	v_mad_u32_u24 v17, s35, v28, v17
	s_lshl_b32 s0, s31, 1
	s_mov_b32 s1, s37
	s_waitcnt lgkmcnt(0)
	s_barrier
	v_lshl_add_u64 v[0:1], v[0:1], 0, v[118:119]
	v_lshl_add_u64 v[4:5], v[2:3], 0, v[118:119]
	v_lshl_add_u64 v[8:9], v[8:9], 0, v[118:119]
	v_lshl_add_u64 v[12:13], v[10:11], 0, v[118:119]
	v_lshl_add_u64 v[16:17], v[16:17], 0, s[0:1]
	v_lshl_add_u64 v[20:21], v[22:23], 0, s[0:1]
	global_load_dwordx4 v[0:3], v[0:1], off offset:1024
	s_nop 0
	global_load_dwordx4 v[4:7], v[4:5], off offset:1024
	s_nop 0
	global_load_dwordx4 v[8:11], v[8:9], off offset:1024
	s_nop 0
	global_load_dwordx4 v[12:15], v[12:13], off offset:1024
	v_lshl_add_u64 v[16:17], v[16:17], 0, v[120:121]
	v_lshl_add_u64 v[20:21], v[20:21], 0, v[120:121]
	global_load_dwordx4 v[16:19], v[16:17], off offset:512
	s_add_u32 s4, s34, s41
	global_load_dwordx4 v[20:23], v[20:21], off offset:512
	v_or_b32_e32 v26, s4, v228
	s_addc_u32 s6, s35, 0
	v_mad_u64_u32 v[26:27], s[4:5], v26, s3, v[24:25]
	v_mad_u32_u24 v27, s6, v28, v27
	v_lshl_add_u64 v[26:27], v[26:27], 0, s[0:1]
	v_lshlrev_b32_e32 v32, 1, v155
	v_lshl_add_u64 v[26:27], v[26:27], 0, v[32:33]
	global_load_dwordx4 v[64:67], v[26:27], off
	global_load_dwordx4 v[68:71], v[26:27], off offset:32
	global_load_dwordx4 v[72:75], v[26:27], off offset:64
	global_load_dwordx4 v[76:79], v[26:27], off offset:96
	v_mad_u64_u32 v[24:25], s[0:1], v82, s3, v[24:25]
	v_mad_u32_u24 v25, v83, s3, v25
	v_lshl_add_u64 v[24:25], v[24:25], 0, s[36:37]
	v_lshl_add_u64 v[24:25], v[24:25], 0, v[114:115]
	v_lshlrev_b32_e32 v28, 16, v52
	v_lshlrev_b32_e32 v32, 16, v54
	v_and_b32_e32 v33, 0xffff0000, v54
	v_lshlrev_b32_e32 v34, 16, v55
	v_and_b32_e32 v35, 0xffff0000, v55
	v_lshlrev_b32_e32 v26, 16, v51
	v_and_b32_e32 v27, 0xffff0000, v51
	global_load_dwordx4 v[48:51], v[24:25], off offset:2096
	global_load_dwordx4 v[52:55], v[24:25], off offset:2080
	global_load_dwordx4 v[56:59], v[24:25], off offset:2064
	global_load_dwordx4 v[60:63], v[24:25], off offset:2048
	v_pk_fma_f32 v[28:29], v[124:125], v[134:135], v[28:29] op_sel_hi:[0,1,1]
	v_pk_fma_f32 v[32:33], v[124:125], v[138:139], v[32:33] op_sel_hi:[0,1,1]
	v_pk_fma_f32 v[34:35], v[124:125], v[140:141], v[34:35] op_sel_hi:[0,1,1]
	v_pk_fma_f32 v[38:39], v[124:125], v[144:145], v[38:39] op_sel_hi:[0,1,1]
	v_pk_fma_f32 v[42:43], v[124:125], v[148:149], v[26:27] op_sel_hi:[0,1,1]
	v_cvt_pk_bf16_f32 v24, v28, v29
	v_cvt_pk_bf16_f32 v25, v30, v31
	v_cvt_pk_bf16_f32 v26, v32, v33
	v_cvt_pk_bf16_f32 v27, v34, v35
	v_add_u32_e32 v28, v163, v168
	ds_write_b128 v28, v[24:27] offset:51200
	v_cvt_pk_bf16_f32 v24, v36, v37
	v_cvt_pk_bf16_f32 v25, v38, v39
	v_cvt_pk_bf16_f32 v26, v40, v41
	v_cvt_pk_bf16_f32 v27, v42, v43
	v_add_u32_e32 v29, v163, v169
	ds_write_b128 v29, v[24:27] offset:51200
	s_waitcnt vmcnt(13)
	ds_write_b128 v164, v[0:3] offset:18432
	s_waitcnt vmcnt(12)
	ds_write_b128 v165, v[4:7] offset:18432
	s_waitcnt vmcnt(11)
	ds_write_b128 v164, v[8:11] offset:22528
	s_waitcnt vmcnt(10)
	ds_write_b128 v166, v[12:15] offset:18432
	s_waitcnt vmcnt(9)
	ds_write_b128 v28, v[16:19]
	v_add_u32_e32 v0, v163, v171
	v_add_u32_e32 v36, v167, v170
	s_mov_b32 s3, 0x5040100
	s_waitcnt vmcnt(8)
	ds_write_b128 v0, v[20:23]
	s_waitcnt lgkmcnt(0)
	s_barrier
	ds_read_b128 v[0:3], v36 offset:51200
	ds_read_b128 v[16:19], v36 offset:51232
	s_waitcnt vmcnt(7) lgkmcnt(1)
	v_mfma_f32_32x32x16_bf16 v[0:15], v[0:3], v[64:67], 0
	s_waitcnt vmcnt(6) lgkmcnt(0)
	v_mfma_f32_32x32x16_bf16 v[0:15], v[16:19], v[68:71], v[0:15]
	ds_read_b128 v[16:19], v36 offset:51264
	ds_read_b128 v[20:23], v36 offset:51296
	s_waitcnt vmcnt(5) lgkmcnt(1)
	v_mfma_f32_32x32x16_bf16 v[0:15], v[16:19], v[72:75], v[0:15]
	ds_read_b128 v[16:19], v36 offset:55808
	ds_read_b128 v[32:35], v36 offset:55840
	s_waitcnt vmcnt(4) lgkmcnt(2)
	v_mfma_f32_32x32x16_bf16 v[0:15], v[20:23], v[76:79], v[0:15]
	s_waitcnt lgkmcnt(1)
	v_mfma_f32_32x32x16_bf16 v[16:31], v[16:19], v[64:67], 0
	s_nop 9
	v_mul_f32_e64 v14, v132, v14
	v_mul_f32_e64 v15, v133, v15
	v_mul_f32_e64 v12, v130, v12
	v_mul_f32_e64 v13, v131, v13
	v_mul_f32_e64 v10, v128, v10
	v_mul_f32_e64 v11, v129, v11
	v_pk_mul_f32 v[8:9], v[110:111], v[8:9]
	v_pk_mul_f32 v[6:7], v[108:109], v[6:7]
	v_pk_mul_f32 v[4:5], v[106:107], v[4:5]
	v_pk_mul_f32 v[2:3], v[104:105], v[2:3]
	s_waitcnt lgkmcnt(0)
	v_mfma_f32_32x32x16_bf16 v[16:31], v[32:35], v[68:71], v[16:31]
	ds_read_b128 v[32:35], v36 offset:55872
	ds_read_b128 v[36:39], v36 offset:55904
	v_mul_f32_e64 v0, v102, v0
	v_mul_f32_e64 v1, v103, v1
	s_waitcnt lgkmcnt(1)
	v_mfma_f32_32x32x16_bf16 v[16:31], v[32:35], v[72:75], v[16:31]
	s_waitcnt lgkmcnt(0)
	v_mfma_f32_32x32x16_bf16 v[16:31], v[36:39], v[76:79], v[16:31]
	s_nop 11
	v_pk_mul_f32 v[30:31], v[132:133], v[30:31]
	v_pk_mul_f32 v[28:29], v[130:131], v[28:29]
	v_pk_mul_f32 v[26:27], v[128:129], v[26:27]
	v_pk_mul_f32 v[24:25], v[110:111], v[24:25]
	v_pk_mul_f32 v[22:23], v[108:109], v[22:23]
	v_pk_mul_f32 v[20:21], v[106:107], v[20:21]
	v_pk_mul_f32 v[18:19], v[104:105], v[18:19]
	v_pk_mul_f32 v[16:17], v[102:103], v[16:17]
.LBB0_588:
	v_add_u32_e32 v113, v161, v159
	v_sub_u32_e32 v115, v159, v89
	v_sub_u32_e32 v124, v159, v88
	v_sub_u32_e32 v138, v159, v91
	v_sub_u32_e32 v139, v159, v90
	v_sub_u32_e32 v140, v159, v93
	v_sub_u32_e32 v141, v159, v92
	v_sub_u32_e32 v142, v159, v95
	v_sub_u32_e32 v143, v159, v94
	v_cvt_f32_u32_e32 v39, v113
	v_cvt_f32_u32_e32 v40, v124
	v_cvt_f32_u32_e32 v41, v115
	v_cvt_f32_u32_e32 v42, v139
	v_cvt_f32_u32_e32 v43, v138
	v_cvt_f32_u32_e32 v44, v141
	v_cvt_f32_u32_e32 v45, v140
	v_cvt_f32_u32_e32 v46, v143
	v_cvt_f32_u32_e32 v47, v142
	ds_read_b128 v[32:35], v162
	ds_read_b128 v[84:87], v162 offset:32
	ds_read_b128 v[102:105], v162 offset:64
	ds_read_b128 v[106:109], v162 offset:96
	v_add_u32_e32 v36, 0xffffdc00, v160
	v_add_u32_e32 v37, 0xfffffc00, v160
	v_add_u32_e32 v38, 0xffffe000, v160
	ds_read_b64_tr_b16 v[120:121], v36
	ds_read_b64_tr_b16 v[122:123], v36 offset:512
	ds_read_b64_tr_b16 v[116:117], v37
	ds_read_b64_tr_b16 v[118:119], v37 offset:512
	s_waitcnt lgkmcnt(0)
	ds_read_b64_tr_b16 v[130:131], v38
	ds_read_b64_tr_b16 v[132:133], v38 offset:512
	ds_read_b64_tr_b16 v[126:127], v160
	ds_read_b64_tr_b16 v[128:129], v160 offset:512
	s_waitcnt lgkmcnt(0)
	v_mul_f32_e32 v154, v151, v39
	v_mul_f32_e32 v155, v151, v40
	v_mul_f32_e32 v163, v151, v41
	v_mul_f32_e32 v164, v151, v42
	v_mul_f32_e32 v165, v151, v43
	v_mul_f32_e32 v166, v151, v44
	v_mul_f32_e32 v167, v151, v45
	v_mul_f32_e32 v168, v151, v46
	v_mul_f32_e32 v169, v151, v47
	s_waitcnt lgkmcnt(3)
	v_mfma_f32_32x32x16_bf16 v[32:47], v[32:35], v[64:67], 0
	v_add_u32_e32 v152, -1, v113
	v_sub_u32_e32 v144, v159, v97
	v_sub_u32_e32 v145, v159, v96
	v_sub_u32_e32 v146, v159, v99
	v_sub_u32_e32 v147, v159, v98
	v_sub_u32_e32 v148, v159, v101
	v_sub_u32_e32 v149, v159, v100
	s_waitcnt lgkmcnt(2)
	v_mfma_f32_32x32x16_bf16 v[32:47], v[84:87], v[68:71], v[32:47]
	v_cvt_f32_u32_e32 v153, v152
	v_cvt_f32_u32_e32 v110, v145
	v_cvt_f32_u32_e32 v111, v144
	v_cvt_f32_u32_e32 v134, v147
	v_cvt_f32_u32_e32 v135, v146
	v_cvt_f32_u32_e32 v136, v149
	v_cvt_f32_u32_e32 v137, v148
	s_waitcnt lgkmcnt(1)
	v_mfma_f32_32x32x16_bf16 v[32:47], v[102:105], v[72:75], v[32:47]
	v_mul_f32_e32 v153, v151, v153
	v_mul_f32_e32 v170, v151, v110
	v_mul_f32_e32 v171, v151, v111
	v_mul_f32_e32 v173, v151, v134
	v_mul_f32_e32 v174, v151, v135
	v_mul_f32_e32 v136, v151, v136
	v_mul_f32_e32 v137, v151, v137
	s_waitcnt lgkmcnt(0)
	v_mfma_f32_32x32x16_bf16 v[32:47], v[106:109], v[76:79], v[32:47]
	v_exp_f32_e32 v154, v154
	v_exp_f32_e32 v110, v155
	v_exp_f32_e32 v111, v163
	v_exp_f32_e32 v84, v164
	v_exp_f32_e32 v85, v165
	v_exp_f32_e32 v86, v166
	v_exp_f32_e32 v87, v167
	v_exp_f32_e32 v153, v153
	v_exp_f32_e32 v134, v168
	v_exp_f32_e32 v135, v169
	v_exp_f32_e32 v102, v170
	v_exp_f32_e32 v103, v171
	v_exp_f32_e32 v104, v173
	v_exp_f32_e32 v105, v174
	v_exp_f32_e32 v136, v136
	v_exp_f32_e32 v137, v137
	v_mul_f32_e32 v106, v154, v32
	v_mul_f32_e32 v107, v153, v33
	v_cmp_lt_i32_e32 vcc, -1, v152
	v_pk_mul_f32 v[32:33], v[110:111], v[34:35]
	v_pk_mul_f32 v[34:35], v[84:85], v[36:37]
	v_pk_mul_f32 v[36:37], v[86:87], v[38:39]
	v_pk_mul_f32 v[38:39], v[134:135], v[40:41]
	v_pk_mul_f32 v[40:41], v[102:103], v[42:43]
	v_pk_mul_f32 v[42:43], v[104:105], v[44:45]
	v_pk_mul_f32 v[44:45], v[136:137], v[46:47]
	v_cmp_lt_i32_e64 s[0:1], -1, v113
	v_cndmask_b32_e32 v47, 0, v107, vcc
	v_cvt_pk_bf16_f32 v33, v32, v33
	v_cmp_lt_i32_e32 vcc, -1, v124
	v_cvt_pk_bf16_f32 v34, v34, v35
	v_cvt_pk_bf16_f32 v35, v36, v37
	v_cndmask_b32_e64 v46, 0, v106, s[0:1]
	v_cmp_lt_i32_e64 s[0:1], -1, v139
	v_cmp_lt_i32_e64 s[4:5], -1, v141
	v_cvt_pk_bf16_f32 v36, v38, v39
	v_cvt_pk_bf16_f32 v37, v40, v41
	v_cvt_pk_bf16_f32 v39, v44, v45
	v_lshrrev_b32_e32 v40, 16, v34
	v_cmp_lt_i32_e64 s[14:15], -1, v138
	v_lshrrev_b32_e32 v41, 16, v35
	v_cmp_lt_i32_e64 s[16:17], -1, v140
	v_cndmask_b32_e32 v45, 0, v33, vcc
	v_lshrrev_b32_e32 v33, 16, v33
	v_cmp_lt_i32_e32 vcc, -1, v115
	v_cndmask_b32_e64 v34, 0, v34, s[0:1]
	v_cndmask_b32_e64 v35, 0, v35, s[4:5]
	v_cndmask_b32_e32 v33, 0, v33, vcc
	v_cndmask_b32_e64 v40, 0, v40, s[14:15]
	v_cndmask_b32_e64 v41, 0, v41, s[16:17]
	v_cvt_pk_bf16_f32 v32, v46, v47
	v_perm_b32 v33, v33, v45, s3
	v_perm_b32 v34, v40, v34, s3
	v_perm_b32 v35, v41, v35, s3
	v_cmp_lt_i32_e64 s[6:7], -1, v143
	v_cvt_pk_bf16_f32 v38, v42, v43
	v_mfma_f32_32x32x16_bf16 v[0:15], v[120:123], v[32:35], v[0:15]
	v_cmp_lt_i32_e64 s[8:9], -1, v145
	v_cmp_lt_i32_e64 s[10:11], -1, v147
	v_cmp_lt_i32_e64 s[12:13], -1, v149
	v_lshrrev_b32_e32 v42, 16, v37
	v_cmp_lt_i32_e64 s[18:19], -1, v144
	v_lshrrev_b32_e32 v43, 16, v38
	v_cmp_lt_i32_e64 s[20:21], -1, v146
	v_mfma_f32_32x32x16_bf16 v[16:31], v[116:119], v[32:35], v[16:31]
	v_lshrrev_b32_e32 v44, 16, v39
	v_cmp_lt_i32_e64 s[22:23], -1, v148
	v_cndmask_b32_e64 v40, 0, v36, s[6:7]
	v_lshrrev_b32_e32 v36, 16, v36
	v_cmp_lt_i32_e32 vcc, -1, v142
	v_cndmask_b32_e64 v37, 0, v37, s[8:9]
	v_cndmask_b32_e64 v38, 0, v38, s[10:11]
	v_cndmask_b32_e64 v39, 0, v39, s[12:13]
	v_cndmask_b32_e32 v36, 0, v36, vcc
	v_cndmask_b32_e64 v33, 0, v42, s[18:19]
	v_cndmask_b32_e64 v34, 0, v43, s[20:21]
	v_cndmask_b32_e64 v35, 0, v44, s[22:23]
	v_perm_b32 v32, v36, v40, s3
	v_perm_b32 v33, v33, v37, s3
	v_perm_b32 v34, v34, v38, s3
	v_perm_b32 v35, v35, v39, s3
	s_add_i32 s2, s2, -1
	v_subrev_u32_e32 v159, 32, v159
	v_mfma_f32_32x32x16_bf16 v[0:15], v[130:133], v[32:35], v[0:15]
	v_add_u32_e32 v162, 0x1200, v162
	s_cmp_lg_u32 s2, 0
	v_add_u32_e32 v160, 0x800, v160
	v_mfma_f32_32x32x16_bf16 v[16:31], v[126:129], v[32:35], v[16:31]
	s_cbranch_scc1 .LBB0_588
	v_lshlrev_b64 v[32:33], 12, v[82:83]
	v_readlane_b32 s4, v254, 0
	v_lshlrev_b32_e32 v36, 11, v82
	v_and_b32_e32 v32, 0xfff00000, v32
	v_readlane_b32 s6, v254, 2
	v_readlane_b32 s7, v254, 3
	s_waitcnt vmcnt(0)
	v_lshlrev_b32_e32 v40, 16, v62
	v_and_b32_e32 v38, 0xffff0000, v62
	v_lshl_add_u64 v[34:35], s[6:7], 0, v[32:33]
	v_and_b32_e32 v32, 0x7f800, v36
	v_mul_f32_e32 v36, 0xbfb8aa3b, v40
	v_mul_f32_e32 v37, 0xbfb8aa3b, v38
	v_exp_f32_e32 v36, v36
	v_exp_f32_e32 v37, v37
	v_mov_b32_e32 v33, 0
	v_lshl_add_u64 v[34:35], v[34:35], 0, v[32:33]
	v_lshlrev_b32_e32 v45, 16, v61
	v_pk_add_f32 v[36:37], v[36:37], 1.0 op_sel_hi:[1,0]
	v_and_b32_e32 v46, 0xffff0000, v61
	v_lshlrev_b32_e32 v66, 16, v63
	v_and_b32_e32 v44, 0xffff0000, v63
	v_lshlrev_b32_e32 v71, 16, v58
	v_rcp_f32_e32 v32, v37
	s_nop 0
	v_mul_f32_e32 v37, v38, v32
	v_mul_f32_e32 v38, 0xbfb8aa3b, v45
	v_mul_f32_e32 v39, 0xbfb8aa3b, v46
	v_exp_f32_e32 v38, v38
	v_exp_f32_e32 v39, v39
	s_nop 0
	v_pk_add_f32 v[38:39], v[38:39], 1.0 op_sel_hi:[1,0]
	v_rcp_f32_e32 v32, v36
	s_nop 0
	v_mul_f32_e32 v36, v40, v32
	v_and_b32_e32 v58, 0xffff0000, v58
	v_rcp_f32_e32 v32, v39
	s_nop 0
	v_mul_f32_e32 v39, v46, v32
	v_lshlrev_b32_e32 v78, 16, v59
	v_lshlrev_b32_e32 v42, 16, v60
	v_and_b32_e32 v43, 0xffff0000, v60
	v_mul_f32_e32 v40, 0xbfb8aa3b, v42
	v_mul_f32_e32 v41, 0xbfb8aa3b, v43
	v_exp_f32_e32 v40, v40
	v_exp_f32_e32 v41, v41
	v_rcp_f32_e32 v32, v38
	s_nop 0
	v_mul_f32_e32 v38, v45, v32
	v_and_b32_e32 v76, 0xffff0000, v59
	v_lshlrev_b32_e32 v77, 16, v57
	v_pk_add_f32 v[40:41], v[40:41], 1.0 op_sel_hi:[1,0]
	v_and_b32_e32 v57, 0xffff0000, v57
	v_div_scale_f32 v67, s[0:1], v41, v41, v43
	v_rcp_f32_e32 v68, v67
	s_waitcnt lgkmcnt(0)
	s_barrier
	v_rcp_f32_e32 v45, v41
	s_nop 0
	v_mul_f32_e32 v41, v43, v45
	ds_write2_b32 v172, v0, v1 offset1:1
	ds_write2_b32 v172, v2, v3 offset0:2 offset1:3
	ds_write2_b32 v172, v4, v5 offset0:8 offset1:9
	ds_write2_b32 v172, v6, v7 offset0:10 offset1:11
	ds_write2_b32 v172, v8, v9 offset0:16 offset1:17
	ds_write2_b32 v172, v10, v11 offset0:18 offset1:19
	ds_write2_b32 v172, v12, v13 offset0:24 offset1:25
	ds_write2_b32 v172, v14, v15 offset0:26 offset1:27
	ds_write2_b32 v172, v16, v17 offset0:32 offset1:33
	ds_write2_b32 v172, v18, v19 offset0:34 offset1:35
	ds_write2_b32 v172, v20, v21 offset0:40 offset1:41
	ds_write2_b32 v172, v22, v23 offset0:42 offset1:43
	ds_write2_b32 v172, v24, v25 offset0:48 offset1:49
	ds_write2_b32 v172, v26, v27 offset0:50 offset1:51
	ds_write2_b32 v172, v28, v29 offset0:56 offset1:57
	ds_write2_b32 v172, v30, v31 offset0:58 offset1:59
	v_rcp_f32_e32 v43, v40
	s_nop 0
	v_mul_f32_e32 v40, v42, v43
	v_mul_f32_e32 v42, 0xbfb8aa3b, v66
	v_mul_f32_e32 v43, 0xbfb8aa3b, v44
	v_exp_f32_e32 v42, v42
	v_exp_f32_e32 v43, v43
	s_waitcnt lgkmcnt(0)
	s_barrier
	v_pk_add_f32 v[42:43], v[42:43], 1.0 op_sel_hi:[1,0]
	v_lshlrev_b32_e32 v79, 16, v56
	global_load_dwordx4 v[16:19], v[80:81], off offset:48
	global_load_dwordx4 v[20:23], v[80:81], off offset:32
	global_load_dwordx4 v[24:27], v[80:81], off offset:16
	global_load_dwordx4 v[28:31], v[80:81], off
	global_load_dwordx4 v[0:3], v[80:81], off offset:112
	global_load_dwordx4 v[4:7], v[80:81], off offset:96
	global_load_dwordx4 v[8:11], v[80:81], off offset:80
	global_load_dwordx4 v[12:15], v[80:81], off offset:64
	v_and_b32_e32 v80, 0xffff0000, v56
	v_mul_f32_e32 v56, 0xbfb8aa3b, v79
	v_rcp_f32_e32 v45, v43
	s_nop 0
	v_mul_f32_e32 v43, v44, v45
	v_mul_f32_e32 v44, 0xbfb8aa3b, v71
	v_mul_f32_e32 v45, 0xbfb8aa3b, v58
	v_exp_f32_e32 v44, v44
	v_exp_f32_e32 v45, v45
	v_rcp_f32_e32 v67, v42
	s_nop 0
	v_mul_f32_e32 v42, v66, v67
	v_pk_add_f32 v[44:45], v[44:45], 1.0 op_sel_hi:[1,0]
	v_lshlrev_b32_e32 v83, 16, v54
	v_and_b32_e32 v54, 0xffff0000, v54
	v_lshlrev_b32_e32 v113, 16, v55
	v_and_b32_e32 v124, 0xffff0000, v55
	v_rcp_f32_e32 v59, v45
	s_nop 0
	v_mul_f32_e32 v45, v58, v59
	v_mul_f32_e32 v59, 0xbfb8aa3b, v57
	v_mul_f32_e32 v58, 0xbfb8aa3b, v77
	v_exp_f32_e32 v58, v58
	v_exp_f32_e32 v59, v59
	s_nop 0
	v_pk_add_f32 v[58:59], v[58:59], 1.0 op_sel_hi:[1,0]
	v_rcp_f32_e32 v66, v44
	s_nop 0
	v_mul_f32_e32 v44, v71, v66
	v_lshlrev_b32_e32 v88, 16, v53
	v_rcp_f32_e32 v66, v59
	s_nop 0
	v_mul_f32_e32 v57, v57, v66
	v_and_b32_e32 v53, 0xffff0000, v53
	v_exp_f32_e32 v66, v56
	v_mul_f32_e32 v56, 0xbfb8aa3b, v80
	v_exp_f32_e32 v67, v56
	v_rcp_f32_e32 v56, v58
	s_nop 0
	v_mul_f32_e32 v56, v77, v56
	v_lshlrev_b32_e32 v89, 16, v52
	ds_read2_b32 v[46:47], v158 offset0:6 offset1:7
	ds_read2_b32 v[60:61], v158 offset0:4 offset1:5
	ds_read2_b32 v[62:63], v158 offset0:2 offset1:3
	ds_read2_b32 v[64:65], v158 offset1:1
	v_pk_add_f32 v[66:67], v[66:67], 1.0 op_sel_hi:[1,0]
	ds_read2_b32 v[68:69], v158 offset0:14 offset1:15
	ds_read2_b32 v[70:71], v158 offset0:12 offset1:13
	ds_read2_b32 v[72:73], v158 offset0:10 offset1:11
	ds_read2_b32 v[74:75], v158 offset0:8 offset1:9
	s_waitcnt lgkmcnt(4)
	v_add_f32_e32 v32, 0, v64
	v_add_f32_e32 v32, v32, v65
	v_add_f32_e32 v32, v32, v62
	v_rcp_f32_e32 v59, v67
	s_nop 0
	v_mul_f32_e32 v59, v80, v59
	v_add_f32_e32 v32, v32, v63
	v_rcp_f32_e32 v58, v66
	s_nop 0
	v_mul_f32_e32 v58, v79, v58
	v_mul_f32_e32 v66, 0xbfb8aa3b, v78
	v_mul_f32_e32 v67, 0xbfb8aa3b, v76
	v_exp_f32_e32 v66, v66
	v_exp_f32_e32 v67, v67
	v_add_f32_e32 v32, v32, v60
	v_add_f32_e32 v32, v32, v61
	v_add_f32_e32 v32, v32, v46
	v_pk_add_f32 v[66:67], v[66:67], 1.0 op_sel_hi:[1,0]
	v_add_f32_e32 v32, v32, v47
	s_waitcnt lgkmcnt(0)
	v_add_f32_e32 v32, v32, v74
	v_add_f32_e32 v32, v32, v75
	v_add_f32_e32 v32, v32, v72
	v_rcp_f32_e32 v77, v67
	s_nop 0
	v_mul_f32_e32 v67, v76, v77
	v_mul_f32_e32 v76, 0xbfb8aa3b, v83
	v_mul_f32_e32 v77, 0xbfb8aa3b, v54
	v_exp_f32_e32 v76, v76
	v_exp_f32_e32 v77, v77
	v_rcp_f32_e32 v79, v66
	s_nop 0
	v_mul_f32_e32 v66, v78, v79
	v_pk_add_f32 v[76:77], v[76:77], 1.0 op_sel_hi:[1,0]
	v_add_f32_e32 v32, v32, v73
	v_add_f32_e32 v32, v32, v70
	v_add_f32_e32 v32, v32, v71
	v_add_f32_e32 v32, v32, v68
	v_mul_f32_e32 v78, 0xbfb8aa3b, v88
	v_mul_f32_e32 v79, 0xbfb8aa3b, v53
	v_rcp_f32_e32 v55, v77
	s_nop 0
	v_mul_f32_e32 v55, v54, v55
	v_exp_f32_e32 v78, v78
	v_exp_f32_e32 v79, v79
	s_nop 0
	v_pk_add_f32 v[78:79], v[78:79], 1.0 op_sel_hi:[1,0]
	v_rcp_f32_e32 v54, v76
	s_nop 0
	v_mul_f32_e32 v54, v83, v54
	v_add_f32_e32 v32, v32, v69
	v_rcp_f32_e32 v77, v79
	s_nop 0
	v_mul_f32_e32 v77, v53, v77
	s_mov_b32 s37, 0
	v_and_b32_e32 v79, 0xffff0000, v52
	v_mul_f32_e32 v52, 0xbfb8aa3b, v89
	v_mul_f32_e32 v53, 0xbfb8aa3b, v79
	v_exp_f32_e32 v52, v52
	v_exp_f32_e32 v53, v53
	v_rcp_f32_e32 v76, v78
	s_nop 0
	v_mul_f32_e32 v76, v88, v76
	ds_read2_b32 v[80:81], v158 offset0:22 offset1:23
	ds_read2_b32 v[82:83], v158 offset0:20 offset1:21
	ds_read2_b32 v[84:85], v158 offset0:18 offset1:19
	ds_read2_b32 v[86:87], v158 offset0:16 offset1:17
	v_lshl_add_u64 v[34:35], v[34:35], 0, s[36:37]
	v_pk_add_f32 v[52:53], v[52:53], 1.0 op_sel_hi:[1,0]
	v_mov_b32_e32 v115, v33
	s_waitcnt lgkmcnt(0)
	v_add_f32_e32 v32, v32, v86
	v_add_f32_e32 v32, v32, v87
	v_add_f32_e32 v32, v32, v84
	v_rcp_f32_e32 v78, v53
	s_nop 0
	v_mul_f32_e32 v79, v79, v78
	v_add_f32_e32 v32, v32, v85
	v_rcp_f32_e32 v78, v52
	s_nop 0
	v_mul_f32_e32 v78, v89, v78
	v_mul_f32_e32 v52, 0xbfb8aa3b, v113
	v_mul_f32_e32 v53, 0xbfb8aa3b, v124
	v_exp_f32_e32 v52, v52
	v_exp_f32_e32 v53, v53
	v_add_f32_e32 v32, v32, v82
	v_add_f32_e32 v32, v32, v83
	v_add_f32_e32 v32, v32, v80
	v_pk_add_f32 v[88:89], v[52:53], 1.0 op_sel_hi:[1,0]
	ds_read2_b32 v[90:91], v158 offset0:30 offset1:31
	ds_read2_b32 v[52:53], v158 offset0:28 offset1:29
	ds_read2_b32 v[92:93], v158 offset0:26 offset1:27
	ds_read2_b32 v[94:95], v158 offset0:24 offset1:25
	v_add_f32_e32 v32, v32, v81
	s_waitcnt lgkmcnt(0)
	v_add_f32_e32 v32, v32, v94
	v_add_f32_e32 v32, v32, v95
	v_add_f32_e32 v32, v32, v92
	v_add_f32_e32 v32, v32, v93
	v_add_f32_e32 v32, v32, v52
	v_add_f32_e32 v32, v32, v53
	v_add_f32_e32 v32, v32, v90
	v_add_f32_e32 v32, v32, v91
	ds_bpermute_b32 v97, v157, v32
	s_waitcnt lgkmcnt(0)
	v_add_f32_e32 v32, v32, v97
	ds_bpermute_b32 v97, v156, v32
	v_lshl_add_u64 v[34:35], v[34:35], 0, v[114:115]
	s_waitcnt lgkmcnt(0)
	v_add_f32_e32 v32, v32, v97
	v_mul_f32_e32 v32, 0x3c000000, v32
	v_pk_add_f32 v[64:65], v[64:65], v[32:33] op_sel_hi:[1,0] neg_lo:[0,1] neg_hi:[0,1]
	v_pk_add_f32 v[62:63], v[62:63], v[32:33] op_sel_hi:[1,0] neg_lo:[0,1] neg_hi:[0,1]
	v_pk_mul_f32 v[96:97], v[64:65], v[64:65]
	v_pk_mul_f32 v[98:99], v[62:63], v[62:63]
	v_pk_add_f32 v[100:101], v[60:61], v[32:33] op_sel_hi:[1,0] neg_lo:[0,1] neg_hi:[0,1]
	v_pk_add_f32 v[104:105], v[46:47], v[32:33] op_sel_hi:[1,0] neg_lo:[0,1] neg_hi:[0,1]
	v_pk_add_f32 v[74:75], v[74:75], v[32:33] op_sel_hi:[1,0] neg_lo:[0,1] neg_hi:[0,1]
	v_pk_add_f32 v[72:73], v[72:73], v[32:33] op_sel_hi:[1,0] neg_lo:[0,1] neg_hi:[0,1]
	v_pk_add_f32 v[70:71], v[70:71], v[32:33] op_sel_hi:[1,0] neg_lo:[0,1] neg_hi:[0,1]
	v_pk_add_f32 v[68:69], v[68:69], v[32:33] op_sel_hi:[1,0] neg_lo:[0,1] neg_hi:[0,1]
	v_pk_add_f32 v[86:87], v[86:87], v[32:33] op_sel_hi:[1,0] neg_lo:[0,1] neg_hi:[0,1]
	v_pk_add_f32 v[84:85], v[84:85], v[32:33] op_sel_hi:[1,0] neg_lo:[0,1] neg_hi:[0,1]
	v_pk_add_f32 v[82:83], v[82:83], v[32:33] op_sel_hi:[1,0] neg_lo:[0,1] neg_hi:[0,1]
	v_pk_add_f32 v[80:81], v[80:81], v[32:33] op_sel_hi:[1,0] neg_lo:[0,1] neg_hi:[0,1]
	v_pk_add_f32 v[94:95], v[94:95], v[32:33] op_sel_hi:[1,0] neg_lo:[0,1] neg_hi:[0,1]
	v_pk_add_f32 v[60:61], v[92:93], v[32:33] op_sel_hi:[1,0] neg_lo:[0,1] neg_hi:[0,1]
	v_pk_add_f32 v[52:53], v[52:53], v[32:33] op_sel_hi:[1,0] neg_lo:[0,1] neg_hi:[0,1]
	v_pk_add_f32 v[46:47], v[90:91], v[32:33] op_sel_hi:[1,0] neg_lo:[0,1] neg_hi:[0,1]
	v_add_f32_e32 v32, v96, v97
	v_add_f32_e32 v32, v98, v32
	v_pk_mul_f32 v[102:103], v[100:101], v[100:101]
	v_add_f32_e32 v32, v99, v32
	v_add_f32_e32 v32, v102, v32
	v_pk_mul_f32 v[106:107], v[104:105], v[104:105]
	v_add_f32_e32 v32, v103, v32
	v_add_f32_e32 v32, v106, v32
	v_pk_mul_f32 v[108:109], v[74:75], v[74:75]
	v_add_f32_e32 v32, v107, v32
	v_add_f32_e32 v32, v108, v32
	v_pk_mul_f32 v[110:111], v[72:73], v[72:73]
	v_add_f32_e32 v32, v109, v32
	v_add_f32_e32 v32, v110, v32
	v_pk_mul_f32 v[114:115], v[70:71], v[70:71]
	v_add_f32_e32 v32, v111, v32
	v_add_f32_e32 v32, v114, v32
	v_pk_mul_f32 v[116:117], v[68:69], v[68:69]
	v_add_f32_e32 v32, v115, v32
	v_add_f32_e32 v32, v116, v32
	v_pk_mul_f32 v[118:119], v[86:87], v[86:87]
	v_add_f32_e32 v32, v117, v32
	v_add_f32_e32 v32, v118, v32
	v_pk_mul_f32 v[120:121], v[84:85], v[84:85]
	v_add_f32_e32 v32, v119, v32
	v_add_f32_e32 v32, v120, v32
	v_pk_mul_f32 v[122:123], v[82:83], v[82:83]
	v_add_f32_e32 v32, v121, v32
	v_add_f32_e32 v32, v122, v32
	v_pk_mul_f32 v[126:127], v[80:81], v[80:81]
	v_add_f32_e32 v32, v123, v32
	v_add_f32_e32 v32, v126, v32
	v_pk_mul_f32 v[128:129], v[94:95], v[94:95]
	v_add_f32_e32 v32, v127, v32
	v_add_f32_e32 v32, v128, v32
	v_pk_mul_f32 v[92:93], v[60:61], v[60:61]
	v_add_f32_e32 v32, v129, v32
	v_add_f32_e32 v32, v92, v32
	v_pk_mul_f32 v[130:131], v[52:53], v[52:53]
	v_add_f32_e32 v32, v93, v32
	v_add_f32_e32 v32, v130, v32
	v_pk_mul_f32 v[90:91], v[46:47], v[46:47]
	v_add_f32_e32 v32, v131, v32
	v_add_f32_e32 v32, v90, v32
	v_add_f32_e32 v32, v91, v32
	ds_bpermute_b32 v90, v157, v32
	s_mov_b32 s0, 0xf800000
	v_rcp_f32_e32 v91, v89
	s_nop 0
	v_mul_f32_e32 v89, v124, v91
	s_waitcnt lgkmcnt(0)
	v_add_f32_e32 v32, v32, v90
	ds_bpermute_b32 v90, v156, v32
	s_waitcnt lgkmcnt(0)
	v_add_f32_e32 v32, v32, v90
	v_mov_b32_e32 v90, 0x358637bd
	v_fmac_f32_e32 v90, 0x3c000000, v32
	v_mul_f32_e32 v32, 0x4f800000, v90
	v_cmp_gt_f32_e64 s[0:1], s0, v90
	s_nop 1
	v_cndmask_b32_e64 v32, v90, v32, s[0:1]
	v_sqrt_f32_e32 v90, v32
	v_readlane_b32 s5, v254, 1
	v_add_u32_e32 v93, -1, v90
	v_fma_f32 v96, -v93, v90, v32
	v_cmp_ge_f32_e64 s[4:5], 0, v96
	v_add_u32_e32 v96, 1, v90
	s_nop 1
	v_cndmask_b32_e64 v93, v90, v93, s[4:5]
	v_fma_f32 v90, -v96, v90, v32
	v_cmp_lt_f32_e64 s[4:5], 0, v90
	v_rcp_f32_e32 v91, v88
	s_nop 0
	v_mul_f32_e32 v88, v113, v91
	s_movk_i32 s2, 0x37ff
	v_cndmask_b32_e64 v90, v93, v96, s[4:5]
	v_mul_f32_e32 v93, 0x37800000, v90
	v_cndmask_b32_e64 v90, v90, v93, s[0:1]
	v_mov_b32_e32 v93, 0x260
	v_cmp_class_f32_e64 s[0:1], v32, v93
	s_nop 1
	v_cndmask_b32_e64 v32, v90, v32, s[0:1]
	v_rcp_f32_e32 v32, v32
	s_nop 0
	v_pk_mul_f32 v[64:65], v[64:65], v[32:33] op_sel_hi:[1,0]
	s_waitcnt vmcnt(4)
	v_pk_mul_f32 v[28:29], v[28:29], v[64:65]
	s_nop 0
	v_pk_mul_f32 v[28:29], v[40:41], v[28:29]
	v_pk_mul_f32 v[40:41], v[62:63], v[32:33] op_sel_hi:[1,0]
	s_nop 0
	v_pk_mul_f32 v[30:31], v[30:31], v[40:41]
	s_nop 0
	v_pk_mul_f32 v[30:31], v[38:39], v[30:31]
	v_pk_mul_f32 v[38:39], v[100:101], v[32:33] op_sel_hi:[1,0]
	s_nop 0
	v_pk_mul_f32 v[24:25], v[24:25], v[38:39]
	s_nop 0
	v_pk_mul_f32 v[36:37], v[36:37], v[24:25]
	v_pk_mul_f32 v[24:25], v[104:105], v[32:33] op_sel_hi:[1,0]
	s_nop 0
	v_pk_mul_f32 v[24:25], v[26:27], v[24:25]
	v_cvt_pk_bf16_f32 v26, v36, v37
	v_pk_mul_f32 v[38:39], v[42:43], v[24:25]
	v_cvt_pk_bf16_f32 v24, v28, v29
	v_cvt_pk_bf16_f32 v25, v30, v31
	v_cvt_pk_bf16_f32 v27, v38, v39
	global_store_dwordx4 v[34:35], v[24:27], off
	s_nop 1
	v_pk_mul_f32 v[24:25], v[74:75], v[32:33] op_sel_hi:[1,0]
	s_nop 0
	v_pk_mul_f32 v[20:21], v[20:21], v[24:25]
	v_pk_mul_f32 v[24:25], v[72:73], v[32:33] op_sel_hi:[1,0]
	v_pk_mul_f32 v[20:21], v[58:59], v[20:21]
	v_pk_mul_f32 v[22:23], v[22:23], v[24:25]
	v_pk_mul_f32 v[24:25], v[70:71], v[32:33] op_sel_hi:[1,0]
	v_pk_mul_f32 v[22:23], v[56:57], v[22:23]
	v_pk_mul_f32 v[16:17], v[16:17], v[24:25]
	s_nop 0
	v_pk_mul_f32 v[24:25], v[44:45], v[16:17]
	v_pk_mul_f32 v[16:17], v[68:69], v[32:33] op_sel_hi:[1,0]
	s_nop 0
	v_pk_mul_f32 v[16:17], v[18:19], v[16:17]
	v_cvt_pk_bf16_f32 v18, v24, v25
	v_pk_mul_f32 v[26:27], v[66:67], v[16:17]
	v_cvt_pk_bf16_f32 v16, v20, v21
	v_cvt_pk_bf16_f32 v17, v22, v23
	v_cvt_pk_bf16_f32 v19, v26, v27
	global_store_dwordx4 v[34:35], v[16:19], off offset:16
	v_lshlrev_b32_e32 v20, 16, v48
	v_and_b32_e32 v21, 0xffff0000, v48
	v_pk_mul_f32 v[16:17], v[86:87], v[32:33] op_sel_hi:[1,0]
	s_waitcnt vmcnt(2)
	v_pk_mul_f32 v[12:13], v[12:13], v[16:17]
	v_pk_mul_f32 v[16:17], v[84:85], v[32:33] op_sel_hi:[1,0]
	v_pk_mul_f32 v[12:13], v[78:79], v[12:13]
	v_pk_mul_f32 v[14:15], v[14:15], v[16:17]
	v_pk_mul_f32 v[16:17], v[82:83], v[32:33] op_sel_hi:[1,0]
	v_pk_mul_f32 v[14:15], v[76:77], v[14:15]
	v_pk_mul_f32 v[8:9], v[8:9], v[16:17]
	s_nop 0
	v_pk_mul_f32 v[16:17], v[54:55], v[8:9]
	v_pk_mul_f32 v[8:9], v[80:81], v[32:33] op_sel_hi:[1,0]
	s_nop 0
	v_pk_mul_f32 v[8:9], v[10:11], v[8:9]
	v_mul_f32_e32 v10, 0xbfb8aa3b, v20
	v_mul_f32_e32 v11, 0xbfb8aa3b, v21
	v_exp_f32_e32 v10, v10
	v_exp_f32_e32 v11, v11
	v_pk_mul_f32 v[18:19], v[88:89], v[8:9]
	v_cvt_pk_bf16_f32 v8, v12, v13
	v_cvt_pk_bf16_f32 v9, v14, v15
	v_pk_add_f32 v[12:13], v[10:11], 1.0 op_sel_hi:[1,0]
	v_cvt_pk_bf16_f32 v10, v16, v17
	v_cvt_pk_bf16_f32 v11, v18, v19
	global_store_dwordx4 v[34:35], v[8:11], off offset:32
	v_and_b32_e32 v16, 0xffff0000, v49
	s_nop 0
	v_rcp_f32_e32 v9, v13
	s_nop 0
	v_mul_f32_e32 v9, v21, v9
	v_lshlrev_b32_e32 v15, 16, v49
	v_mul_f32_e32 v10, 0xbfb8aa3b, v15
	v_mul_f32_e32 v11, 0xbfb8aa3b, v16
	v_exp_f32_e32 v10, v10
	v_exp_f32_e32 v11, v11
	v_rcp_f32_e32 v8, v12
	s_nop 0
	v_mul_f32_e32 v8, v20, v8
	v_pk_mul_f32 v[12:13], v[94:95], v[32:33] op_sel_hi:[1,0]
	v_pk_add_f32 v[10:11], v[10:11], 1.0 op_sel_hi:[1,0]
	v_pk_mul_f32 v[4:5], v[4:5], v[12:13]
	v_pk_mul_f32 v[4:5], v[8:9], v[4:5]
	v_rcp_f32_e32 v9, v11
	s_nop 0
	v_mul_f32_e32 v9, v16, v9
	v_lshlrev_b32_e32 v16, 16, v50
	v_and_b32_e32 v17, 0xffff0000, v50
	v_mul_f32_e32 v12, 0xbfb8aa3b, v16
	v_mul_f32_e32 v13, 0xbfb8aa3b, v17
	v_exp_f32_e32 v12, v12
	v_exp_f32_e32 v13, v13
	v_rcp_f32_e32 v8, v10
	s_nop 0
	v_mul_f32_e32 v8, v15, v8
	v_pk_add_f32 v[10:11], v[12:13], 1.0 op_sel_hi:[1,0]
	s_nop 0
	v_pk_mul_f32 v[12:13], v[60:61], v[32:33] op_sel_hi:[1,0]
	s_nop 0
	v_pk_mul_f32 v[6:7], v[6:7], v[12:13]
	s_nop 0
	v_pk_mul_f32 v[6:7], v[8:9], v[6:7]
	v_rcp_f32_e32 v9, v11
	s_nop 0
	v_mul_f32_e32 v9, v17, v9
	v_lshlrev_b32_e32 v15, 16, v51
	v_and_b32_e32 v17, 0xffff0000, v51
	v_mul_f32_e32 v12, 0xbfb8aa3b, v15
	v_mul_f32_e32 v13, 0xbfb8aa3b, v17
	v_exp_f32_e32 v12, v12
	v_exp_f32_e32 v13, v13
	v_rcp_f32_e32 v8, v10
	s_nop 0
	v_mul_f32_e32 v8, v16, v8
	v_pk_add_f32 v[10:11], v[12:13], 1.0 op_sel_hi:[1,0]
	s_nop 0
	v_pk_mul_f32 v[12:13], v[52:53], v[32:33] op_sel_hi:[1,0]
	s_nop 0
	v_pk_mul_f32 v[0:1], v[0:1], v[12:13]
	s_nop 0
	v_pk_mul_f32 v[8:9], v[8:9], v[0:1]
	v_rcp_f32_e32 v1, v11
	s_nop 0
	v_mul_f32_e32 v1, v17, v1
	v_rcp_f32_e32 v0, v10
	s_nop 0
	v_mul_f32_e32 v0, v15, v0
	v_pk_mul_f32 v[10:11], v[46:47], v[32:33] op_sel_hi:[1,0]
	s_mov_b64 s[0:1], 0x3300000
	v_pk_mul_f32 v[2:3], v[2:3], v[10:11]
	s_nop 0
	v_pk_mul_f32 v[10:11], v[0:1], v[2:3]
	v_cvt_pk_bf16_f32 v0, v4, v5
	v_cvt_pk_bf16_f32 v1, v6, v7
	v_cvt_pk_bf16_f32 v2, v8, v9
	v_cvt_pk_bf16_f32 v3, v10, v11
	global_store_dwordx4 v[34:35], v[0:3], off offset:48
	v_lshl_add_u32 v5, s52, 9, v226
	s_waitcnt lgkmcnt(0)
	s_barrier
	s_lshr_b32 s0, s88, 5
	s_lshl_b32 s1, s0, 3
	s_add_i32 s1, s1, s53
	s_lshl_b32 s2, s1, 8
	s_lshl_b32 s3, s52, 3
	s_add_i32 s2, s2, s3
	v_readlane_b32 s8, v254, 2
	v_readlane_b32 s9, v254, 3
	v_lshrrev_b32_e32 v22, 6, v226
	v_add_u32_e32 v23, s2, v22
	v_and_b32_e32 v32, 63, v226
	v_lshlrev_b32_e32 v32, 4, v32
	v_bfe_u32 v33, v226, 3, 3
	v_lshlrev_b32_e32 v33, 2, v33
	v_lshl_add_u32 v0, v23, 5, v33
	v_add_u32_e32 v0, 0x3300000, v0
	v_add_u32_e32 v1, 0x1000, v0
	v_add_u32_e32 v2, 0x80000, v0
	v_add_u32_e32 v3, 0x81000, v0
	v_add_u32_e32 v4, 0x100000, v0
	v_add_u32_e32 v5, 0x101000, v0
	v_lshl_add_u32 v6, v23, 10, v32
	v_add_u32_e32 v6, 0xb500000, v6
	v_add_u32_e32 v7, s3, v22
	v_lshl_add_u32 v7, v7, 11, v32
	s_lshl_b32 s2, s1, 20
	s_add_u32 s8, s8, s2
	s_addc_u32 s9, s9, 0
	global_load_dword v60, v0, s[96:97]
	global_load_dword v61, v2, s[96:97]
	global_load_dword v62, v4, s[96:97]
	global_load_dwordx4 v[48:51], v6, s[96:97]
	v_add_u32_e32 v8, 0x1000000, v6
	global_load_dwordx4 v[52:55], v8, s[96:97]
	v_add_u32_e32 v8, 0x2000000, v6
	global_load_dwordx4 v[56:59], v8, s[96:97]
	global_load_dword v76, v0, s[96:97] offset:1024
	global_load_dword v77, v2, s[96:97] offset:1024
	global_load_dword v78, v4, s[96:97] offset:1024
	v_add_u32_e32 v8, 0x8000, v6
	global_load_dwordx4 v[64:67], v8, s[96:97]
	v_add_u32_e32 v8, 0x1008000, v6
	global_load_dwordx4 v[68:71], v8, s[96:97]
	v_add_u32_e32 v8, 0x2008000, v6
	global_load_dwordx4 v[72:75], v8, s[96:97]
	global_load_dword v92, v0, s[96:97] offset:2048
	global_load_dword v93, v2, s[96:97] offset:2048
	global_load_dword v94, v4, s[96:97] offset:2048
	v_add_u32_e32 v8, 0x10000, v6
	global_load_dwordx4 v[80:83], v8, s[96:97]
	v_add_u32_e32 v8, 0x1010000, v6
	global_load_dwordx4 v[84:87], v8, s[96:97]
	v_add_u32_e32 v8, 0x2010000, v6
	global_load_dwordx4 v[88:91], v8, s[96:97]
	global_load_dword v108, v0, s[96:97] offset:3072
	global_load_dword v109, v2, s[96:97] offset:3072
	global_load_dword v110, v4, s[96:97] offset:3072
	v_add_u32_e32 v8, 0x18000, v6
	global_load_dwordx4 v[96:99], v8, s[96:97]
	v_add_u32_e32 v8, 0x1018000, v6
	global_load_dwordx4 v[100:103], v8, s[96:97]
	v_add_u32_e32 v8, 0x2018000, v6
	global_load_dwordx4 v[104:107], v8, s[96:97]
	global_load_dword v140, v1, s[96:97]
	global_load_dword v141, v3, s[96:97]
	global_load_dword v142, v5, s[96:97]
	v_add_u32_e32 v8, 0x20000, v6
	global_load_dwordx4 v[128:131], v8, s[96:97]
	v_add_u32_e32 v8, 0x1020000, v6
	global_load_dwordx4 v[132:135], v8, s[96:97]
	v_add_u32_e32 v8, 0x2020000, v6
	global_load_dwordx4 v[136:139], v8, s[96:97]
	global_load_dword v164, v1, s[96:97] offset:1024
	global_load_dword v165, v3, s[96:97] offset:1024
	global_load_dword v166, v5, s[96:97] offset:1024
	v_add_u32_e32 v8, 0x28000, v6
	global_load_dwordx4 v[152:155], v8, s[96:97]
	v_add_u32_e32 v8, 0x1028000, v6
	global_load_dwordx4 v[156:159], v8, s[96:97]
	v_add_u32_e32 v8, 0x2028000, v6
	global_load_dwordx4 v[160:163], v8, s[96:97]
	global_load_dword v218, v1, s[96:97] offset:2048
	global_load_dword v219, v3, s[96:97] offset:2048
	global_load_dword v220, v5, s[96:97] offset:2048
	v_add_u32_e32 v8, 0x30000, v6
	global_load_dwordx4 v[206:209], v8, s[96:97]
	v_add_u32_e32 v8, 0x1030000, v6
	global_load_dwordx4 v[210:213], v8, s[96:97]
	v_add_u32_e32 v8, 0x2030000, v6
	global_load_dwordx4 v[214:217], v8, s[96:97]
	global_load_dword v244, v1, s[96:97] offset:3072
	global_load_dword v245, v3, s[96:97] offset:3072
	global_load_dword v246, v5, s[96:97] offset:3072
	v_add_u32_e32 v8, 0x38000, v6
	global_load_dwordx4 v[232:235], v8, s[96:97]
	v_add_u32_e32 v8, 0x1038000, v6
	global_load_dwordx4 v[236:239], v8, s[96:97]
	v_add_u32_e32 v8, 0x2038000, v6
	global_load_dwordx4 v[240:243], v8, s[96:97]
	s_waitcnt vmcnt(42)
	v_max3_f32 v5, v60, v61, v62
	v_sub_f32_e32 v9, v60, v5
	v_sub_f32_e32 v40, v61, v5
	v_and_b32_e32 v27, 0xffff0000, v49
	v_lshlrev_b32_e32 v28, 16, v49
	v_sub_f32_e32 v5, v62, v5
	v_lshlrev_b32_e32 v24, 16, v52
	v_and_b32_e32 v11, 0xffff0000, v52
	v_lshlrev_b32_e32 v38, 16, v56
	v_and_b32_e32 v39, 0xffff0000, v56
	v_lshlrev_b32_e32 v26, 16, v53
	v_and_b32_e32 v29, 0xffff0000, v53
	v_lshlrev_b32_e32 v14, 16, v57
	v_and_b32_e32 v15, 0xffff0000, v57
	v_lshlrev_b32_e32 v18, 16, v58
	v_and_b32_e32 v19, 0xffff0000, v58
	v_mul_f32_e32 v9, 0x3fb8aa3b, v9
	v_mul_f32_e32 v20, 0x3fb8aa3b, v40
	v_and_b32_e32 v35, 0xffff0000, v51
	v_lshlrev_b32_e32 v36, 16, v51
	v_lshlrev_b32_e32 v30, 16, v54
	v_and_b32_e32 v13, 0xffff0000, v54
	v_lshlrev_b32_e32 v34, 16, v55
	v_and_b32_e32 v37, 0xffff0000, v55
	v_lshlrev_b32_e32 v16, 16, v59
	v_and_b32_e32 v17, 0xffff0000, v59
	v_mul_f32_e32 v5, 0x3fb8aa3b, v5
	v_exp_f32_e32 v21, v9
	v_exp_f32_e32 v20, v20
	v_exp_f32_e32 v5, v5
	v_and_b32_e32 v25, 0xffff0000, v48
	v_lshlrev_b32_e32 v10, 16, v48
	v_add_f32_e32 v9, v21, v20
	v_add_f32_e32 v9, v5, v9
	v_and_b32_e32 v31, 0xffff0000, v50
	v_rcp_f32_e32 v40, v9
	s_nop 0
	v_lshlrev_b32_e32 v12, 16, v50
	v_pk_mul_f32 v[20:21], v[20:21], v[40:41] op_sel_hi:[1,0]
	v_mul_f32_e32 v42, v5, v40
	v_pk_mul_f32 v[10:11], v[20:21], v[10:11] op_sel:[1,0] op_sel_hi:[0,1]
	v_pk_mul_f32 v[28:29], v[20:21], v[28:29] op_sel:[1,0] op_sel_hi:[0,1]
	v_pk_mul_f32 v[12:13], v[20:21], v[12:13] op_sel:[1,0] op_sel_hi:[0,1]
	v_pk_mul_f32 v[36:37], v[20:21], v[36:37] op_sel:[1,0] op_sel_hi:[0,1]
	v_pk_fma_f32 v[10:11], v[20:21], v[24:25], v[10:11]
	v_pk_fma_f32 v[24:25], v[20:21], v[26:27], v[28:29]
	v_pk_fma_f32 v[12:13], v[20:21], v[30:31], v[12:13]
	v_pk_fma_f32 v[20:21], v[20:21], v[34:35], v[36:37]
	v_pk_fma_f32 v[10:11], v[42:43], v[38:39], v[10:11] op_sel_hi:[0,1,1]
	v_pk_fma_f32 v[14:15], v[42:43], v[14:15], v[24:25] op_sel_hi:[0,1,1]
	v_pk_fma_f32 v[12:13], v[42:43], v[18:19], v[12:13] op_sel_hi:[0,1,1]
	v_pk_fma_f32 v[16:17], v[42:43], v[16:17], v[20:21] op_sel_hi:[0,1,1]
	v_cvt_pk_bf16_f32 v10, v10, v11
	v_cvt_pk_bf16_f32 v11, v14, v15
	v_cvt_pk_bf16_f32 v12, v12, v13
	v_cvt_pk_bf16_f32 v13, v16, v17
	global_store_dwordx4 v7, v[10:13], s[8:9] offset:1024
	s_waitcnt vmcnt(37)
	v_max3_f32 v5, v76, v77, v78
	v_sub_f32_e32 v9, v76, v5
	v_sub_f32_e32 v40, v77, v5
	v_and_b32_e32 v27, 0xffff0000, v65
	v_lshlrev_b32_e32 v28, 16, v65
	v_sub_f32_e32 v5, v78, v5
	v_lshlrev_b32_e32 v24, 16, v68
	v_and_b32_e32 v11, 0xffff0000, v68
	v_lshlrev_b32_e32 v38, 16, v72
	v_and_b32_e32 v39, 0xffff0000, v72
	v_lshlrev_b32_e32 v26, 16, v69
	v_and_b32_e32 v29, 0xffff0000, v69
	v_lshlrev_b32_e32 v14, 16, v73
	v_and_b32_e32 v15, 0xffff0000, v73
	v_lshlrev_b32_e32 v18, 16, v74
	v_and_b32_e32 v19, 0xffff0000, v74
	v_mul_f32_e32 v9, 0x3fb8aa3b, v9
	v_mul_f32_e32 v20, 0x3fb8aa3b, v40
	v_and_b32_e32 v35, 0xffff0000, v67
	v_lshlrev_b32_e32 v36, 16, v67
	v_lshlrev_b32_e32 v30, 16, v70
	v_and_b32_e32 v13, 0xffff0000, v70
	v_lshlrev_b32_e32 v34, 16, v71
	v_and_b32_e32 v37, 0xffff0000, v71
	v_lshlrev_b32_e32 v16, 16, v75
	v_and_b32_e32 v17, 0xffff0000, v75
	v_mul_f32_e32 v5, 0x3fb8aa3b, v5
	v_exp_f32_e32 v21, v9
	v_exp_f32_e32 v20, v20
	v_exp_f32_e32 v5, v5
	v_and_b32_e32 v25, 0xffff0000, v64
	v_lshlrev_b32_e32 v10, 16, v64
	v_add_f32_e32 v9, v21, v20
	v_add_f32_e32 v9, v5, v9
	v_and_b32_e32 v31, 0xffff0000, v66
	v_rcp_f32_e32 v40, v9
	s_nop 0
	v_lshlrev_b32_e32 v12, 16, v66
	v_pk_mul_f32 v[20:21], v[20:21], v[40:41] op_sel_hi:[1,0]
	v_mul_f32_e32 v42, v5, v40
	v_pk_mul_f32 v[10:11], v[20:21], v[10:11] op_sel:[1,0] op_sel_hi:[0,1]
	v_pk_mul_f32 v[28:29], v[20:21], v[28:29] op_sel:[1,0] op_sel_hi:[0,1]
	v_pk_mul_f32 v[12:13], v[20:21], v[12:13] op_sel:[1,0] op_sel_hi:[0,1]
	v_pk_mul_f32 v[36:37], v[20:21], v[36:37] op_sel:[1,0] op_sel_hi:[0,1]
	v_pk_fma_f32 v[10:11], v[20:21], v[24:25], v[10:11]
	v_pk_fma_f32 v[24:25], v[20:21], v[26:27], v[28:29]
	v_pk_fma_f32 v[12:13], v[20:21], v[30:31], v[12:13]
	v_pk_fma_f32 v[20:21], v[20:21], v[34:35], v[36:37]
	v_pk_fma_f32 v[10:11], v[42:43], v[38:39], v[10:11] op_sel_hi:[0,1,1]
	v_pk_fma_f32 v[14:15], v[42:43], v[14:15], v[24:25] op_sel_hi:[0,1,1]
	v_pk_fma_f32 v[12:13], v[42:43], v[18:19], v[12:13] op_sel_hi:[0,1,1]
	v_pk_fma_f32 v[16:17], v[42:43], v[16:17], v[20:21] op_sel_hi:[0,1,1]
	v_cvt_pk_bf16_f32 v10, v10, v11
	v_cvt_pk_bf16_f32 v11, v14, v15
	v_cvt_pk_bf16_f32 v12, v12, v13
	v_cvt_pk_bf16_f32 v13, v16, v17
	v_add_u32_e32 v8, 0x10000, v7
	global_store_dwordx4 v8, v[10:13], s[8:9] offset:1024
	s_waitcnt vmcnt(32)
	v_max3_f32 v5, v92, v93, v94
	v_sub_f32_e32 v9, v92, v5
	v_sub_f32_e32 v40, v93, v5
	v_and_b32_e32 v27, 0xffff0000, v81
	v_lshlrev_b32_e32 v28, 16, v81
	v_sub_f32_e32 v5, v94, v5
	v_lshlrev_b32_e32 v24, 16, v84
	v_and_b32_e32 v11, 0xffff0000, v84
	v_lshlrev_b32_e32 v38, 16, v88
	v_and_b32_e32 v39, 0xffff0000, v88
	v_lshlrev_b32_e32 v26, 16, v85
	v_and_b32_e32 v29, 0xffff0000, v85
	v_lshlrev_b32_e32 v14, 16, v89
	v_and_b32_e32 v15, 0xffff0000, v89
	v_lshlrev_b32_e32 v18, 16, v90
	v_and_b32_e32 v19, 0xffff0000, v90
	v_mul_f32_e32 v9, 0x3fb8aa3b, v9
	v_mul_f32_e32 v20, 0x3fb8aa3b, v40
	v_and_b32_e32 v35, 0xffff0000, v83
	v_lshlrev_b32_e32 v36, 16, v83
	v_lshlrev_b32_e32 v30, 16, v86
	v_and_b32_e32 v13, 0xffff0000, v86
	v_lshlrev_b32_e32 v34, 16, v87
	v_and_b32_e32 v37, 0xffff0000, v87
	v_lshlrev_b32_e32 v16, 16, v91
	v_and_b32_e32 v17, 0xffff0000, v91
	v_mul_f32_e32 v5, 0x3fb8aa3b, v5
	v_exp_f32_e32 v21, v9
	v_exp_f32_e32 v20, v20
	v_exp_f32_e32 v5, v5
	v_and_b32_e32 v25, 0xffff0000, v80
	v_lshlrev_b32_e32 v10, 16, v80
	v_add_f32_e32 v9, v21, v20
	v_add_f32_e32 v9, v5, v9
	v_and_b32_e32 v31, 0xffff0000, v82
	v_rcp_f32_e32 v40, v9
	s_nop 0
	v_lshlrev_b32_e32 v12, 16, v82
	v_pk_mul_f32 v[20:21], v[20:21], v[40:41] op_sel_hi:[1,0]
	v_mul_f32_e32 v42, v5, v40
	v_pk_mul_f32 v[10:11], v[20:21], v[10:11] op_sel:[1,0] op_sel_hi:[0,1]
	v_pk_mul_f32 v[28:29], v[20:21], v[28:29] op_sel:[1,0] op_sel_hi:[0,1]
	v_pk_mul_f32 v[12:13], v[20:21], v[12:13] op_sel:[1,0] op_sel_hi:[0,1]
	v_pk_mul_f32 v[36:37], v[20:21], v[36:37] op_sel:[1,0] op_sel_hi:[0,1]
	v_pk_fma_f32 v[10:11], v[20:21], v[24:25], v[10:11]
	v_pk_fma_f32 v[24:25], v[20:21], v[26:27], v[28:29]
	v_pk_fma_f32 v[12:13], v[20:21], v[30:31], v[12:13]
	v_pk_fma_f32 v[20:21], v[20:21], v[34:35], v[36:37]
	v_pk_fma_f32 v[10:11], v[42:43], v[38:39], v[10:11] op_sel_hi:[0,1,1]
	v_pk_fma_f32 v[14:15], v[42:43], v[14:15], v[24:25] op_sel_hi:[0,1,1]
	v_pk_fma_f32 v[12:13], v[42:43], v[18:19], v[12:13] op_sel_hi:[0,1,1]
	v_pk_fma_f32 v[16:17], v[42:43], v[16:17], v[20:21] op_sel_hi:[0,1,1]
	v_cvt_pk_bf16_f32 v10, v10, v11
	v_cvt_pk_bf16_f32 v11, v14, v15
	v_cvt_pk_bf16_f32 v12, v12, v13
	v_cvt_pk_bf16_f32 v13, v16, v17
	v_add_u32_e32 v8, 0x20000, v7
	global_store_dwordx4 v8, v[10:13], s[8:9] offset:1024
	s_waitcnt vmcnt(27)
	v_max3_f32 v5, v108, v109, v110
	v_sub_f32_e32 v9, v108, v5
	v_sub_f32_e32 v40, v109, v5
	v_and_b32_e32 v27, 0xffff0000, v97
	v_lshlrev_b32_e32 v28, 16, v97
	v_sub_f32_e32 v5, v110, v5
	v_lshlrev_b32_e32 v24, 16, v100
	v_and_b32_e32 v11, 0xffff0000, v100
	v_lshlrev_b32_e32 v38, 16, v104
	v_and_b32_e32 v39, 0xffff0000, v104
	v_lshlrev_b32_e32 v26, 16, v101
	v_and_b32_e32 v29, 0xffff0000, v101
	v_lshlrev_b32_e32 v14, 16, v105
	v_and_b32_e32 v15, 0xffff0000, v105
	v_lshlrev_b32_e32 v18, 16, v106
	v_and_b32_e32 v19, 0xffff0000, v106
	v_mul_f32_e32 v9, 0x3fb8aa3b, v9
	v_mul_f32_e32 v20, 0x3fb8aa3b, v40
	v_and_b32_e32 v35, 0xffff0000, v99
	v_lshlrev_b32_e32 v36, 16, v99
	v_lshlrev_b32_e32 v30, 16, v102
	v_and_b32_e32 v13, 0xffff0000, v102
	v_lshlrev_b32_e32 v34, 16, v103
	v_and_b32_e32 v37, 0xffff0000, v103
	v_lshlrev_b32_e32 v16, 16, v107
	v_and_b32_e32 v17, 0xffff0000, v107
	v_mul_f32_e32 v5, 0x3fb8aa3b, v5
	v_exp_f32_e32 v21, v9
	v_exp_f32_e32 v20, v20
	v_exp_f32_e32 v5, v5
	v_and_b32_e32 v25, 0xffff0000, v96
	v_lshlrev_b32_e32 v10, 16, v96
	v_add_f32_e32 v9, v21, v20
	v_add_f32_e32 v9, v5, v9
	v_and_b32_e32 v31, 0xffff0000, v98
	v_rcp_f32_e32 v40, v9
	s_nop 0
	v_lshlrev_b32_e32 v12, 16, v98
	v_pk_mul_f32 v[20:21], v[20:21], v[40:41] op_sel_hi:[1,0]
	v_mul_f32_e32 v42, v5, v40
	v_pk_mul_f32 v[10:11], v[20:21], v[10:11] op_sel:[1,0] op_sel_hi:[0,1]
	v_pk_mul_f32 v[28:29], v[20:21], v[28:29] op_sel:[1,0] op_sel_hi:[0,1]
	v_pk_mul_f32 v[12:13], v[20:21], v[12:13] op_sel:[1,0] op_sel_hi:[0,1]
	v_pk_mul_f32 v[36:37], v[20:21], v[36:37] op_sel:[1,0] op_sel_hi:[0,1]
	v_pk_fma_f32 v[10:11], v[20:21], v[24:25], v[10:11]
	v_pk_fma_f32 v[24:25], v[20:21], v[26:27], v[28:29]
	v_pk_fma_f32 v[12:13], v[20:21], v[30:31], v[12:13]
	v_pk_fma_f32 v[20:21], v[20:21], v[34:35], v[36:37]
	v_pk_fma_f32 v[10:11], v[42:43], v[38:39], v[10:11] op_sel_hi:[0,1,1]
	v_pk_fma_f32 v[14:15], v[42:43], v[14:15], v[24:25] op_sel_hi:[0,1,1]
	v_pk_fma_f32 v[12:13], v[42:43], v[18:19], v[12:13] op_sel_hi:[0,1,1]
	v_pk_fma_f32 v[16:17], v[42:43], v[16:17], v[20:21] op_sel_hi:[0,1,1]
	v_cvt_pk_bf16_f32 v10, v10, v11
	v_cvt_pk_bf16_f32 v11, v14, v15
	v_cvt_pk_bf16_f32 v12, v12, v13
	v_cvt_pk_bf16_f32 v13, v16, v17
	v_add_u32_e32 v8, 0x30000, v7
	global_store_dwordx4 v8, v[10:13], s[8:9] offset:1024
	s_waitcnt vmcnt(22)
	v_max3_f32 v5, v140, v141, v142
	v_sub_f32_e32 v9, v140, v5
	v_sub_f32_e32 v40, v141, v5
	v_and_b32_e32 v27, 0xffff0000, v129
	v_lshlrev_b32_e32 v28, 16, v129
	v_sub_f32_e32 v5, v142, v5
	v_lshlrev_b32_e32 v24, 16, v132
	v_and_b32_e32 v11, 0xffff0000, v132
	v_lshlrev_b32_e32 v38, 16, v136
	v_and_b32_e32 v39, 0xffff0000, v136
	v_lshlrev_b32_e32 v26, 16, v133
	v_and_b32_e32 v29, 0xffff0000, v133
	v_lshlrev_b32_e32 v14, 16, v137
	v_and_b32_e32 v15, 0xffff0000, v137
	v_lshlrev_b32_e32 v18, 16, v138
	v_and_b32_e32 v19, 0xffff0000, v138
	v_mul_f32_e32 v9, 0x3fb8aa3b, v9
	v_mul_f32_e32 v20, 0x3fb8aa3b, v40
	v_and_b32_e32 v35, 0xffff0000, v131
	v_lshlrev_b32_e32 v36, 16, v131
	v_lshlrev_b32_e32 v30, 16, v134
	v_and_b32_e32 v13, 0xffff0000, v134
	v_lshlrev_b32_e32 v34, 16, v135
	v_and_b32_e32 v37, 0xffff0000, v135
	v_lshlrev_b32_e32 v16, 16, v139
	v_and_b32_e32 v17, 0xffff0000, v139
	v_mul_f32_e32 v5, 0x3fb8aa3b, v5
	v_exp_f32_e32 v21, v9
	v_exp_f32_e32 v20, v20
	v_exp_f32_e32 v5, v5
	v_and_b32_e32 v25, 0xffff0000, v128
	v_lshlrev_b32_e32 v10, 16, v128
	v_add_f32_e32 v9, v21, v20
	v_add_f32_e32 v9, v5, v9
	v_and_b32_e32 v31, 0xffff0000, v130
	v_rcp_f32_e32 v40, v9
	s_nop 0
	v_lshlrev_b32_e32 v12, 16, v130
	v_pk_mul_f32 v[20:21], v[20:21], v[40:41] op_sel_hi:[1,0]
	v_mul_f32_e32 v42, v5, v40
	v_pk_mul_f32 v[10:11], v[20:21], v[10:11] op_sel:[1,0] op_sel_hi:[0,1]
	v_pk_mul_f32 v[28:29], v[20:21], v[28:29] op_sel:[1,0] op_sel_hi:[0,1]
	v_pk_mul_f32 v[12:13], v[20:21], v[12:13] op_sel:[1,0] op_sel_hi:[0,1]
	v_pk_mul_f32 v[36:37], v[20:21], v[36:37] op_sel:[1,0] op_sel_hi:[0,1]
	v_pk_fma_f32 v[10:11], v[20:21], v[24:25], v[10:11]
	v_pk_fma_f32 v[24:25], v[20:21], v[26:27], v[28:29]
	v_pk_fma_f32 v[12:13], v[20:21], v[30:31], v[12:13]
	v_pk_fma_f32 v[20:21], v[20:21], v[34:35], v[36:37]
	v_pk_fma_f32 v[10:11], v[42:43], v[38:39], v[10:11] op_sel_hi:[0,1,1]
	v_pk_fma_f32 v[14:15], v[42:43], v[14:15], v[24:25] op_sel_hi:[0,1,1]
	v_pk_fma_f32 v[12:13], v[42:43], v[18:19], v[12:13] op_sel_hi:[0,1,1]
	v_pk_fma_f32 v[16:17], v[42:43], v[16:17], v[20:21] op_sel_hi:[0,1,1]
	v_cvt_pk_bf16_f32 v10, v10, v11
	v_cvt_pk_bf16_f32 v11, v14, v15
	v_cvt_pk_bf16_f32 v12, v12, v13
	v_cvt_pk_bf16_f32 v13, v16, v17
	v_add_u32_e32 v8, 0x40000, v7
	global_store_dwordx4 v8, v[10:13], s[8:9] offset:1024
	s_waitcnt vmcnt(17)
	v_max3_f32 v5, v164, v165, v166
	v_sub_f32_e32 v9, v164, v5
	v_sub_f32_e32 v40, v165, v5
	v_and_b32_e32 v27, 0xffff0000, v153
	v_lshlrev_b32_e32 v28, 16, v153
	v_sub_f32_e32 v5, v166, v5
	v_lshlrev_b32_e32 v24, 16, v156
	v_and_b32_e32 v11, 0xffff0000, v156
	v_lshlrev_b32_e32 v38, 16, v160
	v_and_b32_e32 v39, 0xffff0000, v160
	v_lshlrev_b32_e32 v26, 16, v157
	v_and_b32_e32 v29, 0xffff0000, v157
	v_lshlrev_b32_e32 v14, 16, v161
	v_and_b32_e32 v15, 0xffff0000, v161
	v_lshlrev_b32_e32 v18, 16, v162
	v_and_b32_e32 v19, 0xffff0000, v162
	v_mul_f32_e32 v9, 0x3fb8aa3b, v9
	v_mul_f32_e32 v20, 0x3fb8aa3b, v40
	v_and_b32_e32 v35, 0xffff0000, v155
	v_lshlrev_b32_e32 v36, 16, v155
	v_lshlrev_b32_e32 v30, 16, v158
	v_and_b32_e32 v13, 0xffff0000, v158
	v_lshlrev_b32_e32 v34, 16, v159
	v_and_b32_e32 v37, 0xffff0000, v159
	v_lshlrev_b32_e32 v16, 16, v163
	v_and_b32_e32 v17, 0xffff0000, v163
	v_mul_f32_e32 v5, 0x3fb8aa3b, v5
	v_exp_f32_e32 v21, v9
	v_exp_f32_e32 v20, v20
	v_exp_f32_e32 v5, v5
	v_and_b32_e32 v25, 0xffff0000, v152
	v_lshlrev_b32_e32 v10, 16, v152
	v_add_f32_e32 v9, v21, v20
	v_add_f32_e32 v9, v5, v9
	v_and_b32_e32 v31, 0xffff0000, v154
	v_rcp_f32_e32 v40, v9
	s_nop 0
	v_lshlrev_b32_e32 v12, 16, v154
	v_pk_mul_f32 v[20:21], v[20:21], v[40:41] op_sel_hi:[1,0]
	v_mul_f32_e32 v42, v5, v40
	v_pk_mul_f32 v[10:11], v[20:21], v[10:11] op_sel:[1,0] op_sel_hi:[0,1]
	v_pk_mul_f32 v[28:29], v[20:21], v[28:29] op_sel:[1,0] op_sel_hi:[0,1]
	v_pk_mul_f32 v[12:13], v[20:21], v[12:13] op_sel:[1,0] op_sel_hi:[0,1]
	v_pk_mul_f32 v[36:37], v[20:21], v[36:37] op_sel:[1,0] op_sel_hi:[0,1]
	v_pk_fma_f32 v[10:11], v[20:21], v[24:25], v[10:11]
	v_pk_fma_f32 v[24:25], v[20:21], v[26:27], v[28:29]
	v_pk_fma_f32 v[12:13], v[20:21], v[30:31], v[12:13]
	v_pk_fma_f32 v[20:21], v[20:21], v[34:35], v[36:37]
	v_pk_fma_f32 v[10:11], v[42:43], v[38:39], v[10:11] op_sel_hi:[0,1,1]
	v_pk_fma_f32 v[14:15], v[42:43], v[14:15], v[24:25] op_sel_hi:[0,1,1]
	v_pk_fma_f32 v[12:13], v[42:43], v[18:19], v[12:13] op_sel_hi:[0,1,1]
	v_pk_fma_f32 v[16:17], v[42:43], v[16:17], v[20:21] op_sel_hi:[0,1,1]
	v_cvt_pk_bf16_f32 v10, v10, v11
	v_cvt_pk_bf16_f32 v11, v14, v15
	v_cvt_pk_bf16_f32 v12, v12, v13
	v_cvt_pk_bf16_f32 v13, v16, v17
	v_add_u32_e32 v8, 0x50000, v7
	global_store_dwordx4 v8, v[10:13], s[8:9] offset:1024
	s_waitcnt vmcnt(12)
	v_max3_f32 v5, v218, v219, v220
	v_sub_f32_e32 v9, v218, v5
	v_sub_f32_e32 v40, v219, v5
	v_and_b32_e32 v27, 0xffff0000, v207
	v_lshlrev_b32_e32 v28, 16, v207
	v_sub_f32_e32 v5, v220, v5
	v_lshlrev_b32_e32 v24, 16, v210
	v_and_b32_e32 v11, 0xffff0000, v210
	v_lshlrev_b32_e32 v38, 16, v214
	v_and_b32_e32 v39, 0xffff0000, v214
	v_lshlrev_b32_e32 v26, 16, v211
	v_and_b32_e32 v29, 0xffff0000, v211
	v_lshlrev_b32_e32 v14, 16, v215
	v_and_b32_e32 v15, 0xffff0000, v215
	v_lshlrev_b32_e32 v18, 16, v216
	v_and_b32_e32 v19, 0xffff0000, v216
	v_mul_f32_e32 v9, 0x3fb8aa3b, v9
	v_mul_f32_e32 v20, 0x3fb8aa3b, v40
	v_and_b32_e32 v35, 0xffff0000, v209
	v_lshlrev_b32_e32 v36, 16, v209
	v_lshlrev_b32_e32 v30, 16, v212
	v_and_b32_e32 v13, 0xffff0000, v212
	v_lshlrev_b32_e32 v34, 16, v213
	v_and_b32_e32 v37, 0xffff0000, v213
	v_lshlrev_b32_e32 v16, 16, v217
	v_and_b32_e32 v17, 0xffff0000, v217
	v_mul_f32_e32 v5, 0x3fb8aa3b, v5
	v_exp_f32_e32 v21, v9
	v_exp_f32_e32 v20, v20
	v_exp_f32_e32 v5, v5
	v_and_b32_e32 v25, 0xffff0000, v206
	v_lshlrev_b32_e32 v10, 16, v206
	v_add_f32_e32 v9, v21, v20
	v_add_f32_e32 v9, v5, v9
	v_and_b32_e32 v31, 0xffff0000, v208
	v_rcp_f32_e32 v40, v9
	s_nop 0
	v_lshlrev_b32_e32 v12, 16, v208
	v_pk_mul_f32 v[20:21], v[20:21], v[40:41] op_sel_hi:[1,0]
	v_mul_f32_e32 v42, v5, v40
	v_pk_mul_f32 v[10:11], v[20:21], v[10:11] op_sel:[1,0] op_sel_hi:[0,1]
	v_pk_mul_f32 v[28:29], v[20:21], v[28:29] op_sel:[1,0] op_sel_hi:[0,1]
	v_pk_mul_f32 v[12:13], v[20:21], v[12:13] op_sel:[1,0] op_sel_hi:[0,1]
	v_pk_mul_f32 v[36:37], v[20:21], v[36:37] op_sel:[1,0] op_sel_hi:[0,1]
	v_pk_fma_f32 v[10:11], v[20:21], v[24:25], v[10:11]
	v_pk_fma_f32 v[24:25], v[20:21], v[26:27], v[28:29]
	v_pk_fma_f32 v[12:13], v[20:21], v[30:31], v[12:13]
	v_pk_fma_f32 v[20:21], v[20:21], v[34:35], v[36:37]
	v_pk_fma_f32 v[10:11], v[42:43], v[38:39], v[10:11] op_sel_hi:[0,1,1]
	v_pk_fma_f32 v[14:15], v[42:43], v[14:15], v[24:25] op_sel_hi:[0,1,1]
	v_pk_fma_f32 v[12:13], v[42:43], v[18:19], v[12:13] op_sel_hi:[0,1,1]
	v_pk_fma_f32 v[16:17], v[42:43], v[16:17], v[20:21] op_sel_hi:[0,1,1]
	v_cvt_pk_bf16_f32 v10, v10, v11
	v_cvt_pk_bf16_f32 v11, v14, v15
	v_cvt_pk_bf16_f32 v12, v12, v13
	v_cvt_pk_bf16_f32 v13, v16, v17
	v_add_u32_e32 v8, 0x60000, v7
	global_store_dwordx4 v8, v[10:13], s[8:9] offset:1024
	s_waitcnt vmcnt(7)
	v_max3_f32 v5, v244, v245, v246
	v_sub_f32_e32 v9, v244, v5
	v_sub_f32_e32 v40, v245, v5
	v_and_b32_e32 v27, 0xffff0000, v233
	v_lshlrev_b32_e32 v28, 16, v233
	v_sub_f32_e32 v5, v246, v5
	v_lshlrev_b32_e32 v24, 16, v236
	v_and_b32_e32 v11, 0xffff0000, v236
	v_lshlrev_b32_e32 v38, 16, v240
	v_and_b32_e32 v39, 0xffff0000, v240
	v_lshlrev_b32_e32 v26, 16, v237
	v_and_b32_e32 v29, 0xffff0000, v237
	v_lshlrev_b32_e32 v14, 16, v241
	v_and_b32_e32 v15, 0xffff0000, v241
	v_lshlrev_b32_e32 v18, 16, v242
	v_and_b32_e32 v19, 0xffff0000, v242
	v_mul_f32_e32 v9, 0x3fb8aa3b, v9
	v_mul_f32_e32 v20, 0x3fb8aa3b, v40
	v_and_b32_e32 v35, 0xffff0000, v235
	v_lshlrev_b32_e32 v36, 16, v235
	v_lshlrev_b32_e32 v30, 16, v238
	v_and_b32_e32 v13, 0xffff0000, v238
	v_lshlrev_b32_e32 v34, 16, v239
	v_and_b32_e32 v37, 0xffff0000, v239
	v_lshlrev_b32_e32 v16, 16, v243
	v_and_b32_e32 v17, 0xffff0000, v243
	v_mul_f32_e32 v5, 0x3fb8aa3b, v5
	v_exp_f32_e32 v21, v9
	v_exp_f32_e32 v20, v20
	v_exp_f32_e32 v5, v5
	v_and_b32_e32 v25, 0xffff0000, v232
	v_lshlrev_b32_e32 v10, 16, v232
	v_add_f32_e32 v9, v21, v20
	v_add_f32_e32 v9, v5, v9
	v_and_b32_e32 v31, 0xffff0000, v234
	v_rcp_f32_e32 v40, v9
	s_nop 0
	v_lshlrev_b32_e32 v12, 16, v234
	v_pk_mul_f32 v[20:21], v[20:21], v[40:41] op_sel_hi:[1,0]
	v_mul_f32_e32 v42, v5, v40
	v_pk_mul_f32 v[10:11], v[20:21], v[10:11] op_sel:[1,0] op_sel_hi:[0,1]
	v_pk_mul_f32 v[28:29], v[20:21], v[28:29] op_sel:[1,0] op_sel_hi:[0,1]
	v_pk_mul_f32 v[12:13], v[20:21], v[12:13] op_sel:[1,0] op_sel_hi:[0,1]
	v_pk_mul_f32 v[36:37], v[20:21], v[36:37] op_sel:[1,0] op_sel_hi:[0,1]
	v_pk_fma_f32 v[10:11], v[20:21], v[24:25], v[10:11]
	v_pk_fma_f32 v[24:25], v[20:21], v[26:27], v[28:29]
	v_pk_fma_f32 v[12:13], v[20:21], v[30:31], v[12:13]
	v_pk_fma_f32 v[20:21], v[20:21], v[34:35], v[36:37]
	v_pk_fma_f32 v[10:11], v[42:43], v[38:39], v[10:11] op_sel_hi:[0,1,1]
	v_pk_fma_f32 v[14:15], v[42:43], v[14:15], v[24:25] op_sel_hi:[0,1,1]
	v_pk_fma_f32 v[12:13], v[42:43], v[18:19], v[12:13] op_sel_hi:[0,1,1]
	v_pk_fma_f32 v[16:17], v[42:43], v[16:17], v[20:21] op_sel_hi:[0,1,1]
	v_cvt_pk_bf16_f32 v10, v10, v11
	v_cvt_pk_bf16_f32 v11, v14, v15
	v_cvt_pk_bf16_f32 v12, v12, v13
	v_cvt_pk_bf16_f32 v13, v16, v17
	v_add_u32_e32 v8, 0x70000, v7
	global_store_dwordx4 v8, v[10:13], s[8:9] offset:1024
	s_waitcnt vmcnt(0)
	s_barrier
	s_mov_b64 s[0:1], exec
	v_readlane_b32 s2, v254, 29
	v_readlane_b32 s3, v254, 30
	s_and_b64 s[2:3], s[0:1], s[2:3]
	s_mov_b64 exec, s[2:3]
	s_cbranch_execz .LBB0_605
	s_andn2_b64 vcc, exec, s[42:43]
	s_cbranch_vccnz .LBB0_594
	buffer_wbl2 sc1
	s_waitcnt vmcnt(0)
	s_waitcnt vmcnt(0)

.LBB0_655:
	s_or_b64 exec, exec, s[0:1]
	s_add_u32 s49, s96, 0x900000
	v_readfirstlane_b32 s0, v226
	s_addc_u32 s50, s97, 0
	s_lshr_b32 s2, s0, 6
	s_mov_b32 s41, 0
	s_lshr_b32 s1, s0, 8
	s_lshl_b32 s51, s2, 10
	s_lshl_b64 s[6:7], s[40:41], 19
	s_lshl_b32 s48, s52, 21
	s_add_u32 s16, s49, s48
	s_addc_u32 s17, s50, 0
	s_add_i32 s54, s51, 0
	s_add_i32 m0, s54, 0x10000
	v_lshl_add_u64 v[0:1], s[16:17], 0, v[156:157]
	s_barrier
	v_and_b32_e32 v250, 0xff, v226
	v_lshl_add_u32 v250, s40, 8, v250
	v_lshlrev_b32_e32 v250, 2, v250
	global_load_dword v251, v250, s[12:13]
	global_load_lds_dwordx4 v[0:1], off
	s_add_i32 m0, s54, 0x12000
	s_add_u32 s14, s16, 0x40000
	v_lshl_add_u64 v[2:3], s[16:17], 0, v[152:153]
	s_addc_u32 s15, s17, 0
	global_load_lds_dwordx4 v[2:3], off
	s_add_i32 m0, s54, 0x14000
	v_lshl_add_u64 v[4:5], s[14:15], 0, v[156:157]
	global_load_lds_dwordx4 v[4:5], off
	s_add_i32 m0, s54, 0x16000
	s_add_u32 s18, s26, s6
	v_lshl_add_u64 v[4:5], s[14:15], 0, v[152:153]
	s_addc_u32 s19, s27, s7
	s_add_i32 s55, s54, 0x2000
	global_load_lds_dwordx4 v[4:5], off
	v_lshl_add_u64 v[6:7], s[18:19], 0, v[158:159]
	s_mov_b32 m0, s54
	s_add_u32 s6, s18, 0x40000
	global_load_lds_dwordx4 v[6:7], off
	v_lshl_add_u64 v[4:5], s[18:19], 0, v[154:155]
	s_mov_b32 m0, s55
	s_addc_u32 s7, s19, 0
	s_add_i32 s56, s54, 0x4000
	global_load_lds_dwordx4 v[4:5], off
	v_lshl_add_u64 v[8:9], s[6:7], 0, v[158:159]
	s_mov_b32 m0, s56
	s_add_i32 s57, s54, 0x6000
	global_load_lds_dwordx4 v[8:9], off
	v_lshl_add_u64 v[8:9], s[6:7], 0, v[154:155]
	s_mov_b32 m0, s57
	s_cmp_eq_u32 s1, 1
	global_load_lds_dwordx4 v[8:9], off
	s_cselect_b64 s[20:21], -1, 0
	s_cmp_lg_u32 s1, 1
	s_cbranch_scc1 .LBB0_657
	s_barrier
.LBB0_657:
	s_add_u32 s14, s96, 0x7500000
	s_addc_u32 s15, s97, 0
	s_lshl_b32 s2, s2, 5
	s_mov_b64 s[22:23], 0x80
	s_and_b32 s7, s2, 0x60
	s_add_i32 m0, s54, 0x18000
	v_lshl_add_u64 v[0:1], v[0:1], 0, s[22:23]
	s_lshl_b32 s58, s52, 2
	s_lshl_b32 s6, s1, 13
	s_lshl_b32 s28, s7, 7
	s_waitcnt vmcnt(2)
	v_and_b32_e32 v250, 0xff, v226
	v_lshlrev_b32_e32 v250, 2, v250
	v_add_u32_e32 v250, 0x20200, v250
	ds_write_b32 v250, v251
	v_mov_b32_e32 v252, 0x20200
	s_waitcnt lgkmcnt(0)
	s_barrier
	global_load_lds_dwordx4 v[0:1], off
	v_lshl_add_u64 v[0:1], v[2:3], 0, s[22:23]
	s_add_i32 m0, s54, 0x1a000
	s_add_i32 s59, s54, 0x8000
	s_add_i32 s60, s54, 0xa000
	global_load_lds_dwordx4 v[0:1], off
	v_lshl_add_u64 v[0:1], v[6:7], 0, s[22:23]
	s_mov_b32 m0, s59
	s_add_u32 s2, s16, 0x40080
	global_load_lds_dwordx4 v[0:1], off
	v_lshl_add_u64 v[0:1], v[4:5], 0, s[22:23]
	s_mov_b32 m0, s60
	s_addc_u32 s3, s17, 0
	global_load_lds_dwordx4 v[0:1], off
	s_add_i32 m0, s54, 0x1c000
	v_lshl_add_u64 v[0:1], s[2:3], 0, v[156:157]
	global_load_lds_dwordx4 v[0:1], off
	v_lshl_add_u64 v[0:1], s[2:3], 0, v[152:153]
	s_add_i32 m0, s54, 0x1e000
	v_lshlrev_b32_e32 v3, 2, v193
	global_load_lds_dwordx4 v[0:1], off
	v_lshrrev_b32_e32 v0, 1, v226
	v_and_b32_e32 v0, 24, v0
	v_lshlrev_b32_e32 v1, 1, v0
	v_lshl_or_b32 v2, v193, 6, v1
	v_and_b32_e32 v138, 32, v3
	v_or_b32_e32 v1, v1, v200
	s_waitcnt vmcnt(6)
	v_bitop3_b32 v2, v2, s6, v138 bitop3:0xde
	v_bitop3_b32 v140, s28, v1, v199 bitop3:0xf6
	s_cmpk_lt_u32 s0, 0x100
	v_lshl_or_b32 v139, s1, 6, v193
	s_cselect_b64 s[28:29], -1, 0
	v_or_b32_e32 v141, s7, v0
	v_add_u32_e32 v142, s36, v140
	v_add_u32_e32 v143, s37, v140
	v_add_u32_e32 v144, 0, v2
	v_mov_b32_e32 v145, 0x358637bd
	s_mov_b32 s61, 0xf800000
	v_mov_b32_e32 v146, 0x260
	s_mov_b32 s30, s58
	s_mov_b32 s34, s40
	s_mov_b32 s62, s41
	s_barrier
	s_branch .LBB0_660

.LBB0_664:
	v_lshl_add_u32 v128, s64, 8, v139
	v_ashrrev_i32_e32 v129, 31, v128
	v_lshl_add_u32 v166, v139, 2, v252
	v_or_b32_e32 v136, 16, v128
	ds_read_b32 v170, v166
	v_ashrrev_i32_e32 v137, 31, v136

	ds_read_b32 v171, v166 offset:64
	v_or_b32_e32 v134, 32, v128
	v_or_b32_e32 v130, 48, v128
	v_ashrrev_i32_e32 v135, 31, v134
	v_ashrrev_i32_e32 v131, 31, v130


	ds_read_b32 v150, v166 offset:512
	ds_read_b32 v149, v166 offset:576
	ds_read_b32 v148, v166 offset:640
	s_nop 0
	ds_read_b32 v164, v166 offset:128
	s_nop 0
	ds_read_b32 v151, v166 offset:192
	ds_read_b32 v147, v166 offset:704
	v_lshl_or_b32 v132, s33, 8, v141
	v_ashrrev_i32_e32 v133, 31, v132
	v_lshlrev_b64 v[128:129], 13, v[128:129]
	v_lshlrev_b64 v[132:133], 1, v[132:133]
	v_lshl_add_u64 v[128:129], s[14:15], 0, v[128:129]
	v_lshl_add_u64 v[128:129], v[128:129], 0, v[132:133]
	s_cmp_eq_u32 s63, 3
	s_waitcnt lgkmcnt(0)
	v_fmamk_f32 v165, v170, 0x3a800000, v145
	v_fmamk_f32 v167, v171, 0x3a800000, v145
	v_rsq_f32_e32 v165, v165
	v_rsq_f32_e32 v171, v167
	v_mov_b32_e32 v166, v165
	v_pk_fma_f32 v[126:127], v[126:127], v[166:167], 0 op_sel_hi:[1,0,0]
	v_pk_fma_f32 v[124:125], v[124:125], v[166:167], 0 op_sel_hi:[1,0,0]
	v_pk_fma_f32 v[122:123], v[122:123], v[166:167], 0 op_sel_hi:[1,0,0]
	v_pk_fma_f32 v[120:121], v[120:121], v[166:167], 0 op_sel_hi:[1,0,0]
	v_pk_fma_f32 v[114:115], v[114:115], v[166:167], 0 op_sel_hi:[1,0,0]
	v_pk_fma_f32 v[112:113], v[112:113], v[166:167], 0 op_sel_hi:[1,0,0]
	v_max_f32_e32 v124, 0, v124
	v_max_f32_e32 v120, 0, v120
	v_max_f32_e32 v125, 0, v125
	v_max_f32_e32 v121, 0, v121
	v_max_f32_e32 v126, 0, v126
	v_max_f32_e32 v122, 0, v122
	v_max_f32_e32 v127, 0, v127
	v_max_f32_e32 v123, 0, v123
	v_max_f32_e32 v112, 0, v112
	v_max_f32_e32 v113, 0, v113
	v_max_f32_e32 v114, 0, v114
	v_max_f32_e32 v115, 0, v115
	v_pk_mul_f32 v[124:125], v[124:125], v[124:125]
	v_pk_mul_f32 v[120:121], v[120:121], v[120:121]
	v_pk_mul_f32 v[126:127], v[126:127], v[126:127]
	v_pk_mul_f32 v[122:123], v[122:123], v[122:123]
	v_pk_fma_f32 v[118:119], v[118:119], v[166:167], 0 op_sel_hi:[1,0,0]
	v_pk_fma_f32 v[116:117], v[116:117], v[166:167], 0 op_sel_hi:[1,0,0]
	v_pk_mul_f32 v[166:167], v[112:113], v[112:113]
	v_pk_mul_f32 v[168:169], v[114:115], v[114:115]
	v_cvt_pk_bf16_f32 v112, v124, v125
	v_cvt_pk_bf16_f32 v113, v126, v127
	v_cvt_pk_bf16_f32 v114, v120, v121
	v_cvt_pk_bf16_f32 v115, v122, v123
	global_store_dwordx4 v[128:129], v[112:115], off
	v_max_f32_e32 v116, 0, v116
	v_max_f32_e32 v117, 0, v117
	v_max_f32_e32 v118, 0, v118
	v_max_f32_e32 v119, 0, v119
	v_pk_mul_f32 v[116:117], v[116:117], v[116:117]
	v_mov_b32_e32 v112, v171
	v_pk_mul_f32 v[118:119], v[118:119], v[118:119]
	v_pk_fma_f32 v[104:105], v[104:105], v[112:113], 0 op_sel_hi:[1,0,0]
	v_cvt_pk_bf16_f32 v116, v116, v117
	v_cvt_pk_bf16_f32 v117, v118, v119
	v_cvt_pk_bf16_f32 v118, v166, v167
	v_cvt_pk_bf16_f32 v119, v168, v169
	v_pk_fma_f32 v[110:111], v[110:111], v[112:113], 0 op_sel_hi:[1,0,0]
	v_pk_fma_f32 v[108:109], v[108:109], v[112:113], 0 op_sel_hi:[1,0,0]
	v_pk_fma_f32 v[106:107], v[106:107], v[112:113], 0 op_sel_hi:[1,0,0]
	v_max_f32_e32 v104, 0, v104
	v_max_f32_e32 v105, 0, v105
	global_store_dwordx4 v[128:129], v[116:119], off offset:256
	v_lshlrev_b64 v[114:115], 13, v[136:137]
	v_max_f32_e32 v108, 0, v108
	v_max_f32_e32 v109, 0, v109
	v_pk_mul_f32 v[116:117], v[104:105], v[104:105]
	v_max_f32_e32 v104, 0, v110
	v_max_f32_e32 v106, 0, v106
	v_max_f32_e32 v105, 0, v111
	v_max_f32_e32 v107, 0, v107
	v_lshl_add_u64 v[114:115], s[14:15], 0, v[114:115]
	v_pk_mul_f32 v[108:109], v[108:109], v[108:109]
	v_pk_mul_f32 v[110:111], v[104:105], v[104:105]
	v_pk_mul_f32 v[118:119], v[106:107], v[106:107]
	v_pk_fma_f32 v[96:97], v[96:97], v[112:113], 0 op_sel_hi:[1,0,0]
	v_lshl_add_u64 v[114:115], v[114:115], 0, v[132:133]
	v_cvt_pk_bf16_f32 v104, v108, v109
	v_cvt_pk_bf16_f32 v105, v110, v111
	v_cvt_pk_bf16_f32 v106, v116, v117
	v_cvt_pk_bf16_f32 v107, v118, v119
	v_pk_fma_f32 v[102:103], v[102:103], v[112:113], 0 op_sel_hi:[1,0,0]
	v_max_f32_e32 v96, 0, v96
	v_max_f32_e32 v97, 0, v97
	global_store_dwordx4 v[114:115], v[104:107], off
	v_pk_fma_f32 v[98:99], v[98:99], v[112:113], 0 op_sel_hi:[1,0,0]
	v_pk_fma_f32 v[100:101], v[100:101], v[112:113], 0 op_sel_hi:[1,0,0]
	v_pk_mul_f32 v[104:105], v[96:97], v[96:97]
	v_max_f32_e32 v96, 0, v102
	v_max_f32_e32 v97, 0, v103
	v_pk_mul_f32 v[102:103], v[96:97], v[96:97]
	v_fmamk_f32 v96, v164, 0x3a800000, v145
	v_max_f32_e32 v98, 0, v98
	v_max_f32_e32 v99, 0, v99
	v_rsq_f32_e32 v108, v96
	v_pk_mul_f32 v[106:107], v[98:99], v[98:99]
	v_max_f32_e32 v100, 0, v100
	v_max_f32_e32 v101, 0, v101
	v_pk_mul_f32 v[100:101], v[100:101], v[100:101]
	v_cvt_pk_bf16_f32 v96, v100, v101
	v_cvt_pk_bf16_f32 v97, v102, v103
	s_nop 0
	v_cvt_pk_bf16_f32 v99, v106, v107
	s_nop 0
	v_mov_b32_e32 v100, v108
	v_cvt_pk_bf16_f32 v98, v104, v105
	global_store_dwordx4 v[114:115], v[96:99], off offset:256
	s_nop 1
	v_mov_b32_e32 v96, v100
	v_pk_fma_f32 v[88:89], v[88:89], v[96:97], 0 op_sel_hi:[1,0,0]
	v_pk_fma_f32 v[94:95], v[94:95], v[96:97], 0 op_sel_hi:[1,0,0]
	v_pk_fma_f32 v[92:93], v[92:93], v[96:97], 0 op_sel_hi:[1,0,0]
	v_pk_fma_f32 v[90:91], v[90:91], v[96:97], 0 op_sel_hi:[1,0,0]
	v_max_f32_e32 v88, 0, v88
	v_max_f32_e32 v89, 0, v89
	v_lshlrev_b64 v[98:99], 13, v[134:135]
	v_max_f32_e32 v92, 0, v92
	v_max_f32_e32 v93, 0, v93
	v_pk_mul_f32 v[100:101], v[88:89], v[88:89]
	v_max_f32_e32 v88, 0, v94
	v_max_f32_e32 v90, 0, v90
	v_max_f32_e32 v89, 0, v95
	v_max_f32_e32 v91, 0, v91
	v_lshl_add_u64 v[98:99], s[14:15], 0, v[98:99]
	v_pk_mul_f32 v[92:93], v[92:93], v[92:93]
	v_pk_mul_f32 v[94:95], v[88:89], v[88:89]
	v_pk_mul_f32 v[102:103], v[90:91], v[90:91]
	v_pk_fma_f32 v[80:81], v[80:81], v[96:97], 0 op_sel_hi:[1,0,0]
	v_lshl_add_u64 v[98:99], v[98:99], 0, v[132:133]
	v_cvt_pk_bf16_f32 v88, v92, v93
	v_cvt_pk_bf16_f32 v89, v94, v95
	v_cvt_pk_bf16_f32 v90, v100, v101
	v_cvt_pk_bf16_f32 v91, v102, v103
	v_pk_fma_f32 v[86:87], v[86:87], v[96:97], 0 op_sel_hi:[1,0,0]
	v_max_f32_e32 v80, 0, v80
	v_max_f32_e32 v81, 0, v81
	global_store_dwordx4 v[98:99], v[88:91], off
	v_pk_fma_f32 v[82:83], v[82:83], v[96:97], 0 op_sel_hi:[1,0,0]
	v_pk_fma_f32 v[84:85], v[84:85], v[96:97], 0 op_sel_hi:[1,0,0]
	v_pk_mul_f32 v[88:89], v[80:81], v[80:81]
	v_max_f32_e32 v80, 0, v86
	v_max_f32_e32 v81, 0, v87
	v_pk_mul_f32 v[86:87], v[80:81], v[80:81]
	v_fmamk_f32 v80, v151, 0x3a800000, v145
	v_max_f32_e32 v82, 0, v82
	v_max_f32_e32 v83, 0, v83
	v_rsq_f32_e32 v92, v80
	v_pk_mul_f32 v[90:91], v[82:83], v[82:83]
	v_max_f32_e32 v84, 0, v84
	v_max_f32_e32 v85, 0, v85
	v_pk_mul_f32 v[84:85], v[84:85], v[84:85]
	v_cvt_pk_bf16_f32 v80, v84, v85
	v_cvt_pk_bf16_f32 v81, v86, v87
	s_nop 0
	v_cvt_pk_bf16_f32 v83, v90, v91
	s_nop 0
	v_mov_b32_e32 v84, v92
	v_cvt_pk_bf16_f32 v82, v88, v89
	global_store_dwordx4 v[98:99], v[80:83], off offset:256
	s_nop 1
	v_mov_b32_e32 v80, v84
	v_pk_fma_f32 v[72:73], v[72:73], v[80:81], 0 op_sel_hi:[1,0,0]
	v_pk_fma_f32 v[78:79], v[78:79], v[80:81], 0 op_sel_hi:[1,0,0]
	v_pk_fma_f32 v[76:77], v[76:77], v[80:81], 0 op_sel_hi:[1,0,0]
	v_pk_fma_f32 v[74:75], v[74:75], v[80:81], 0 op_sel_hi:[1,0,0]
	v_max_f32_e32 v72, 0, v72
	v_max_f32_e32 v73, 0, v73
	v_lshlrev_b64 v[82:83], 13, v[130:131]
	v_max_f32_e32 v76, 0, v76
	v_max_f32_e32 v77, 0, v77
	v_pk_mul_f32 v[84:85], v[72:73], v[72:73]
	v_max_f32_e32 v72, 0, v78
	v_max_f32_e32 v74, 0, v74
	v_max_f32_e32 v73, 0, v79
	v_max_f32_e32 v75, 0, v75
	v_lshl_add_u64 v[82:83], s[14:15], 0, v[82:83]
	v_pk_mul_f32 v[76:77], v[76:77], v[76:77]
	v_pk_mul_f32 v[78:79], v[72:73], v[72:73]
	v_pk_mul_f32 v[86:87], v[74:75], v[74:75]
	v_pk_fma_f32 v[64:65], v[64:65], v[80:81], 0 op_sel_hi:[1,0,0]
	v_lshl_add_u64 v[82:83], v[82:83], 0, v[132:133]
	v_cvt_pk_bf16_f32 v72, v76, v77
	v_cvt_pk_bf16_f32 v73, v78, v79
	v_cvt_pk_bf16_f32 v74, v84, v85
	v_cvt_pk_bf16_f32 v75, v86, v87
	v_pk_fma_f32 v[70:71], v[70:71], v[80:81], 0 op_sel_hi:[1,0,0]
	v_max_f32_e32 v64, 0, v64
	v_max_f32_e32 v65, 0, v65
	global_store_dwordx4 v[82:83], v[72:75], off
	v_pk_fma_f32 v[66:67], v[66:67], v[80:81], 0 op_sel_hi:[1,0,0]
	v_pk_fma_f32 v[68:69], v[68:69], v[80:81], 0 op_sel_hi:[1,0,0]
	v_pk_mul_f32 v[72:73], v[64:65], v[64:65]
	v_max_f32_e32 v64, 0, v70
	v_max_f32_e32 v65, 0, v71
	v_pk_mul_f32 v[70:71], v[64:65], v[64:65]
	v_fmamk_f32 v64, v150, 0x3a800000, v145
	v_max_f32_e32 v66, 0, v66
	v_max_f32_e32 v67, 0, v67
	v_rsq_f32_e32 v76, v64
	v_pk_mul_f32 v[74:75], v[66:67], v[66:67]
	v_max_f32_e32 v68, 0, v68
	v_max_f32_e32 v69, 0, v69
	v_pk_mul_f32 v[68:69], v[68:69], v[68:69]
	v_cvt_pk_bf16_f32 v64, v68, v69
	v_cvt_pk_bf16_f32 v65, v70, v71
	s_nop 0
	v_cvt_pk_bf16_f32 v67, v74, v75
	s_nop 0
	v_mov_b32_e32 v68, v76
	v_cvt_pk_bf16_f32 v66, v72, v73
	global_store_dwordx4 v[82:83], v[64:67], off offset:256
	s_mov_b64 s[0:1], 0x100000
	s_nop 0
	v_mov_b32_e32 v64, v68
	v_pk_fma_f32 v[60:61], v[60:61], v[64:65], 0 op_sel_hi:[1,0,0]
	v_pk_fma_f32 v[56:57], v[56:57], v[64:65], 0 op_sel_hi:[1,0,0]
	v_pk_fma_f32 v[62:63], v[62:63], v[64:65], 0 op_sel_hi:[1,0,0]
	v_pk_fma_f32 v[58:59], v[58:59], v[64:65], 0 op_sel_hi:[1,0,0]
	v_max_f32_e32 v60, 0, v60
	v_max_f32_e32 v56, 0, v56
	v_max_f32_e32 v61, 0, v61
	v_max_f32_e32 v57, 0, v57
	v_lshl_add_u64 v[66:67], v[128:129], 0, s[0:1]
	v_pk_mul_f32 v[60:61], v[60:61], v[60:61]
	v_pk_mul_f32 v[68:69], v[56:57], v[56:57]
	v_max_f32_e32 v56, 0, v62
	v_max_f32_e32 v58, 0, v58
	v_max_f32_e32 v57, 0, v63
	v_max_f32_e32 v59, 0, v59
	s_mov_b32 s0, 0x100000
	v_pk_mul_f32 v[62:63], v[56:57], v[56:57]
	v_pk_mul_f32 v[70:71], v[58:59], v[58:59]
	v_cvt_pk_bf16_f32 v56, v60, v61
	v_add_co_u32_e32 v60, vcc, s0, v128
	v_pk_fma_f32 v[48:49], v[48:49], v[64:65], 0 op_sel_hi:[1,0,0]
	v_cvt_pk_bf16_f32 v57, v62, v63
	v_cvt_pk_bf16_f32 v58, v68, v69
	v_cvt_pk_bf16_f32 v59, v70, v71
	v_addc_co_u32_e32 v61, vcc, 0, v129, vcc
	v_pk_fma_f32 v[54:55], v[54:55], v[64:65], 0 op_sel_hi:[1,0,0]
	v_max_f32_e32 v48, 0, v48
	v_max_f32_e32 v49, 0, v49
	global_store_dwordx4 v[60:61], v[56:59], off
	v_pk_fma_f32 v[50:51], v[50:51], v[64:65], 0 op_sel_hi:[1,0,0]
	v_pk_fma_f32 v[52:53], v[52:53], v[64:65], 0 op_sel_hi:[1,0,0]
	v_pk_mul_f32 v[56:57], v[48:49], v[48:49]
	v_max_f32_e32 v48, 0, v54
	v_max_f32_e32 v49, 0, v55
	v_pk_mul_f32 v[54:55], v[48:49], v[48:49]
	v_fmamk_f32 v48, v149, 0x3a800000, v145
	v_max_f32_e32 v50, 0, v50
	v_max_f32_e32 v51, 0, v51
	v_rsq_f32_e32 v60, v48
	v_pk_mul_f32 v[58:59], v[50:51], v[50:51]
	v_max_f32_e32 v52, 0, v52
	v_max_f32_e32 v53, 0, v53
	v_pk_mul_f32 v[52:53], v[52:53], v[52:53]
	v_cvt_pk_bf16_f32 v48, v52, v53
	v_cvt_pk_bf16_f32 v49, v54, v55
	s_nop 0
	v_cvt_pk_bf16_f32 v51, v58, v59
	s_nop 0
	v_mov_b32_e32 v52, v60
	v_cvt_pk_bf16_f32 v50, v56, v57
	global_store_dwordx4 v[66:67], v[48:51], off offset:256
	s_mov_b64 s[0:1], 0x120000
	s_nop 0
	v_mov_b32_e32 v48, v52
	v_pk_fma_f32 v[44:45], v[44:45], v[48:49], 0 op_sel_hi:[1,0,0]
	v_pk_fma_f32 v[40:41], v[40:41], v[48:49], 0 op_sel_hi:[1,0,0]
	v_pk_fma_f32 v[46:47], v[46:47], v[48:49], 0 op_sel_hi:[1,0,0]
	v_pk_fma_f32 v[42:43], v[42:43], v[48:49], 0 op_sel_hi:[1,0,0]
	v_max_f32_e32 v44, 0, v44
	v_max_f32_e32 v40, 0, v40
	v_max_f32_e32 v45, 0, v45
	v_max_f32_e32 v41, 0, v41
	v_lshl_add_u64 v[50:51], v[128:129], 0, s[0:1]
	v_pk_mul_f32 v[44:45], v[44:45], v[44:45]
	v_pk_mul_f32 v[52:53], v[40:41], v[40:41]
	v_max_f32_e32 v40, 0, v46
	v_max_f32_e32 v42, 0, v42
	v_max_f32_e32 v41, 0, v47
	v_max_f32_e32 v43, 0, v43
	s_mov_b32 s0, 0x120000
	v_pk_mul_f32 v[46:47], v[40:41], v[40:41]
	v_pk_mul_f32 v[54:55], v[42:43], v[42:43]
	v_cvt_pk_bf16_f32 v40, v44, v45
	v_add_co_u32_e32 v44, vcc, s0, v128
	v_pk_fma_f32 v[32:33], v[32:33], v[48:49], 0 op_sel_hi:[1,0,0]
	v_cvt_pk_bf16_f32 v41, v46, v47
	v_cvt_pk_bf16_f32 v42, v52, v53
	v_cvt_pk_bf16_f32 v43, v54, v55
	v_addc_co_u32_e32 v45, vcc, 0, v129, vcc
	v_pk_fma_f32 v[38:39], v[38:39], v[48:49], 0 op_sel_hi:[1,0,0]
	v_max_f32_e32 v32, 0, v32
	v_max_f32_e32 v33, 0, v33
	global_store_dwordx4 v[44:45], v[40:43], off
	v_pk_fma_f32 v[34:35], v[34:35], v[48:49], 0 op_sel_hi:[1,0,0]
	v_pk_fma_f32 v[36:37], v[36:37], v[48:49], 0 op_sel_hi:[1,0,0]
	v_pk_mul_f32 v[40:41], v[32:33], v[32:33]
	v_max_f32_e32 v32, 0, v38
	v_max_f32_e32 v33, 0, v39
	v_pk_mul_f32 v[38:39], v[32:33], v[32:33]
	v_fmamk_f32 v32, v148, 0x3a800000, v145
	v_max_f32_e32 v34, 0, v34
	v_max_f32_e32 v35, 0, v35
	v_rsq_f32_e32 v44, v32
	v_pk_mul_f32 v[42:43], v[34:35], v[34:35]
	v_max_f32_e32 v36, 0, v36
	v_max_f32_e32 v37, 0, v37
	v_pk_mul_f32 v[36:37], v[36:37], v[36:37]
	v_cvt_pk_bf16_f32 v32, v36, v37
	v_cvt_pk_bf16_f32 v33, v38, v39
	s_nop 0
	v_cvt_pk_bf16_f32 v35, v42, v43
	s_nop 0
	v_mov_b32_e32 v36, v44
	v_cvt_pk_bf16_f32 v34, v40, v41
	global_store_dwordx4 v[50:51], v[32:35], off offset:256
	s_mov_b64 s[0:1], 0x140000
	s_nop 0
	v_mov_b32_e32 v32, v36
	v_pk_fma_f32 v[28:29], v[28:29], v[32:33], 0 op_sel_hi:[1,0,0]
	v_pk_fma_f32 v[24:25], v[24:25], v[32:33], 0 op_sel_hi:[1,0,0]
	v_pk_fma_f32 v[30:31], v[30:31], v[32:33], 0 op_sel_hi:[1,0,0]
	v_pk_fma_f32 v[26:27], v[26:27], v[32:33], 0 op_sel_hi:[1,0,0]
	v_max_f32_e32 v28, 0, v28
	v_max_f32_e32 v24, 0, v24
	v_max_f32_e32 v29, 0, v29
	v_max_f32_e32 v25, 0, v25
	v_lshl_add_u64 v[34:35], v[128:129], 0, s[0:1]
	v_pk_mul_f32 v[28:29], v[28:29], v[28:29]
	v_pk_mul_f32 v[36:37], v[24:25], v[24:25]
	v_max_f32_e32 v24, 0, v30
	v_max_f32_e32 v26, 0, v26
	v_max_f32_e32 v25, 0, v31
	v_max_f32_e32 v27, 0, v27
	s_mov_b32 s0, 0x140000
	v_pk_mul_f32 v[30:31], v[24:25], v[24:25]
	v_pk_mul_f32 v[38:39], v[26:27], v[26:27]
	v_cvt_pk_bf16_f32 v24, v28, v29
	v_add_co_u32_e32 v28, vcc, s0, v128
	v_pk_fma_f32 v[16:17], v[16:17], v[32:33], 0 op_sel_hi:[1,0,0]
	v_cvt_pk_bf16_f32 v25, v30, v31
	v_cvt_pk_bf16_f32 v26, v36, v37
	v_cvt_pk_bf16_f32 v27, v38, v39
	v_addc_co_u32_e32 v29, vcc, 0, v129, vcc
	v_pk_fma_f32 v[22:23], v[22:23], v[32:33], 0 op_sel_hi:[1,0,0]
	v_max_f32_e32 v16, 0, v16
	v_max_f32_e32 v17, 0, v17
	global_store_dwordx4 v[28:29], v[24:27], off
	v_pk_fma_f32 v[18:19], v[18:19], v[32:33], 0 op_sel_hi:[1,0,0]
	v_pk_fma_f32 v[20:21], v[20:21], v[32:33], 0 op_sel_hi:[1,0,0]
	v_pk_mul_f32 v[24:25], v[16:17], v[16:17]
	v_max_f32_e32 v16, 0, v22
	v_max_f32_e32 v17, 0, v23
	v_pk_mul_f32 v[22:23], v[16:17], v[16:17]
	v_fmamk_f32 v16, v147, 0x3a800000, v145
	v_max_f32_e32 v18, 0, v18
	v_max_f32_e32 v19, 0, v19
	v_rsq_f32_e32 v28, v16
	v_pk_mul_f32 v[26:27], v[18:19], v[18:19]
	v_max_f32_e32 v20, 0, v20
	v_max_f32_e32 v21, 0, v21
	v_pk_mul_f32 v[20:21], v[20:21], v[20:21]
	v_cvt_pk_bf16_f32 v16, v20, v21
	v_cvt_pk_bf16_f32 v17, v22, v23
	s_nop 0
	v_cvt_pk_bf16_f32 v19, v26, v27
	s_nop 0
	v_mov_b32_e32 v20, v28
	v_cvt_pk_bf16_f32 v18, v24, v25
	global_store_dwordx4 v[34:35], v[16:19], off offset:256
	s_mov_b64 s[0:1], 0x160000
	s_nop 0
	v_mov_b32_e32 v16, v20
	v_pk_fma_f32 v[12:13], v[12:13], v[16:17], 0 op_sel_hi:[1,0,0]
	v_pk_fma_f32 v[8:9], v[8:9], v[16:17], 0 op_sel_hi:[1,0,0]
	v_pk_fma_f32 v[14:15], v[14:15], v[16:17], 0 op_sel_hi:[1,0,0]
	v_pk_fma_f32 v[10:11], v[10:11], v[16:17], 0 op_sel_hi:[1,0,0]
	v_max_f32_e32 v12, 0, v12
	v_max_f32_e32 v8, 0, v8
	v_max_f32_e32 v13, 0, v13
	v_max_f32_e32 v9, 0, v9
	v_lshl_add_u64 v[18:19], v[128:129], 0, s[0:1]
	v_pk_mul_f32 v[12:13], v[12:13], v[12:13]
	v_pk_mul_f32 v[20:21], v[8:9], v[8:9]
	v_max_f32_e32 v8, 0, v14
	v_max_f32_e32 v10, 0, v10
	v_max_f32_e32 v9, 0, v15
	v_max_f32_e32 v11, 0, v11
	s_mov_b32 s0, 0x160000
	v_pk_mul_f32 v[14:15], v[8:9], v[8:9]
	v_pk_mul_f32 v[22:23], v[10:11], v[10:11]
	v_cvt_pk_bf16_f32 v8, v12, v13
	v_add_co_u32_e32 v12, vcc, s0, v128
	v_pk_fma_f32 v[0:1], v[0:1], v[16:17], 0 op_sel_hi:[1,0,0]
	v_cvt_pk_bf16_f32 v9, v14, v15
	v_cvt_pk_bf16_f32 v10, v20, v21
	v_cvt_pk_bf16_f32 v11, v22, v23
	v_addc_co_u32_e32 v13, vcc, 0, v129, vcc
	v_pk_fma_f32 v[6:7], v[6:7], v[16:17], 0 op_sel_hi:[1,0,0]
	v_pk_fma_f32 v[4:5], v[4:5], v[16:17], 0 op_sel_hi:[1,0,0]
	v_pk_fma_f32 v[2:3], v[2:3], v[16:17], 0 op_sel_hi:[1,0,0]
	v_max_f32_e32 v0, 0, v0
	v_max_f32_e32 v1, 0, v1
	global_store_dwordx4 v[12:13], v[8:11], off
	v_max_f32_e32 v4, 0, v4
	v_max_f32_e32 v5, 0, v5
	v_pk_mul_f32 v[8:9], v[0:1], v[0:1]
	v_max_f32_e32 v0, 0, v6
	v_max_f32_e32 v2, 0, v2
	v_max_f32_e32 v1, 0, v7
	v_max_f32_e32 v3, 0, v3
	v_pk_mul_f32 v[4:5], v[4:5], v[4:5]
	v_pk_mul_f32 v[6:7], v[0:1], v[0:1]
	v_pk_mul_f32 v[10:11], v[2:3], v[2:3]
	v_cvt_pk_bf16_f32 v0, v4, v5
	v_cvt_pk_bf16_f32 v1, v6, v7
	v_cvt_pk_bf16_f32 v2, v8, v9
	v_cvt_pk_bf16_f32 v3, v10, v11
	s_mov_b64 s[0:1], -1
	global_store_dwordx4 v[18:19], v[0:3], off offset:256
	s_cbranch_scc1 .LBB0_659
	s_andn2_b64 vcc, exec, s[20:21]
	s_cbranch_vccnz .LBB0_658
	s_barrier
	s_branch .LBB0_658

.LBB0_787:
	s_waitcnt vmcnt(0)
	v_fmamk_f32 v202, v202, 0x3a800000, v235
	v_rsq_f32_e32 v202, v202
	v_cndmask_b32_e64 v218, 1.0, v237, s[12:13]
	v_mov_b32_e32 v219, v218
	v_pk_fma_f32 v[158:159], v[158:159], v[202:203], v[50:51] op_sel_hi:[1,0,1]
	v_pk_fma_f32 v[156:157], v[156:157], v[202:203], v[48:49] op_sel_hi:[1,0,1]
	v_pk_fma_f32 v[154:155], v[154:155], v[202:203], v[58:59] op_sel_hi:[1,0,1]
	v_pk_fma_f32 v[152:153], v[152:153], v[202:203], v[56:57] op_sel_hi:[1,0,1]
	v_pk_fma_f32 v[150:151], v[150:151], v[202:203], v[66:67] op_sel_hi:[1,0,1]
	v_pk_fma_f32 v[148:149], v[148:149], v[202:203], v[64:65] op_sel_hi:[1,0,1]
	v_pk_fma_f32 v[146:147], v[146:147], v[202:203], v[70:71] op_sel_hi:[1,0,1]
	s_and_b64 vcc, exec, s[10:11]
	v_pk_fma_f32 v[144:145], v[144:145], v[202:203], v[68:69] op_sel_hi:[1,0,1]
	s_cbranch_vccnz .LBB0_789
	v_pk_mul_f32 v[240:241], v[158:159], v[158:159]
	v_pk_mul_f32 v[242:243], v[156:157], v[156:157]
	v_mul_f32_e32 v202, v148, v148
	v_pk_mov_b32 v[244:245], v[242:243], v[240:241] op_sel:[1,0]
	v_mov_b32_e32 v243, v241
	v_pk_add_f32 v[240:241], v[244:245], v[242:243]
	v_pk_mul_f32 v[242:243], v[154:155], v[154:155]
	v_pk_mul_f32 v[244:245], v[152:153], v[152:153]
	v_pk_add_f32 v[240:241], v[240:241], v[240:241] op_sel_hi:[0,1]
	v_pk_mov_b32 v[246:247], v[244:245], v[242:243] op_sel:[1,0]
	v_mov_b32_e32 v245, v243
	v_pk_add_f32 v[242:243], v[246:247], v[244:245]
	v_pk_fma_f32 v[244:245], v[148:149], v[148:149], v[202:203] op_sel_hi:[1,1,0]
	v_mul_f32_e32 v202, v150, v150
	v_pk_add_f32 v[242:243], v[242:243], v[242:243] op_sel_hi:[0,1]
	v_pk_fma_f32 v[246:247], v[150:151], v[150:151], v[202:203] op_sel_hi:[1,1,0]
	v_and_b32_e32 v225, 64, v238
	v_mul_f32_e32 v244, v144, v144
	v_mul_f32_e32 v246, v145, v145
	v_mul_f32_e32 v240, v146, v146
	v_mul_f32_e32 v242, v147, v147
	v_xor_b32_e32 v221, 16, v238
	v_add_u32_e32 v225, 64, v225
	v_pk_add_f32 v[244:245], v[244:245], v[246:247]
	v_pk_add_f32 v[240:241], v[240:241], v[242:243]
	v_cmp_lt_i32_e32 vcc, v221, v225
	v_pk_add_f32 v[240:241], v[244:245], v[240:241]
	s_nop 0
	v_cndmask_b32_e32 v221, v238, v221, vcc
	v_add_f32_e32 v202, v240, v241
	v_lshlrev_b32_e32 v221, 2, v221
	ds_bpermute_b32 v239, v221, v202
	s_waitcnt lgkmcnt(0)
	v_add_f32_e32 v202, v202, v239
	v_xor_b32_e32 v239, 32, v238
	v_cmp_lt_i32_e32 vcc, v239, v225
	s_nop 1
	v_cndmask_b32_e32 v225, v238, v239, vcc
	v_lshlrev_b32_e32 v225, 2, v225
	ds_bpermute_b32 v225, v225, v202
	s_waitcnt lgkmcnt(0)
	v_add_f32_e32 v202, v202, v225
	v_fmamk_f32 v202, v202, 0x3c800000, v235
	v_rsq_f32_e32 v202, v202
	s_nop 0
	v_pk_mul_f32 v[156:157], v[156:157], v[202:203] op_sel_hi:[1,0]
	v_pk_mul_f32 v[158:159], v[158:159], v[202:203] op_sel_hi:[1,0]
	v_pk_mul_f32 v[156:157], v[36:37], v[156:157]
	ds_bpermute_b32 v225, v221, v156
	v_pk_mul_f32 v[152:153], v[152:153], v[202:203] op_sel_hi:[1,0]
	v_pk_mul_f32 v[154:155], v[154:155], v[202:203] op_sel_hi:[1,0]
	v_pk_mul_f32 v[150:151], v[150:151], v[202:203] op_sel_hi:[1,0]
	v_pk_mul_f32 v[148:149], v[148:149], v[202:203] op_sel_hi:[1,0]
	v_pk_mul_f32 v[146:147], v[146:147], v[202:203] op_sel_hi:[1,0]
	v_pk_mul_f32 v[144:145], v[144:145], v[202:203] op_sel_hi:[1,0]
	ds_bpermute_b32 v202, v221, v157
	s_waitcnt lgkmcnt(1)
	v_mul_f32_e32 v188, v188, v225
	v_cndmask_b32_e64 v188, v188, -v188, s[4:5]
	v_pk_mul_f32 v[158:159], v[38:39], v[158:159]
	v_fmac_f32_e32 v188, v184, v156
	s_waitcnt lgkmcnt(0)
	v_mul_f32_e32 v184, v189, v202
	v_cndmask_b32_e64 v156, v156, v188, s[6:7]
	ds_bpermute_b32 v188, v221, v158
	v_cndmask_b32_e64 v184, v184, -v184, s[4:5]
	v_fmac_f32_e32 v184, v185, v157
	v_cndmask_b32_e64 v157, v157, v184, s[6:7]
	ds_bpermute_b32 v184, v221, v159
	s_waitcnt lgkmcnt(1)
	v_mul_f32_e32 v185, v190, v188
	v_cndmask_b32_e64 v185, v185, -v185, s[4:5]
	v_pk_mul_f32 v[152:153], v[32:33], v[152:153]
	v_fmac_f32_e32 v185, v186, v158
	s_waitcnt lgkmcnt(0)
	v_mul_f32_e32 v184, v191, v184
	v_cndmask_b32_e64 v158, v158, v185, s[6:7]
	ds_bpermute_b32 v185, v221, v152
	v_cndmask_b32_e64 v184, v184, -v184, s[4:5]
	v_fmac_f32_e32 v184, v187, v159
	v_cndmask_b32_e64 v159, v159, v184, s[6:7]
	ds_bpermute_b32 v184, v221, v153
	s_waitcnt lgkmcnt(1)
	v_mul_f32_e32 v180, v180, v185
	v_cndmask_b32_e64 v180, v180, -v180, s[4:5]
	v_fmac_f32_e32 v180, v176, v152
	v_pk_mul_f32 v[154:155], v[34:35], v[154:155]
	s_waitcnt lgkmcnt(0)
	v_mul_f32_e32 v176, v181, v184
	v_cndmask_b32_e64 v176, v176, -v176, s[4:5]
	v_fmac_f32_e32 v176, v177, v153
	v_cndmask_b32_e64 v152, v152, v180, s[6:7]
	ds_bpermute_b32 v180, v221, v154
	v_cndmask_b32_e64 v153, v153, v176, s[6:7]
	ds_bpermute_b32 v176, v221, v155
	v_pk_mul_f32 v[148:149], v[44:45], v[148:149]
	v_pk_mul_f32 v[150:151], v[46:47], v[150:151]
	s_waitcnt lgkmcnt(1)
	v_mul_f32_e32 v177, v182, v180
	v_cndmask_b32_e64 v177, v177, -v177, s[4:5]
	s_waitcnt lgkmcnt(0)
	v_mul_f32_e32 v176, v183, v176
	v_cndmask_b32_e64 v176, v176, -v176, s[4:5]
	v_fmac_f32_e32 v177, v178, v154
	v_fmac_f32_e32 v176, v179, v155
	v_pk_mul_f32 v[144:145], v[40:41], v[144:145]
	v_pk_mul_f32 v[146:147], v[42:43], v[146:147]
	v_cndmask_b32_e64 v154, v154, v177, s[6:7]
	v_cndmask_b32_e64 v155, v155, v176, s[6:7]
	v_mov_b32_e32 v176, v218
	v_mov_b32_e32 v177, v218
	v_pk_mul_f32 v[158:159], v[176:177], v[158:159]
	v_pk_mul_f32 v[156:157], v[218:219], v[156:157]
	v_pk_mul_f32 v[154:155], v[176:177], v[154:155]
	v_pk_mul_f32 v[152:153], v[218:219], v[152:153]
	v_pk_mul_f32 v[150:151], v[176:177], v[150:151]
	v_pk_mul_f32 v[148:149], v[218:219], v[148:149]
	v_pk_mul_f32 v[146:147], v[176:177], v[146:147]
	v_pk_mul_f32 v[144:145], v[218:219], v[144:145]
.LBB0_789:
	v_cvt_pk_bf16_f32 v156, v156, v157
	v_cvt_pk_bf16_f32 v157, v158, v159
	v_cvt_pk_bf16_f32 v158, v152, v153
	v_fmamk_f32 v152, v217, 0x3a800000, v235
	v_mov_b64_e32 v[176:177], s[18:19]
	v_cvt_pk_bf16_f32 v148, v148, v149
	v_rsq_f32_e32 v152, v152
	v_cvt_pk_bf16_f32 v149, v150, v151
	v_mad_i64_i32 v[176:177], s[0:1], v220, s66, v[176:177]
	v_cvt_pk_bf16_f32 v159, v154, v155
	v_lshl_add_u64 v[176:177], s[44:45], 1, v[176:177]
	v_lshlrev_b32_e32 v202, 1, v204
	v_cvt_pk_bf16_f32 v151, v146, v147
	v_lshl_add_u64 v[176:177], v[176:177], 0, v[202:203]
	v_cvt_pk_bf16_f32 v150, v144, v145
	global_store_dwordx4 v[176:177], v[156:159], off
	global_store_dwordx4 v[176:177], v[148:151], off offset:64
	v_mov_b32_e32 v144, v152
	v_pk_fma_f32 v[142:143], v[142:143], v[144:145], v[50:51] op_sel_hi:[1,0,1]
	v_pk_fma_f32 v[140:141], v[140:141], v[144:145], v[48:49] op_sel_hi:[1,0,1]
	v_pk_fma_f32 v[138:139], v[138:139], v[144:145], v[58:59] op_sel_hi:[1,0,1]
	v_pk_fma_f32 v[136:137], v[136:137], v[144:145], v[56:57] op_sel_hi:[1,0,1]
	v_pk_fma_f32 v[134:135], v[134:135], v[144:145], v[66:67] op_sel_hi:[1,0,1]
	v_pk_fma_f32 v[132:133], v[132:133], v[144:145], v[64:65] op_sel_hi:[1,0,1]
	v_pk_fma_f32 v[130:131], v[130:131], v[144:145], v[70:71] op_sel_hi:[1,0,1]
	s_and_b64 vcc, exec, s[10:11]
	v_pk_fma_f32 v[128:129], v[128:129], v[144:145], v[68:69] op_sel_hi:[1,0,1]
	s_cbranch_vccnz .LBB0_791
	v_pk_mul_f32 v[144:145], v[142:143], v[142:143]
	v_pk_mul_f32 v[146:147], v[140:141], v[140:141]
	s_nop 0
	v_pk_mov_b32 v[148:149], v[146:147], v[144:145] op_sel:[1,0]
	v_mov_b32_e32 v147, v145
	v_pk_add_f32 v[144:145], v[148:149], v[146:147]
	v_pk_mul_f32 v[146:147], v[138:139], v[138:139]
	v_pk_add_f32 v[144:145], v[144:145], v[144:145] op_sel_hi:[0,1]
	v_pk_mul_f32 v[148:149], v[136:137], v[136:137]
	v_mul_f32_e32 v144, v132, v132
	v_pk_mov_b32 v[150:151], v[148:149], v[146:147] op_sel:[1,0]
	v_mov_b32_e32 v149, v147
	v_pk_add_f32 v[146:147], v[150:151], v[148:149]
	v_pk_fma_f32 v[148:149], v[132:133], v[132:133], v[144:145] op_sel_hi:[1,1,0]
	v_mul_f32_e32 v144, v134, v134
	v_pk_add_f32 v[146:147], v[146:147], v[146:147] op_sel_hi:[0,1]
	v_pk_fma_f32 v[150:151], v[134:135], v[134:135], v[144:145] op_sel_hi:[1,1,0]
	v_mul_f32_e32 v148, v128, v128
	v_mul_f32_e32 v150, v129, v129
	v_mul_f32_e32 v144, v130, v130
	v_mul_f32_e32 v146, v131, v131
	v_pk_add_f32 v[148:149], v[148:149], v[150:151]
	v_pk_add_f32 v[144:145], v[144:145], v[146:147]
	v_and_b32_e32 v146, 64, v238
	v_pk_add_f32 v[144:145], v[148:149], v[144:145]
	v_add_u32_e32 v146, 64, v146
	v_add_f32_e32 v144, v144, v145
	v_xor_b32_e32 v145, 16, v238
	v_cmp_lt_i32_e32 vcc, v145, v146
	s_nop 1
	v_cndmask_b32_e32 v145, v238, v145, vcc
	v_lshlrev_b32_e32 v145, 2, v145
	ds_bpermute_b32 v147, v145, v144
	s_waitcnt lgkmcnt(0)
	v_add_f32_e32 v144, v144, v147
	v_xor_b32_e32 v147, 32, v238
	v_cmp_lt_i32_e32 vcc, v147, v146
	s_nop 1
	v_cndmask_b32_e32 v146, v238, v147, vcc
	v_lshlrev_b32_e32 v146, 2, v146
	ds_bpermute_b32 v146, v146, v144
	s_waitcnt lgkmcnt(0)
	v_add_f32_e32 v144, v144, v146
	v_fmamk_f32 v144, v144, 0x3c800000, v235
	v_rsq_f32_e32 v144, v144
	s_nop 0
	v_pk_mul_f32 v[140:141], v[140:141], v[144:145] op_sel_hi:[1,0]
	v_pk_mul_f32 v[142:143], v[142:143], v[144:145] op_sel_hi:[1,0]
	v_pk_mul_f32 v[140:141], v[36:37], v[140:141]
	v_pk_mul_f32 v[136:137], v[136:137], v[144:145] op_sel_hi:[1,0]
	v_pk_mul_f32 v[138:139], v[138:139], v[144:145] op_sel_hi:[1,0]
	v_pk_mul_f32 v[134:135], v[134:135], v[144:145] op_sel_hi:[1,0]
	v_pk_mul_f32 v[132:133], v[132:133], v[144:145] op_sel_hi:[1,0]
	v_pk_mul_f32 v[130:131], v[130:131], v[144:145] op_sel_hi:[1,0]
	ds_bpermute_b32 v146, v145, v140
	v_pk_mul_f32 v[128:129], v[128:129], v[144:145] op_sel_hi:[1,0]
	ds_bpermute_b32 v144, v145, v141
	v_pk_mul_f32 v[142:143], v[38:39], v[142:143]
	v_pk_mul_f32 v[136:137], v[32:33], v[136:137]
	s_waitcnt lgkmcnt(1)
	v_mul_f32_e32 v146, v172, v146
	v_cndmask_b32_e64 v146, v146, -v146, s[4:5]
	s_waitcnt lgkmcnt(0)
	v_mul_f32_e32 v144, v173, v144
	v_cndmask_b32_e64 v144, v144, -v144, s[4:5]
	v_fmac_f32_e32 v146, v168, v140
	v_fmac_f32_e32 v144, v169, v141
	v_cndmask_b32_e64 v140, v140, v146, s[6:7]
	ds_bpermute_b32 v146, v145, v142
	v_cndmask_b32_e64 v141, v141, v144, s[6:7]
	ds_bpermute_b32 v144, v145, v143
	v_pk_mul_f32 v[138:139], v[34:35], v[138:139]
	v_pk_mul_f32 v[132:133], v[44:45], v[132:133]
	s_waitcnt lgkmcnt(1)
	v_mul_f32_e32 v146, v174, v146
	v_cndmask_b32_e64 v146, v146, -v146, s[4:5]
	s_waitcnt lgkmcnt(0)
	v_mul_f32_e32 v144, v175, v144
	v_cndmask_b32_e64 v144, v144, -v144, s[4:5]
	v_fmac_f32_e32 v146, v170, v142
	v_fmac_f32_e32 v144, v171, v143
	v_cndmask_b32_e64 v142, v142, v146, s[6:7]
	ds_bpermute_b32 v146, v145, v136
	v_cndmask_b32_e64 v143, v143, v144, s[6:7]
	ds_bpermute_b32 v144, v145, v137
	v_pk_mul_f32 v[134:135], v[46:47], v[134:135]
	v_pk_mul_f32 v[128:129], v[40:41], v[128:129]
	s_waitcnt lgkmcnt(1)
	v_mul_f32_e32 v146, v164, v146
	v_cndmask_b32_e64 v146, v146, -v146, s[4:5]
	s_waitcnt lgkmcnt(0)
	v_mul_f32_e32 v144, v165, v144
	v_cndmask_b32_e64 v144, v144, -v144, s[4:5]
	v_fmac_f32_e32 v146, v160, v136
	v_fmac_f32_e32 v144, v161, v137
	v_cndmask_b32_e64 v136, v136, v146, s[6:7]
	ds_bpermute_b32 v146, v145, v138
	v_cndmask_b32_e64 v137, v137, v144, s[6:7]
	ds_bpermute_b32 v144, v145, v139
	v_pk_mul_f32 v[130:131], v[42:43], v[130:131]
	v_pk_mul_f32 v[140:141], v[218:219], v[140:141]
	s_waitcnt lgkmcnt(1)
	v_mul_f32_e32 v145, v166, v146
	v_cndmask_b32_e64 v145, v145, -v145, s[4:5]
	s_waitcnt lgkmcnt(0)
	v_mul_f32_e32 v144, v167, v144
	v_cndmask_b32_e64 v144, v144, -v144, s[4:5]
	v_fmac_f32_e32 v145, v162, v138
	v_fmac_f32_e32 v144, v163, v139
	v_cndmask_b32_e64 v138, v138, v145, s[6:7]
	v_cndmask_b32_e64 v139, v139, v144, s[6:7]
	v_mov_b32_e32 v144, v218
	v_mov_b32_e32 v145, v218
	v_pk_mul_f32 v[142:143], v[144:145], v[142:143]
	v_pk_mul_f32 v[138:139], v[144:145], v[138:139]
	v_pk_mul_f32 v[136:137], v[218:219], v[136:137]
	v_pk_mul_f32 v[134:135], v[144:145], v[134:135]
	v_pk_mul_f32 v[132:133], v[218:219], v[132:133]
	v_pk_mul_f32 v[130:131], v[144:145], v[130:131]
	v_pk_mul_f32 v[128:129], v[218:219], v[128:129]

.LBB0_799:
	s_waitcnt vmcnt(1)
	v_fmamk_f32 v161, v166, 0x3a800000, v235
	v_rsq_f32_e32 v161, v161
	s_nop 0
	v_mov_b32_e32 v164, v161
	v_pk_fma_f32 v[126:127], v[126:127], v[164:165], v[50:51] op_sel_hi:[1,0,1]
	v_pk_fma_f32 v[124:125], v[124:125], v[164:165], v[48:49] op_sel_hi:[1,0,1]
	v_pk_fma_f32 v[122:123], v[122:123], v[164:165], v[58:59] op_sel_hi:[1,0,1]
	v_pk_fma_f32 v[120:121], v[120:121], v[164:165], v[56:57] op_sel_hi:[1,0,1]
	v_pk_fma_f32 v[118:119], v[118:119], v[164:165], v[66:67] op_sel_hi:[1,0,1]
	v_pk_fma_f32 v[116:117], v[116:117], v[164:165], v[64:65] op_sel_hi:[1,0,1]
	v_pk_fma_f32 v[114:115], v[114:115], v[164:165], v[70:71] op_sel_hi:[1,0,1]
	s_and_b64 vcc, exec, s[10:11]
	v_pk_fma_f32 v[112:113], v[112:113], v[164:165], v[68:69] op_sel_hi:[1,0,1]
	s_cbranch_vccnz .LBB0_801
	v_pk_mul_f32 v[164:165], v[126:127], v[126:127]
	v_pk_mul_f32 v[166:167], v[124:125], v[124:125]
	s_nop 0
	v_pk_mov_b32 v[168:169], v[166:167], v[164:165] op_sel:[1,0]
	v_mov_b32_e32 v167, v165
	v_pk_add_f32 v[164:165], v[168:169], v[166:167]
	v_pk_mul_f32 v[166:167], v[122:123], v[122:123]
	v_pk_add_f32 v[164:165], v[164:165], v[164:165] op_sel_hi:[0,1]
	v_pk_mul_f32 v[168:169], v[120:121], v[120:121]
	v_mul_f32_e32 v164, v116, v116
	v_pk_mov_b32 v[170:171], v[168:169], v[166:167] op_sel:[1,0]
	v_mov_b32_e32 v169, v167
	v_pk_add_f32 v[166:167], v[170:171], v[168:169]
	v_pk_fma_f32 v[168:169], v[116:117], v[116:117], v[164:165] op_sel_hi:[1,1,0]
	v_mul_f32_e32 v164, v118, v118
	v_pk_add_f32 v[166:167], v[166:167], v[166:167] op_sel_hi:[0,1]
	v_pk_fma_f32 v[170:171], v[118:119], v[118:119], v[164:165] op_sel_hi:[1,1,0]
	v_mul_f32_e32 v168, v112, v112
	v_mul_f32_e32 v170, v113, v113
	v_mul_f32_e32 v164, v114, v114
	v_mul_f32_e32 v166, v115, v115
	v_pk_add_f32 v[168:169], v[168:169], v[170:171]
	v_pk_add_f32 v[164:165], v[164:165], v[166:167]
	s_nop 0
	v_pk_add_f32 v[164:165], v[168:169], v[164:165]
	s_nop 0
	v_add_f32_e32 v161, v164, v165
	v_and_b32_e32 v165, 64, v238
	v_xor_b32_e32 v164, 16, v238
	v_add_u32_e32 v165, 64, v165
	v_cmp_lt_i32_e32 vcc, v164, v165
	s_nop 1
	v_cndmask_b32_e32 v164, v238, v164, vcc
	v_lshlrev_b32_e32 v166, 2, v164
	ds_bpermute_b32 v164, v166, v161
	s_waitcnt lgkmcnt(0)
	v_add_f32_e32 v161, v161, v164
	v_xor_b32_e32 v164, 32, v238
	v_cmp_lt_i32_e32 vcc, v164, v165
	s_nop 1
	v_cndmask_b32_e32 v164, v238, v164, vcc
	v_lshlrev_b32_e32 v164, 2, v164
	ds_bpermute_b32 v164, v164, v161
	s_waitcnt lgkmcnt(0)
	v_add_f32_e32 v161, v161, v164
	v_fmamk_f32 v161, v161, 0x3c800000, v235
	v_rsq_f32_e32 v161, v161
	s_nop 0
	v_mov_b32_e32 v164, v161
	v_pk_mul_f32 v[124:125], v[124:125], v[164:165] op_sel_hi:[1,0]
	v_pk_mul_f32 v[126:127], v[126:127], v[164:165] op_sel_hi:[1,0]
	v_pk_mul_f32 v[124:125], v[36:37], v[124:125]
	ds_bpermute_b32 v161, v166, v124
	v_pk_mul_f32 v[120:121], v[120:121], v[164:165] op_sel_hi:[1,0]
	v_pk_mul_f32 v[122:123], v[122:123], v[164:165] op_sel_hi:[1,0]
	v_pk_mul_f32 v[118:119], v[118:119], v[164:165] op_sel_hi:[1,0]
	v_pk_mul_f32 v[116:117], v[116:117], v[164:165] op_sel_hi:[1,0]
	v_pk_mul_f32 v[114:115], v[114:115], v[164:165] op_sel_hi:[1,0]
	v_pk_mul_f32 v[112:113], v[112:113], v[164:165] op_sel_hi:[1,0]
	ds_bpermute_b32 v164, v166, v125
	s_waitcnt lgkmcnt(1)
	v_mul_f32_e32 v156, v156, v161
	v_cndmask_b32_e64 v156, v156, -v156, s[4:5]
	v_pk_mul_f32 v[126:127], v[38:39], v[126:127]
	v_fmac_f32_e32 v156, v152, v124
	s_waitcnt lgkmcnt(0)
	v_mul_f32_e32 v152, v157, v164
	v_cndmask_b32_e64 v124, v124, v156, s[6:7]
	ds_bpermute_b32 v156, v166, v126
	v_cndmask_b32_e64 v152, v152, -v152, s[4:5]
	v_fmac_f32_e32 v152, v153, v125
	v_cndmask_b32_e64 v125, v125, v152, s[6:7]
	ds_bpermute_b32 v152, v166, v127
	s_waitcnt lgkmcnt(1)
	v_mul_f32_e32 v153, v158, v156
	v_cndmask_b32_e64 v153, v153, -v153, s[4:5]
	v_pk_mul_f32 v[120:121], v[32:33], v[120:121]
	v_fmac_f32_e32 v153, v154, v126
	s_waitcnt lgkmcnt(0)
	v_mul_f32_e32 v152, v159, v152
	v_cndmask_b32_e64 v126, v126, v153, s[6:7]
	ds_bpermute_b32 v153, v166, v120
	v_cndmask_b32_e64 v152, v152, -v152, s[4:5]
	v_fmac_f32_e32 v152, v155, v127
	v_cndmask_b32_e64 v127, v127, v152, s[6:7]
	ds_bpermute_b32 v152, v166, v121
	s_waitcnt lgkmcnt(1)
	v_mul_f32_e32 v148, v148, v153
	v_cndmask_b32_e64 v148, v148, -v148, s[4:5]
	v_fmac_f32_e32 v148, v144, v120
	v_pk_mul_f32 v[122:123], v[34:35], v[122:123]
	s_waitcnt lgkmcnt(0)
	v_mul_f32_e32 v144, v149, v152
	v_cndmask_b32_e64 v144, v144, -v144, s[4:5]
	v_fmac_f32_e32 v144, v145, v121
	v_cndmask_b32_e64 v120, v120, v148, s[6:7]
	ds_bpermute_b32 v148, v166, v122
	v_cndmask_b32_e64 v121, v121, v144, s[6:7]
	ds_bpermute_b32 v144, v166, v123
	v_pk_mul_f32 v[116:117], v[44:45], v[116:117]
	v_pk_mul_f32 v[118:119], v[46:47], v[118:119]
	s_waitcnt lgkmcnt(1)
	v_mul_f32_e32 v145, v150, v148
	v_cndmask_b32_e64 v145, v145, -v145, s[4:5]
	s_waitcnt lgkmcnt(0)
	v_mul_f32_e32 v144, v151, v144
	v_cndmask_b32_e64 v144, v144, -v144, s[4:5]
	v_fmac_f32_e32 v145, v146, v122
	v_fmac_f32_e32 v144, v147, v123
	v_pk_mul_f32 v[112:113], v[40:41], v[112:113]
	v_pk_mul_f32 v[114:115], v[42:43], v[114:115]
	v_cndmask_b32_e64 v122, v122, v145, s[6:7]
	v_cndmask_b32_e64 v123, v123, v144, s[6:7]
	v_mov_b32_e32 v144, v218
	v_mov_b32_e32 v145, v218
	v_pk_mul_f32 v[126:127], v[144:145], v[126:127]
	v_pk_mul_f32 v[124:125], v[218:219], v[124:125]
	v_pk_mul_f32 v[122:123], v[144:145], v[122:123]
	v_pk_mul_f32 v[120:121], v[218:219], v[120:121]
	v_pk_mul_f32 v[118:119], v[144:145], v[118:119]
	v_pk_mul_f32 v[116:117], v[218:219], v[116:117]
	v_pk_mul_f32 v[114:115], v[144:145], v[114:115]
	v_pk_mul_f32 v[112:113], v[218:219], v[112:113]
.LBB0_801:
	v_cvt_pk_bf16_f32 v124, v124, v125
	v_cvt_pk_bf16_f32 v125, v126, v127
	v_cvt_pk_bf16_f32 v126, v120, v121
	s_waitcnt vmcnt(0)
	v_fmamk_f32 v120, v163, 0x3a800000, v235
	v_mov_b64_e32 v[144:145], s[18:19]
	v_cvt_pk_bf16_f32 v116, v116, v117
	v_rsq_f32_e32 v120, v120
	v_cvt_pk_bf16_f32 v117, v118, v119
	v_mad_i64_i32 v[144:145], s[0:1], v162, s66, v[144:145]
	v_cvt_pk_bf16_f32 v127, v122, v123
	v_lshl_add_u64 v[144:145], s[44:45], 1, v[144:145]
	v_lshl_add_u64 v[144:145], v[144:145], 0, v[202:203]
	v_cvt_pk_bf16_f32 v119, v114, v115
	global_store_dwordx4 v[144:145], v[124:127], off
	v_cvt_pk_bf16_f32 v118, v112, v113
	global_store_dwordx4 v[144:145], v[116:119], off offset:64
	v_mov_b32_e32 v112, v120
	v_pk_fma_f32 v[110:111], v[110:111], v[112:113], v[50:51] op_sel_hi:[1,0,1]
	v_pk_fma_f32 v[108:109], v[108:109], v[112:113], v[48:49] op_sel_hi:[1,0,1]
	v_pk_fma_f32 v[106:107], v[106:107], v[112:113], v[58:59] op_sel_hi:[1,0,1]
	v_pk_fma_f32 v[104:105], v[104:105], v[112:113], v[56:57] op_sel_hi:[1,0,1]
	v_pk_fma_f32 v[102:103], v[102:103], v[112:113], v[66:67] op_sel_hi:[1,0,1]
	v_pk_fma_f32 v[100:101], v[100:101], v[112:113], v[64:65] op_sel_hi:[1,0,1]
	v_pk_fma_f32 v[98:99], v[98:99], v[112:113], v[70:71] op_sel_hi:[1,0,1]
	s_and_b64 vcc, exec, s[10:11]
	v_pk_fma_f32 v[96:97], v[96:97], v[112:113], v[68:69] op_sel_hi:[1,0,1]
	s_cbranch_vccnz .LBB0_803
	v_pk_mul_f32 v[112:113], v[110:111], v[110:111]
	v_pk_mul_f32 v[114:115], v[108:109], v[108:109]
	s_nop 0
	v_pk_mov_b32 v[116:117], v[114:115], v[112:113] op_sel:[1,0]
	v_mov_b32_e32 v115, v113
	v_pk_add_f32 v[112:113], v[116:117], v[114:115]
	v_pk_mul_f32 v[114:115], v[106:107], v[106:107]
	v_pk_add_f32 v[112:113], v[112:113], v[112:113] op_sel_hi:[0,1]
	v_pk_mul_f32 v[116:117], v[104:105], v[104:105]
	v_mul_f32_e32 v112, v100, v100
	v_pk_mov_b32 v[118:119], v[116:117], v[114:115] op_sel:[1,0]
	v_mov_b32_e32 v117, v115
	v_pk_add_f32 v[114:115], v[118:119], v[116:117]
	v_pk_fma_f32 v[116:117], v[100:101], v[100:101], v[112:113] op_sel_hi:[1,1,0]
	v_mul_f32_e32 v112, v102, v102
	v_pk_add_f32 v[114:115], v[114:115], v[114:115] op_sel_hi:[0,1]
	v_pk_fma_f32 v[118:119], v[102:103], v[102:103], v[112:113] op_sel_hi:[1,1,0]
	v_mul_f32_e32 v116, v96, v96
	v_mul_f32_e32 v118, v97, v97
	v_mul_f32_e32 v112, v98, v98
	v_mul_f32_e32 v114, v99, v99
	v_pk_add_f32 v[116:117], v[116:117], v[118:119]
	v_pk_add_f32 v[112:113], v[112:113], v[114:115]
	v_and_b32_e32 v114, 64, v238
	v_pk_add_f32 v[112:113], v[116:117], v[112:113]
	v_add_u32_e32 v114, 64, v114
	v_add_f32_e32 v112, v112, v113
	v_xor_b32_e32 v113, 16, v238
	v_cmp_lt_i32_e32 vcc, v113, v114
	s_nop 1
	v_cndmask_b32_e32 v113, v238, v113, vcc
	v_lshlrev_b32_e32 v113, 2, v113
	ds_bpermute_b32 v115, v113, v112
	s_waitcnt lgkmcnt(0)
	v_add_f32_e32 v112, v112, v115
	v_xor_b32_e32 v115, 32, v238
	v_cmp_lt_i32_e32 vcc, v115, v114
	s_nop 1
	v_cndmask_b32_e32 v114, v238, v115, vcc
	v_lshlrev_b32_e32 v114, 2, v114
	ds_bpermute_b32 v114, v114, v112
	s_waitcnt lgkmcnt(0)
	v_add_f32_e32 v112, v112, v114
	v_fmamk_f32 v112, v112, 0x3c800000, v235
	v_rsq_f32_e32 v112, v112
	s_nop 0
	v_pk_mul_f32 v[108:109], v[108:109], v[112:113] op_sel_hi:[1,0]
	v_pk_mul_f32 v[110:111], v[110:111], v[112:113] op_sel_hi:[1,0]
	v_pk_mul_f32 v[108:109], v[36:37], v[108:109]
	v_pk_mul_f32 v[104:105], v[104:105], v[112:113] op_sel_hi:[1,0]
	v_pk_mul_f32 v[106:107], v[106:107], v[112:113] op_sel_hi:[1,0]
	v_pk_mul_f32 v[102:103], v[102:103], v[112:113] op_sel_hi:[1,0]
	v_pk_mul_f32 v[100:101], v[100:101], v[112:113] op_sel_hi:[1,0]
	v_pk_mul_f32 v[98:99], v[98:99], v[112:113] op_sel_hi:[1,0]
	ds_bpermute_b32 v114, v113, v108
	v_pk_mul_f32 v[96:97], v[96:97], v[112:113] op_sel_hi:[1,0]
	ds_bpermute_b32 v112, v113, v109
	v_pk_mul_f32 v[110:111], v[38:39], v[110:111]
	v_pk_mul_f32 v[104:105], v[32:33], v[104:105]
	s_waitcnt lgkmcnt(1)
	v_mul_f32_e32 v114, v140, v114
	v_cndmask_b32_e64 v114, v114, -v114, s[4:5]
	s_waitcnt lgkmcnt(0)
	v_mul_f32_e32 v112, v141, v112
	v_cndmask_b32_e64 v112, v112, -v112, s[4:5]
	v_fmac_f32_e32 v114, v136, v108
	v_fmac_f32_e32 v112, v137, v109
	v_cndmask_b32_e64 v108, v108, v114, s[6:7]
	ds_bpermute_b32 v114, v113, v110
	v_cndmask_b32_e64 v109, v109, v112, s[6:7]
	ds_bpermute_b32 v112, v113, v111
	v_pk_mul_f32 v[106:107], v[34:35], v[106:107]
	v_pk_mul_f32 v[100:101], v[44:45], v[100:101]
	s_waitcnt lgkmcnt(1)
	v_mul_f32_e32 v114, v142, v114
	v_cndmask_b32_e64 v114, v114, -v114, s[4:5]
	s_waitcnt lgkmcnt(0)
	v_mul_f32_e32 v112, v143, v112
	v_cndmask_b32_e64 v112, v112, -v112, s[4:5]
	v_fmac_f32_e32 v114, v138, v110
	v_fmac_f32_e32 v112, v139, v111
	v_cndmask_b32_e64 v110, v110, v114, s[6:7]
	ds_bpermute_b32 v114, v113, v104
	v_cndmask_b32_e64 v111, v111, v112, s[6:7]
	ds_bpermute_b32 v112, v113, v105
	v_pk_mul_f32 v[102:103], v[46:47], v[102:103]
	v_pk_mul_f32 v[96:97], v[40:41], v[96:97]
	s_waitcnt lgkmcnt(1)
	v_mul_f32_e32 v114, v132, v114
	v_cndmask_b32_e64 v114, v114, -v114, s[4:5]
	s_waitcnt lgkmcnt(0)
	v_mul_f32_e32 v112, v133, v112
	v_cndmask_b32_e64 v112, v112, -v112, s[4:5]
	v_fmac_f32_e32 v114, v128, v104
	v_fmac_f32_e32 v112, v129, v105
	v_cndmask_b32_e64 v104, v104, v114, s[6:7]
	ds_bpermute_b32 v114, v113, v106
	v_cndmask_b32_e64 v105, v105, v112, s[6:7]
	ds_bpermute_b32 v112, v113, v107
	v_pk_mul_f32 v[98:99], v[42:43], v[98:99]
	v_pk_mul_f32 v[108:109], v[218:219], v[108:109]
	s_waitcnt lgkmcnt(1)
	v_mul_f32_e32 v113, v134, v114
	v_cndmask_b32_e64 v113, v113, -v113, s[4:5]
	s_waitcnt lgkmcnt(0)
	v_mul_f32_e32 v112, v135, v112
	v_cndmask_b32_e64 v112, v112, -v112, s[4:5]
	v_fmac_f32_e32 v113, v130, v106
	v_fmac_f32_e32 v112, v131, v107
	v_cndmask_b32_e64 v106, v106, v113, s[6:7]
	v_cndmask_b32_e64 v107, v107, v112, s[6:7]
	v_mov_b32_e32 v112, v218
	v_mov_b32_e32 v113, v218
	v_pk_mul_f32 v[110:111], v[112:113], v[110:111]
	v_pk_mul_f32 v[106:107], v[112:113], v[106:107]
	v_pk_mul_f32 v[104:105], v[218:219], v[104:105]
	v_pk_mul_f32 v[102:103], v[112:113], v[102:103]
	v_pk_mul_f32 v[100:101], v[218:219], v[100:101]
	v_pk_mul_f32 v[98:99], v[112:113], v[98:99]
	v_pk_mul_f32 v[96:97], v[218:219], v[96:97]

.LBB0_811:
	s_waitcnt vmcnt(1)
	v_fmamk_f32 v129, v134, 0x3a800000, v235
	v_rsq_f32_e32 v129, v129
	s_nop 0
	v_mov_b32_e32 v132, v129
	v_pk_fma_f32 v[94:95], v[94:95], v[132:133], v[50:51] op_sel_hi:[1,0,1]
	v_pk_fma_f32 v[92:93], v[92:93], v[132:133], v[48:49] op_sel_hi:[1,0,1]
	v_pk_fma_f32 v[90:91], v[90:91], v[132:133], v[58:59] op_sel_hi:[1,0,1]
	v_pk_fma_f32 v[88:89], v[88:89], v[132:133], v[56:57] op_sel_hi:[1,0,1]
	v_pk_fma_f32 v[86:87], v[86:87], v[132:133], v[66:67] op_sel_hi:[1,0,1]
	v_pk_fma_f32 v[84:85], v[84:85], v[132:133], v[64:65] op_sel_hi:[1,0,1]
	v_pk_fma_f32 v[82:83], v[82:83], v[132:133], v[70:71] op_sel_hi:[1,0,1]
	s_and_b64 vcc, exec, s[10:11]
	v_pk_fma_f32 v[80:81], v[80:81], v[132:133], v[68:69] op_sel_hi:[1,0,1]
	s_cbranch_vccnz .LBB0_813
	v_pk_mul_f32 v[132:133], v[94:95], v[94:95]
	v_pk_mul_f32 v[134:135], v[92:93], v[92:93]
	s_nop 0
	v_pk_mov_b32 v[136:137], v[134:135], v[132:133] op_sel:[1,0]
	v_mov_b32_e32 v135, v133
	v_pk_add_f32 v[132:133], v[136:137], v[134:135]
	v_pk_mul_f32 v[134:135], v[90:91], v[90:91]
	v_pk_add_f32 v[132:133], v[132:133], v[132:133] op_sel_hi:[0,1]
	v_pk_mul_f32 v[136:137], v[88:89], v[88:89]
	v_mul_f32_e32 v132, v84, v84
	v_pk_mov_b32 v[138:139], v[136:137], v[134:135] op_sel:[1,0]
	v_mov_b32_e32 v137, v135
	v_pk_add_f32 v[134:135], v[138:139], v[136:137]
	v_pk_fma_f32 v[136:137], v[84:85], v[84:85], v[132:133] op_sel_hi:[1,1,0]
	v_mul_f32_e32 v132, v86, v86
	v_pk_add_f32 v[134:135], v[134:135], v[134:135] op_sel_hi:[0,1]
	v_pk_fma_f32 v[138:139], v[86:87], v[86:87], v[132:133] op_sel_hi:[1,1,0]
	v_mul_f32_e32 v136, v80, v80
	v_mul_f32_e32 v138, v81, v81
	v_mul_f32_e32 v132, v82, v82
	v_mul_f32_e32 v134, v83, v83
	v_pk_add_f32 v[136:137], v[136:137], v[138:139]
	v_pk_add_f32 v[132:133], v[132:133], v[134:135]
	s_nop 0
	v_pk_add_f32 v[132:133], v[136:137], v[132:133]
	s_nop 0
	v_add_f32_e32 v129, v132, v133
	v_and_b32_e32 v133, 64, v238
	v_xor_b32_e32 v132, 16, v238
	v_add_u32_e32 v133, 64, v133
	v_cmp_lt_i32_e32 vcc, v132, v133
	s_nop 1
	v_cndmask_b32_e32 v132, v238, v132, vcc
	v_lshlrev_b32_e32 v134, 2, v132
	ds_bpermute_b32 v132, v134, v129
	s_waitcnt lgkmcnt(0)
	v_add_f32_e32 v129, v129, v132
	v_xor_b32_e32 v132, 32, v238
	v_cmp_lt_i32_e32 vcc, v132, v133
	s_nop 1
	v_cndmask_b32_e32 v132, v238, v132, vcc
	v_lshlrev_b32_e32 v132, 2, v132
	ds_bpermute_b32 v132, v132, v129
	s_waitcnt lgkmcnt(0)
	v_add_f32_e32 v129, v129, v132
	v_fmamk_f32 v129, v129, 0x3c800000, v235
	v_rsq_f32_e32 v129, v129
	s_nop 0
	v_mov_b32_e32 v132, v129
	v_pk_mul_f32 v[92:93], v[92:93], v[132:133] op_sel_hi:[1,0]
	v_pk_mul_f32 v[94:95], v[94:95], v[132:133] op_sel_hi:[1,0]
	v_pk_mul_f32 v[92:93], v[36:37], v[92:93]
	ds_bpermute_b32 v129, v134, v92
	v_pk_mul_f32 v[88:89], v[88:89], v[132:133] op_sel_hi:[1,0]
	v_pk_mul_f32 v[90:91], v[90:91], v[132:133] op_sel_hi:[1,0]
	v_pk_mul_f32 v[86:87], v[86:87], v[132:133] op_sel_hi:[1,0]
	v_pk_mul_f32 v[84:85], v[84:85], v[132:133] op_sel_hi:[1,0]
	v_pk_mul_f32 v[82:83], v[82:83], v[132:133] op_sel_hi:[1,0]
	v_pk_mul_f32 v[80:81], v[80:81], v[132:133] op_sel_hi:[1,0]
	ds_bpermute_b32 v132, v134, v93
	s_waitcnt lgkmcnt(1)
	v_mul_f32_e32 v124, v124, v129
	v_cndmask_b32_e64 v124, v124, -v124, s[4:5]
	v_pk_mul_f32 v[94:95], v[38:39], v[94:95]
	v_fmac_f32_e32 v124, v120, v92
	s_waitcnt lgkmcnt(0)
	v_mul_f32_e32 v120, v125, v132
	v_cndmask_b32_e64 v92, v92, v124, s[6:7]
	ds_bpermute_b32 v124, v134, v94
	v_cndmask_b32_e64 v120, v120, -v120, s[4:5]
	v_fmac_f32_e32 v120, v121, v93
	v_cndmask_b32_e64 v93, v93, v120, s[6:7]
	ds_bpermute_b32 v120, v134, v95
	s_waitcnt lgkmcnt(1)
	v_mul_f32_e32 v121, v126, v124
	v_cndmask_b32_e64 v121, v121, -v121, s[4:5]
	v_pk_mul_f32 v[88:89], v[32:33], v[88:89]
	v_fmac_f32_e32 v121, v122, v94
	s_waitcnt lgkmcnt(0)
	v_mul_f32_e32 v120, v127, v120
	v_cndmask_b32_e64 v94, v94, v121, s[6:7]
	ds_bpermute_b32 v121, v134, v88
	v_cndmask_b32_e64 v120, v120, -v120, s[4:5]
	v_fmac_f32_e32 v120, v123, v95
	v_cndmask_b32_e64 v95, v95, v120, s[6:7]
	ds_bpermute_b32 v120, v134, v89
	s_waitcnt lgkmcnt(1)
	v_mul_f32_e32 v116, v116, v121
	v_cndmask_b32_e64 v116, v116, -v116, s[4:5]
	v_fmac_f32_e32 v116, v112, v88
	v_pk_mul_f32 v[90:91], v[34:35], v[90:91]
	s_waitcnt lgkmcnt(0)
	v_mul_f32_e32 v112, v117, v120
	v_cndmask_b32_e64 v112, v112, -v112, s[4:5]
	v_fmac_f32_e32 v112, v113, v89
	v_cndmask_b32_e64 v88, v88, v116, s[6:7]
	ds_bpermute_b32 v116, v134, v90
	v_cndmask_b32_e64 v89, v89, v112, s[6:7]
	ds_bpermute_b32 v112, v134, v91
	v_pk_mul_f32 v[84:85], v[44:45], v[84:85]
	v_pk_mul_f32 v[86:87], v[46:47], v[86:87]
	s_waitcnt lgkmcnt(1)
	v_mul_f32_e32 v113, v118, v116
	v_cndmask_b32_e64 v113, v113, -v113, s[4:5]
	s_waitcnt lgkmcnt(0)
	v_mul_f32_e32 v112, v119, v112
	v_cndmask_b32_e64 v112, v112, -v112, s[4:5]
	v_fmac_f32_e32 v113, v114, v90
	v_fmac_f32_e32 v112, v115, v91
	v_pk_mul_f32 v[80:81], v[40:41], v[80:81]
	v_pk_mul_f32 v[82:83], v[42:43], v[82:83]
	v_cndmask_b32_e64 v90, v90, v113, s[6:7]
	v_cndmask_b32_e64 v91, v91, v112, s[6:7]
	v_mov_b32_e32 v112, v218
	v_mov_b32_e32 v113, v218
	v_pk_mul_f32 v[94:95], v[112:113], v[94:95]
	v_pk_mul_f32 v[92:93], v[218:219], v[92:93]
	v_pk_mul_f32 v[90:91], v[112:113], v[90:91]
	v_pk_mul_f32 v[88:89], v[218:219], v[88:89]
	v_pk_mul_f32 v[86:87], v[112:113], v[86:87]
	v_pk_mul_f32 v[84:85], v[218:219], v[84:85]
	v_pk_mul_f32 v[82:83], v[112:113], v[82:83]
	v_pk_mul_f32 v[80:81], v[218:219], v[80:81]
.LBB0_813:
	v_cvt_pk_bf16_f32 v92, v92, v93
	v_cvt_pk_bf16_f32 v93, v94, v95
	v_cvt_pk_bf16_f32 v94, v88, v89
	s_waitcnt vmcnt(0)
	v_fmamk_f32 v88, v131, 0x3a800000, v235
	v_mov_b64_e32 v[112:113], s[18:19]
	v_cvt_pk_bf16_f32 v84, v84, v85
	v_rsq_f32_e32 v88, v88
	v_cvt_pk_bf16_f32 v85, v86, v87
	v_mad_i64_i32 v[112:113], s[0:1], v130, s66, v[112:113]
	v_cvt_pk_bf16_f32 v95, v90, v91
	v_lshl_add_u64 v[112:113], s[44:45], 1, v[112:113]
	v_lshl_add_u64 v[112:113], v[112:113], 0, v[202:203]
	v_cvt_pk_bf16_f32 v87, v82, v83
	global_store_dwordx4 v[112:113], v[92:95], off
	v_cvt_pk_bf16_f32 v86, v80, v81
	global_store_dwordx4 v[112:113], v[84:87], off offset:64
	v_mov_b32_e32 v80, v88
	v_pk_fma_f32 v[78:79], v[78:79], v[80:81], v[50:51] op_sel_hi:[1,0,1]
	v_pk_fma_f32 v[76:77], v[76:77], v[80:81], v[48:49] op_sel_hi:[1,0,1]
	v_pk_fma_f32 v[74:75], v[74:75], v[80:81], v[58:59] op_sel_hi:[1,0,1]
	v_pk_fma_f32 v[72:73], v[72:73], v[80:81], v[56:57] op_sel_hi:[1,0,1]
	v_pk_fma_f32 v[62:63], v[62:63], v[80:81], v[66:67] op_sel_hi:[1,0,1]
	v_pk_fma_f32 v[60:61], v[60:61], v[80:81], v[64:65] op_sel_hi:[1,0,1]
	v_pk_fma_f32 v[54:55], v[54:55], v[80:81], v[70:71] op_sel_hi:[1,0,1]
	s_and_b64 vcc, exec, s[10:11]
	v_pk_fma_f32 v[52:53], v[52:53], v[80:81], v[68:69] op_sel_hi:[1,0,1]
	s_cbranch_vccnz .LBB0_815
	v_pk_mul_f32 v[80:81], v[78:79], v[78:79]
	v_pk_mul_f32 v[82:83], v[76:77], v[76:77]
	s_nop 0
	v_pk_mov_b32 v[84:85], v[82:83], v[80:81] op_sel:[1,0]
	v_mov_b32_e32 v83, v81
	v_pk_add_f32 v[80:81], v[84:85], v[82:83]
	v_pk_mul_f32 v[82:83], v[74:75], v[74:75]
	v_pk_add_f32 v[80:81], v[80:81], v[80:81] op_sel_hi:[0,1]
	v_pk_mul_f32 v[84:85], v[72:73], v[72:73]
	v_mul_f32_e32 v80, v60, v60
	v_pk_mov_b32 v[86:87], v[84:85], v[82:83] op_sel:[1,0]
	v_mov_b32_e32 v85, v83
	v_pk_add_f32 v[82:83], v[86:87], v[84:85]
	v_pk_fma_f32 v[84:85], v[60:61], v[60:61], v[80:81] op_sel_hi:[1,1,0]
	v_mul_f32_e32 v80, v62, v62
	v_pk_add_f32 v[82:83], v[82:83], v[82:83] op_sel_hi:[0,1]
	v_pk_fma_f32 v[86:87], v[62:63], v[62:63], v[80:81] op_sel_hi:[1,1,0]
	v_mul_f32_e32 v84, v52, v52
	v_mul_f32_e32 v86, v53, v53
	v_mul_f32_e32 v80, v54, v54
	v_mul_f32_e32 v82, v55, v55
	v_pk_add_f32 v[84:85], v[84:85], v[86:87]
	v_pk_add_f32 v[80:81], v[80:81], v[82:83]
	v_and_b32_e32 v82, 64, v238
	v_pk_add_f32 v[80:81], v[84:85], v[80:81]
	v_add_u32_e32 v82, 64, v82
	v_add_f32_e32 v80, v80, v81
	v_xor_b32_e32 v81, 16, v238
	v_cmp_lt_i32_e32 vcc, v81, v82
	s_nop 1
	v_cndmask_b32_e32 v81, v238, v81, vcc
	v_lshlrev_b32_e32 v81, 2, v81
	ds_bpermute_b32 v83, v81, v80
	s_waitcnt lgkmcnt(0)
	v_add_f32_e32 v80, v80, v83
	v_xor_b32_e32 v83, 32, v238
	v_cmp_lt_i32_e32 vcc, v83, v82
	s_nop 1
	v_cndmask_b32_e32 v82, v238, v83, vcc
	v_lshlrev_b32_e32 v82, 2, v82
	ds_bpermute_b32 v82, v82, v80
	s_waitcnt lgkmcnt(0)
	v_add_f32_e32 v80, v80, v82
	v_fmamk_f32 v80, v80, 0x3c800000, v235
	v_rsq_f32_e32 v80, v80
	s_nop 0
	v_pk_mul_f32 v[76:77], v[76:77], v[80:81] op_sel_hi:[1,0]
	v_pk_mul_f32 v[78:79], v[78:79], v[80:81] op_sel_hi:[1,0]
	v_pk_mul_f32 v[76:77], v[36:37], v[76:77]
	v_pk_mul_f32 v[72:73], v[72:73], v[80:81] op_sel_hi:[1,0]
	v_pk_mul_f32 v[74:75], v[74:75], v[80:81] op_sel_hi:[1,0]
	v_pk_mul_f32 v[62:63], v[62:63], v[80:81] op_sel_hi:[1,0]
	v_pk_mul_f32 v[60:61], v[60:61], v[80:81] op_sel_hi:[1,0]
	v_pk_mul_f32 v[54:55], v[54:55], v[80:81] op_sel_hi:[1,0]
	ds_bpermute_b32 v82, v81, v76
	v_pk_mul_f32 v[52:53], v[52:53], v[80:81] op_sel_hi:[1,0]
	ds_bpermute_b32 v80, v81, v77
	v_pk_mul_f32 v[78:79], v[38:39], v[78:79]
	v_pk_mul_f32 v[72:73], v[32:33], v[72:73]
	s_waitcnt lgkmcnt(1)
	v_mul_f32_e32 v82, v108, v82
	v_cndmask_b32_e64 v82, v82, -v82, s[4:5]
	s_waitcnt lgkmcnt(0)
	v_mul_f32_e32 v80, v109, v80
	v_cndmask_b32_e64 v80, v80, -v80, s[4:5]
	v_fmac_f32_e32 v82, v104, v76
	v_fmac_f32_e32 v80, v105, v77
	v_cndmask_b32_e64 v76, v76, v82, s[6:7]
	ds_bpermute_b32 v82, v81, v78
	v_cndmask_b32_e64 v77, v77, v80, s[6:7]
	ds_bpermute_b32 v80, v81, v79
	v_pk_mul_f32 v[74:75], v[34:35], v[74:75]
	v_pk_mul_f32 v[60:61], v[44:45], v[60:61]
	s_waitcnt lgkmcnt(1)
	v_mul_f32_e32 v82, v110, v82
	v_cndmask_b32_e64 v82, v82, -v82, s[4:5]
	s_waitcnt lgkmcnt(0)
	v_mul_f32_e32 v80, v111, v80
	v_cndmask_b32_e64 v80, v80, -v80, s[4:5]
	v_fmac_f32_e32 v82, v106, v78
	v_fmac_f32_e32 v80, v107, v79
	v_cndmask_b32_e64 v78, v78, v82, s[6:7]
	ds_bpermute_b32 v82, v81, v72
	v_cndmask_b32_e64 v79, v79, v80, s[6:7]
	ds_bpermute_b32 v80, v81, v73
	v_pk_mul_f32 v[62:63], v[46:47], v[62:63]
	v_pk_mul_f32 v[52:53], v[40:41], v[52:53]
	s_waitcnt lgkmcnt(1)
	v_mul_f32_e32 v82, v100, v82
	v_cndmask_b32_e64 v82, v82, -v82, s[4:5]
	s_waitcnt lgkmcnt(0)
	v_mul_f32_e32 v80, v101, v80
	v_cndmask_b32_e64 v80, v80, -v80, s[4:5]
	v_fmac_f32_e32 v82, v96, v72
	v_fmac_f32_e32 v80, v97, v73
	v_cndmask_b32_e64 v72, v72, v82, s[6:7]
	ds_bpermute_b32 v82, v81, v74
	v_cndmask_b32_e64 v73, v73, v80, s[6:7]
	ds_bpermute_b32 v80, v81, v75
	v_pk_mul_f32 v[54:55], v[42:43], v[54:55]
	v_pk_mul_f32 v[76:77], v[218:219], v[76:77]
	s_waitcnt lgkmcnt(1)
	v_mul_f32_e32 v81, v102, v82
	v_cndmask_b32_e64 v81, v81, -v81, s[4:5]
	s_waitcnt lgkmcnt(0)
	v_mul_f32_e32 v80, v103, v80
	v_cndmask_b32_e64 v80, v80, -v80, s[4:5]
	v_fmac_f32_e32 v81, v98, v74
	v_fmac_f32_e32 v80, v99, v75
	v_cndmask_b32_e64 v74, v74, v81, s[6:7]
	v_cndmask_b32_e64 v75, v75, v80, s[6:7]
	v_mov_b32_e32 v80, v218
	v_mov_b32_e32 v81, v218
	v_pk_mul_f32 v[78:79], v[80:81], v[78:79]
	v_pk_mul_f32 v[74:75], v[80:81], v[74:75]
	v_pk_mul_f32 v[72:73], v[218:219], v[72:73]
	v_pk_mul_f32 v[62:63], v[80:81], v[62:63]
	v_pk_mul_f32 v[60:61], v[218:219], v[60:61]
	v_pk_mul_f32 v[54:55], v[80:81], v[54:55]
	v_pk_mul_f32 v[52:53], v[218:219], v[52:53]

.LBB0_823:
	s_waitcnt vmcnt(1)
	v_fmamk_f32 v97, v102, 0x3a800000, v235
	v_rsq_f32_e32 v97, v97
	s_nop 0
	v_mov_b32_e32 v100, v97
	v_pk_fma_f32 v[30:31], v[30:31], v[100:101], v[50:51] op_sel_hi:[1,0,1]
	v_pk_fma_f32 v[28:29], v[28:29], v[100:101], v[48:49] op_sel_hi:[1,0,1]
	v_pk_fma_f32 v[26:27], v[26:27], v[100:101], v[58:59] op_sel_hi:[1,0,1]
	v_pk_fma_f32 v[24:25], v[24:25], v[100:101], v[56:57] op_sel_hi:[1,0,1]
	v_pk_fma_f32 v[22:23], v[22:23], v[100:101], v[66:67] op_sel_hi:[1,0,1]
	v_pk_fma_f32 v[20:21], v[20:21], v[100:101], v[64:65] op_sel_hi:[1,0,1]
	v_pk_fma_f32 v[18:19], v[18:19], v[100:101], v[70:71] op_sel_hi:[1,0,1]
	s_and_b64 vcc, exec, s[10:11]
	v_pk_fma_f32 v[16:17], v[16:17], v[100:101], v[68:69] op_sel_hi:[1,0,1]
	s_cbranch_vccnz .LBB0_825
	v_pk_mul_f32 v[100:101], v[30:31], v[30:31]
	v_pk_mul_f32 v[102:103], v[28:29], v[28:29]
	s_nop 0
	v_pk_mov_b32 v[104:105], v[102:103], v[100:101] op_sel:[1,0]
	v_mov_b32_e32 v103, v101
	v_pk_add_f32 v[100:101], v[104:105], v[102:103]
	v_pk_mul_f32 v[102:103], v[26:27], v[26:27]
	v_pk_add_f32 v[100:101], v[100:101], v[100:101] op_sel_hi:[0,1]
	v_pk_mul_f32 v[104:105], v[24:25], v[24:25]
	v_mul_f32_e32 v100, v20, v20
	v_pk_mov_b32 v[106:107], v[104:105], v[102:103] op_sel:[1,0]
	v_mov_b32_e32 v105, v103
	v_pk_add_f32 v[102:103], v[106:107], v[104:105]
	v_pk_fma_f32 v[104:105], v[20:21], v[20:21], v[100:101] op_sel_hi:[1,1,0]
	v_mul_f32_e32 v100, v22, v22
	v_pk_add_f32 v[102:103], v[102:103], v[102:103] op_sel_hi:[0,1]
	v_pk_fma_f32 v[106:107], v[22:23], v[22:23], v[100:101] op_sel_hi:[1,1,0]
	v_mul_f32_e32 v104, v16, v16
	v_mul_f32_e32 v106, v17, v17
	v_mul_f32_e32 v100, v18, v18
	v_mul_f32_e32 v102, v19, v19
	v_pk_add_f32 v[104:105], v[104:105], v[106:107]
	v_pk_add_f32 v[100:101], v[100:101], v[102:103]
	s_nop 0
	v_pk_add_f32 v[100:101], v[104:105], v[100:101]
	s_nop 0
	v_add_f32_e32 v97, v100, v101
	v_and_b32_e32 v101, 64, v238
	v_xor_b32_e32 v100, 16, v238
	v_add_u32_e32 v101, 64, v101
	v_cmp_lt_i32_e32 vcc, v100, v101
	s_nop 1
	v_cndmask_b32_e32 v100, v238, v100, vcc
	v_lshlrev_b32_e32 v102, 2, v100
	ds_bpermute_b32 v100, v102, v97
	s_waitcnt lgkmcnt(0)
	v_add_f32_e32 v97, v97, v100
	v_xor_b32_e32 v100, 32, v238
	v_cmp_lt_i32_e32 vcc, v100, v101
	s_nop 1
	v_cndmask_b32_e32 v100, v238, v100, vcc
	v_lshlrev_b32_e32 v100, 2, v100
	ds_bpermute_b32 v100, v100, v97
	s_waitcnt lgkmcnt(0)
	v_add_f32_e32 v97, v97, v100
	v_fmamk_f32 v97, v97, 0x3c800000, v235
	v_rsq_f32_e32 v97, v97
	s_nop 0
	v_mov_b32_e32 v100, v97
	v_pk_mul_f32 v[28:29], v[28:29], v[100:101] op_sel_hi:[1,0]
	v_pk_mul_f32 v[30:31], v[30:31], v[100:101] op_sel_hi:[1,0]
	v_pk_mul_f32 v[28:29], v[36:37], v[28:29]
	ds_bpermute_b32 v97, v102, v28
	v_pk_mul_f32 v[24:25], v[24:25], v[100:101] op_sel_hi:[1,0]
	v_pk_mul_f32 v[26:27], v[26:27], v[100:101] op_sel_hi:[1,0]
	v_pk_mul_f32 v[22:23], v[22:23], v[100:101] op_sel_hi:[1,0]
	v_pk_mul_f32 v[20:21], v[20:21], v[100:101] op_sel_hi:[1,0]
	v_pk_mul_f32 v[18:19], v[18:19], v[100:101] op_sel_hi:[1,0]
	v_pk_mul_f32 v[16:17], v[16:17], v[100:101] op_sel_hi:[1,0]
	ds_bpermute_b32 v100, v102, v29
	s_waitcnt lgkmcnt(1)
	v_mul_f32_e32 v92, v92, v97
	v_cndmask_b32_e64 v92, v92, -v92, s[4:5]
	v_pk_mul_f32 v[30:31], v[38:39], v[30:31]
	v_fmac_f32_e32 v92, v88, v28
	s_waitcnt lgkmcnt(0)
	v_mul_f32_e32 v88, v93, v100
	v_cndmask_b32_e64 v28, v28, v92, s[6:7]
	ds_bpermute_b32 v92, v102, v30
	v_cndmask_b32_e64 v88, v88, -v88, s[4:5]
	v_fmac_f32_e32 v88, v89, v29
	v_cndmask_b32_e64 v29, v29, v88, s[6:7]
	ds_bpermute_b32 v88, v102, v31
	s_waitcnt lgkmcnt(1)
	v_mul_f32_e32 v89, v94, v92
	v_cndmask_b32_e64 v89, v89, -v89, s[4:5]
	v_pk_mul_f32 v[24:25], v[32:33], v[24:25]
	v_fmac_f32_e32 v89, v90, v30
	s_waitcnt lgkmcnt(0)
	v_mul_f32_e32 v88, v95, v88
	v_cndmask_b32_e64 v30, v30, v89, s[6:7]
	ds_bpermute_b32 v89, v102, v24
	v_cndmask_b32_e64 v88, v88, -v88, s[4:5]
	v_fmac_f32_e32 v88, v91, v31
	v_cndmask_b32_e64 v31, v31, v88, s[6:7]
	ds_bpermute_b32 v88, v102, v25
	s_waitcnt lgkmcnt(1)
	v_mul_f32_e32 v84, v84, v89
	v_cndmask_b32_e64 v84, v84, -v84, s[4:5]
	v_fmac_f32_e32 v84, v80, v24
	v_pk_mul_f32 v[26:27], v[34:35], v[26:27]
	s_waitcnt lgkmcnt(0)
	v_mul_f32_e32 v80, v85, v88
	v_cndmask_b32_e64 v80, v80, -v80, s[4:5]
	v_fmac_f32_e32 v80, v81, v25
	v_cndmask_b32_e64 v24, v24, v84, s[6:7]
	ds_bpermute_b32 v84, v102, v26
	v_cndmask_b32_e64 v25, v25, v80, s[6:7]
	ds_bpermute_b32 v80, v102, v27
	v_pk_mul_f32 v[20:21], v[44:45], v[20:21]
	v_pk_mul_f32 v[22:23], v[46:47], v[22:23]
	s_waitcnt lgkmcnt(1)
	v_mul_f32_e32 v81, v86, v84
	v_cndmask_b32_e64 v81, v81, -v81, s[4:5]
	s_waitcnt lgkmcnt(0)
	v_mul_f32_e32 v80, v87, v80
	v_cndmask_b32_e64 v80, v80, -v80, s[4:5]
	v_fmac_f32_e32 v81, v82, v26
	v_fmac_f32_e32 v80, v83, v27
	v_pk_mul_f32 v[16:17], v[40:41], v[16:17]
	v_pk_mul_f32 v[18:19], v[42:43], v[18:19]
	v_cndmask_b32_e64 v26, v26, v81, s[6:7]
	v_cndmask_b32_e64 v27, v27, v80, s[6:7]
	v_mov_b32_e32 v80, v218
	v_mov_b32_e32 v81, v218
	v_pk_mul_f32 v[30:31], v[80:81], v[30:31]
	v_pk_mul_f32 v[28:29], v[218:219], v[28:29]
	v_pk_mul_f32 v[26:27], v[80:81], v[26:27]
	v_pk_mul_f32 v[24:25], v[218:219], v[24:25]
	v_pk_mul_f32 v[22:23], v[80:81], v[22:23]
	v_pk_mul_f32 v[20:21], v[218:219], v[20:21]
	v_pk_mul_f32 v[18:19], v[80:81], v[18:19]
	v_pk_mul_f32 v[16:17], v[218:219], v[16:17]
.LBB0_825:
	v_cvt_pk_bf16_f32 v28, v28, v29
	v_cvt_pk_bf16_f32 v29, v30, v31
	v_cvt_pk_bf16_f32 v30, v24, v25
	s_waitcnt vmcnt(0)
	v_fmamk_f32 v24, v99, 0x3a800000, v235
	v_mov_b64_e32 v[80:81], s[18:19]
	v_cvt_pk_bf16_f32 v20, v20, v21
	v_rsq_f32_e32 v24, v24
	v_cvt_pk_bf16_f32 v21, v22, v23
	v_mad_i64_i32 v[80:81], s[0:1], v98, s66, v[80:81]
	v_cvt_pk_bf16_f32 v31, v26, v27
	v_lshl_add_u64 v[80:81], s[44:45], 1, v[80:81]
	v_lshl_add_u64 v[80:81], v[80:81], 0, v[202:203]
	v_cvt_pk_bf16_f32 v23, v18, v19
	global_store_dwordx4 v[80:81], v[28:31], off
	v_cvt_pk_bf16_f32 v22, v16, v17
	global_store_dwordx4 v[80:81], v[20:23], off offset:64
	v_mov_b32_e32 v16, v24
	v_pk_fma_f32 v[14:15], v[14:15], v[16:17], v[50:51] op_sel_hi:[1,0,1]
	v_pk_fma_f32 v[12:13], v[12:13], v[16:17], v[48:49] op_sel_hi:[1,0,1]
	v_pk_fma_f32 v[10:11], v[10:11], v[16:17], v[58:59] op_sel_hi:[1,0,1]
	v_pk_fma_f32 v[8:9], v[8:9], v[16:17], v[56:57] op_sel_hi:[1,0,1]
	v_pk_fma_f32 v[6:7], v[6:7], v[16:17], v[66:67] op_sel_hi:[1,0,1]
	v_pk_fma_f32 v[4:5], v[4:5], v[16:17], v[64:65] op_sel_hi:[1,0,1]
	v_pk_fma_f32 v[2:3], v[2:3], v[16:17], v[70:71] op_sel_hi:[1,0,1]
	s_and_b64 vcc, exec, s[10:11]
	v_pk_fma_f32 v[0:1], v[0:1], v[16:17], v[68:69] op_sel_hi:[1,0,1]
	s_cbranch_vccnz .LBB0_827
	v_pk_mul_f32 v[16:17], v[14:15], v[14:15]
	v_pk_mul_f32 v[18:19], v[12:13], v[12:13]
	s_nop 0
	v_pk_mov_b32 v[20:21], v[18:19], v[16:17] op_sel:[1,0]
	v_mov_b32_e32 v19, v17
	v_pk_add_f32 v[16:17], v[20:21], v[18:19]
	v_pk_mul_f32 v[18:19], v[10:11], v[10:11]
	v_pk_add_f32 v[16:17], v[16:17], v[16:17] op_sel_hi:[0,1]
	v_pk_mul_f32 v[20:21], v[8:9], v[8:9]
	v_mul_f32_e32 v16, v4, v4
	v_pk_mov_b32 v[22:23], v[20:21], v[18:19] op_sel:[1,0]
	v_mov_b32_e32 v21, v19
	v_pk_add_f32 v[18:19], v[22:23], v[20:21]
	v_pk_fma_f32 v[20:21], v[4:5], v[4:5], v[16:17] op_sel_hi:[1,1,0]
	v_mul_f32_e32 v16, v6, v6
	v_pk_add_f32 v[18:19], v[18:19], v[18:19] op_sel_hi:[0,1]
	v_pk_fma_f32 v[22:23], v[6:7], v[6:7], v[16:17] op_sel_hi:[1,1,0]
	v_mul_f32_e32 v20, v0, v0
	v_mul_f32_e32 v22, v1, v1
	v_mul_f32_e32 v16, v2, v2
	v_mul_f32_e32 v18, v3, v3
	v_pk_add_f32 v[20:21], v[20:21], v[22:23]
	v_pk_add_f32 v[16:17], v[16:17], v[18:19]
	v_and_b32_e32 v18, 64, v238
	v_pk_add_f32 v[16:17], v[20:21], v[16:17]
	v_add_u32_e32 v18, 64, v18
	v_add_f32_e32 v16, v16, v17
	v_xor_b32_e32 v17, 16, v238
	v_cmp_lt_i32_e32 vcc, v17, v18
	s_nop 1
	v_cndmask_b32_e32 v17, v238, v17, vcc
	v_lshlrev_b32_e32 v17, 2, v17
	ds_bpermute_b32 v19, v17, v16
	s_waitcnt lgkmcnt(0)
	v_add_f32_e32 v16, v16, v19
	v_xor_b32_e32 v19, 32, v238
	v_cmp_lt_i32_e32 vcc, v19, v18
	s_nop 1
	v_cndmask_b32_e32 v18, v238, v19, vcc
	v_lshlrev_b32_e32 v18, 2, v18
	ds_bpermute_b32 v18, v18, v16
	s_waitcnt lgkmcnt(0)
	v_add_f32_e32 v16, v16, v18
	v_fmamk_f32 v16, v16, 0x3c800000, v235
	v_rsq_f32_e32 v16, v16
	s_nop 0
	v_pk_mul_f32 v[12:13], v[12:13], v[16:17] op_sel_hi:[1,0]
	v_pk_mul_f32 v[14:15], v[14:15], v[16:17] op_sel_hi:[1,0]
	v_pk_mul_f32 v[12:13], v[36:37], v[12:13]
	v_pk_mul_f32 v[8:9], v[8:9], v[16:17] op_sel_hi:[1,0]
	v_pk_mul_f32 v[10:11], v[10:11], v[16:17] op_sel_hi:[1,0]
	v_pk_mul_f32 v[6:7], v[6:7], v[16:17] op_sel_hi:[1,0]
	v_pk_mul_f32 v[4:5], v[4:5], v[16:17] op_sel_hi:[1,0]
	v_pk_mul_f32 v[2:3], v[2:3], v[16:17] op_sel_hi:[1,0]
	ds_bpermute_b32 v18, v17, v12
	v_pk_mul_f32 v[0:1], v[0:1], v[16:17] op_sel_hi:[1,0]
	ds_bpermute_b32 v16, v17, v13
	v_pk_mul_f32 v[14:15], v[38:39], v[14:15]
	v_pk_mul_f32 v[8:9], v[32:33], v[8:9]
	s_waitcnt lgkmcnt(1)
	v_mul_f32_e32 v18, v76, v18
	v_cndmask_b32_e64 v18, v18, -v18, s[4:5]
	s_waitcnt lgkmcnt(0)
	v_mul_f32_e32 v16, v77, v16
	v_cndmask_b32_e64 v16, v16, -v16, s[4:5]
	v_fmac_f32_e32 v18, v72, v12
	v_fmac_f32_e32 v16, v73, v13
	v_cndmask_b32_e64 v12, v12, v18, s[6:7]
	ds_bpermute_b32 v18, v17, v14
	v_cndmask_b32_e64 v13, v13, v16, s[6:7]
	ds_bpermute_b32 v16, v17, v15
	v_pk_mul_f32 v[10:11], v[34:35], v[10:11]
	v_pk_mul_f32 v[4:5], v[44:45], v[4:5]
	s_waitcnt lgkmcnt(1)
	v_mul_f32_e32 v18, v78, v18
	v_cndmask_b32_e64 v18, v18, -v18, s[4:5]
	s_waitcnt lgkmcnt(0)
	v_mul_f32_e32 v16, v79, v16
	v_cndmask_b32_e64 v16, v16, -v16, s[4:5]
	v_fmac_f32_e32 v18, v74, v14
	v_fmac_f32_e32 v16, v75, v15
	v_cndmask_b32_e64 v14, v14, v18, s[6:7]
	ds_bpermute_b32 v18, v17, v8
	v_cndmask_b32_e64 v15, v15, v16, s[6:7]
	ds_bpermute_b32 v16, v17, v9
	v_pk_mul_f32 v[6:7], v[46:47], v[6:7]
	v_pk_mul_f32 v[0:1], v[40:41], v[0:1]
	s_waitcnt lgkmcnt(1)
	v_mul_f32_e32 v18, v60, v18
	v_cndmask_b32_e64 v18, v18, -v18, s[4:5]
	s_waitcnt lgkmcnt(0)
	v_mul_f32_e32 v16, v61, v16
	v_cndmask_b32_e64 v16, v16, -v16, s[4:5]
	v_fmac_f32_e32 v18, v52, v8
	v_fmac_f32_e32 v16, v53, v9
	v_cndmask_b32_e64 v8, v8, v18, s[6:7]
	ds_bpermute_b32 v18, v17, v10
	v_cndmask_b32_e64 v9, v9, v16, s[6:7]
	ds_bpermute_b32 v16, v17, v11
	v_pk_mul_f32 v[2:3], v[42:43], v[2:3]
	v_pk_mul_f32 v[12:13], v[218:219], v[12:13]
	s_waitcnt lgkmcnt(1)
	v_mul_f32_e32 v17, v62, v18
	v_cndmask_b32_e64 v17, v17, -v17, s[4:5]
	s_waitcnt lgkmcnt(0)
	v_mul_f32_e32 v16, v63, v16
	v_cndmask_b32_e64 v16, v16, -v16, s[4:5]
	v_fmac_f32_e32 v17, v54, v10
	v_fmac_f32_e32 v16, v55, v11
	v_cndmask_b32_e64 v10, v10, v17, s[6:7]
	v_cndmask_b32_e64 v11, v11, v16, s[6:7]
	v_mov_b32_e32 v16, v218
	v_mov_b32_e32 v17, v218
	v_pk_mul_f32 v[14:15], v[16:17], v[14:15]
	v_pk_mul_f32 v[10:11], v[16:17], v[10:11]
	v_pk_mul_f32 v[8:9], v[218:219], v[8:9]
	v_pk_mul_f32 v[6:7], v[16:17], v[6:7]
	v_pk_mul_f32 v[4:5], v[218:219], v[4:5]
	v_pk_mul_f32 v[2:3], v[16:17], v[2:3]
	v_pk_mul_f32 v[0:1], v[218:219], v[0:1]

.LBB0_988:
	s_or_b64 exec, exec, s[0:1]
	s_add_u32 s55, s96, 0x1100000
	v_readfirstlane_b32 s0, v226
	s_mov_b32 s41, 0
	s_addc_u32 s56, s97, 0
	s_lshr_b32 s4, s0, 6
	s_lshr_b32 s1, s0, 8
	s_lshl_b32 s57, s4, 10
	s_lshl_b64 s[12:13], s[40:41], 19
	s_lshl_b32 s54, s52, 21
	s_add_u32 s16, s55, s54
	s_addc_u32 s17, s56, 0
	s_add_i32 s58, s57, 0
	s_add_i32 m0, s58, 0x10000
	v_lshl_add_u64 v[0:1], s[16:17], 0, v[156:157]
	s_barrier
	v_and_b32_e32 v250, 0xff, v226
	v_lshl_add_u32 v250, s40, 8, v250
	v_lshlrev_b32_e32 v250, 2, v250
	global_load_dword v251, v250, s[10:11]
	global_load_lds_dwordx4 v[0:1], off
	s_add_i32 m0, s58, 0x12000
	s_add_u32 s14, s16, 0x40000
	v_lshl_add_u64 v[2:3], s[16:17], 0, v[152:153]
	s_addc_u32 s15, s17, 0
	global_load_lds_dwordx4 v[2:3], off
	s_add_i32 m0, s58, 0x14000
	v_lshl_add_u64 v[4:5], s[14:15], 0, v[156:157]
	global_load_lds_dwordx4 v[4:5], off
	s_add_i32 m0, s58, 0x16000
	s_add_u32 s18, s6, s12
	v_lshl_add_u64 v[4:5], s[14:15], 0, v[152:153]
	s_addc_u32 s19, s7, s13
	s_add_i32 s59, s58, 0x2000
	global_load_lds_dwordx4 v[4:5], off
	v_lshl_add_u64 v[6:7], s[18:19], 0, v[158:159]
	s_mov_b32 m0, s58
	s_add_u32 s12, s18, 0x40000
	global_load_lds_dwordx4 v[6:7], off
	v_lshl_add_u64 v[4:5], s[18:19], 0, v[154:155]
	s_mov_b32 m0, s59
	s_addc_u32 s13, s19, 0
	s_add_i32 s60, s58, 0x4000
	global_load_lds_dwordx4 v[4:5], off
	v_lshl_add_u64 v[8:9], s[12:13], 0, v[158:159]
	s_mov_b32 m0, s60
	s_add_i32 s61, s58, 0x6000
	global_load_lds_dwordx4 v[8:9], off
	v_lshl_add_u64 v[8:9], s[12:13], 0, v[154:155]
	s_mov_b32 m0, s61
	s_cmp_eq_u32 s1, 1
	global_load_lds_dwordx4 v[8:9], off
	s_cselect_b64 s[20:21], -1, 0
	s_cmp_lg_u32 s1, 1
	s_cbranch_scc1 .LBB0_990
	s_barrier
.LBB0_990:
	s_lshl_b32 s4, s4, 5
	s_and_b32 s26, s4, 0x60
	s_lshl_b32 s52, s52, 2
	s_lshl_b32 s24, s1, 13
	s_lshl_b32 s25, s26, 7
	s_lshl_b64 s[12:13], s[40:41], 21
	s_sub_u32 s4, 0, s12
	s_subb_u32 s5, 0, s13
	s_add_u32 s14, s44, s4
	s_mov_b64 s[22:23], 0x80
	s_addc_u32 s15, s45, s5
	s_add_i32 m0, s58, 0x18000
	v_lshl_add_u64 v[0:1], v[0:1], 0, s[22:23]
	s_waitcnt vmcnt(2)
	v_and_b32_e32 v250, 0xff, v226
	v_lshlrev_b32_e32 v250, 2, v250
	v_add_u32_e32 v250, 0x20200, v250
	ds_write_b32 v250, v251
	v_mov_b32_e32 v252, 0x20200
	s_waitcnt lgkmcnt(0)
	s_barrier
	global_load_lds_dwordx4 v[0:1], off
	v_lshl_add_u64 v[0:1], v[2:3], 0, s[22:23]
	s_add_i32 m0, s58, 0x1a000
	s_add_i32 s62, s58, 0x8000
	s_add_i32 s63, s58, 0xa000
	global_load_lds_dwordx4 v[0:1], off
	v_lshl_add_u64 v[0:1], v[6:7], 0, s[22:23]
	s_mov_b32 m0, s62
	s_add_u32 s4, s16, 0x40080
	global_load_lds_dwordx4 v[0:1], off
	v_lshl_add_u64 v[0:1], v[4:5], 0, s[22:23]
	s_mov_b32 m0, s63
	s_addc_u32 s5, s17, 0
	global_load_lds_dwordx4 v[0:1], off
	s_add_i32 m0, s58, 0x1c000
	v_lshl_add_u64 v[0:1], s[4:5], 0, v[156:157]
	global_load_lds_dwordx4 v[0:1], off
	v_lshl_add_u64 v[0:1], s[4:5], 0, v[152:153]
	s_add_i32 m0, s58, 0x1e000
	s_cmpk_lt_u32 s0, 0x100
	global_load_lds_dwordx4 v[0:1], off
	v_lshlrev_b32_e32 v0, 1, v182
	v_lshlrev_b32_e32 v1, 2, v191
	v_lshl_or_b32 v138, v191, 6, v0
	v_and_b32_e32 v140, 32, v1
	v_or_b32_e32 v2, v0, v197
	s_waitcnt vmcnt(6)
	v_bitop3_b32 v1, v138, s24, v140 bitop3:0xde
	v_bitop3_b32 v142, s25, v2, v196 bitop3:0xf6
	v_lshl_or_b32 v141, s1, 6, v191
	v_bitop3_b32 v139, v0, v196, v197 bitop3:0x36
	s_cselect_b64 s[24:25], -1, 0
	v_or_b32_e32 v143, s26, v182
	v_add_u32_e32 v144, s48, v142
	v_add_u32_e32 v145, s49, v142
	v_add_u32_e32 v146, 0, v1
	v_mov_b32_e32 v147, 0x358637bd
	s_mov_b32 s64, 0xf800000
	v_mov_b32_e32 v148, 0x260
	s_mov_b64 s[26:27], 0x100000
	s_mov_b32 s65, 0x100000
	s_mov_b64 s[28:29], 0x120000
	s_mov_b32 s66, 0x120000
	s_mov_b64 s[30:31], 0x140000
	s_mov_b32 s67, 0x140000
	s_mov_b64 s[34:35], 0x160000
	s_mov_b32 s68, 0x160000
	s_mov_b32 s36, s52
	s_mov_b32 s42, s40
	s_barrier
	s_branch .LBB0_993

.LBB0_997:
	v_lshl_add_u32 v128, s71, 8, v141
	v_ashrrev_i32_e32 v129, 31, v128
	v_lshl_add_u32 v164, v141, 2, v252
	v_or_b32_e32 v136, 16, v128
	ds_read_b32 v170, v164
	v_ashrrev_i32_e32 v137, 31, v136

	ds_read_b32 v171, v164 offset:64
	v_or_b32_e32 v130, 48, v128
	v_or_b32_e32 v134, 32, v128
	v_ashrrev_i32_e32 v131, 31, v130
	v_ashrrev_i32_e32 v135, 31, v134


	ds_read_b32 v172, v164 offset:512
	ds_read_b32 v151, v164 offset:576
	ds_read_b32 v150, v164 offset:640
	ds_read_b32 v173, v164 offset:128
	s_nop 0
	ds_read_b32 v168, v164 offset:192
	s_nop 0
	ds_read_b32 v149, v164 offset:704
	v_lshl_or_b32 v132, s70, 8, v143
	v_ashrrev_i32_e32 v133, 31, v132
	v_lshlrev_b64 v[128:129], 13, v[128:129]
	v_lshlrev_b64 v[132:133], 1, v[132:133]
	v_lshl_add_u64 v[128:129], s[14:15], 0, v[128:129]
	v_lshl_add_u64 v[128:129], v[128:129], 0, v[132:133]
	s_cmp_eq_u32 s69, 3
	s_waitcnt lgkmcnt(0)
	v_fmamk_f32 v164, v170, 0x3a800000, v147
	v_fmamk_f32 v166, v171, 0x3a800000, v147
	v_rsq_f32_e32 v164, v164
	v_rsq_f32_e32 v171, v166
	v_pk_fma_f32 v[126:127], v[126:127], v[164:165], 0 op_sel_hi:[1,0,0]
	v_pk_fma_f32 v[124:125], v[124:125], v[164:165], 0 op_sel_hi:[1,0,0]
	v_pk_fma_f32 v[122:123], v[122:123], v[164:165], 0 op_sel_hi:[1,0,0]
	v_pk_fma_f32 v[120:121], v[120:121], v[164:165], 0 op_sel_hi:[1,0,0]
	v_pk_fma_f32 v[114:115], v[114:115], v[164:165], 0 op_sel_hi:[1,0,0]
	v_pk_fma_f32 v[112:113], v[112:113], v[164:165], 0 op_sel_hi:[1,0,0]
	v_max_f32_e32 v124, 0, v124
	v_max_f32_e32 v120, 0, v120
	v_max_f32_e32 v125, 0, v125
	v_max_f32_e32 v121, 0, v121
	v_max_f32_e32 v126, 0, v126
	v_max_f32_e32 v122, 0, v122
	v_max_f32_e32 v127, 0, v127
	v_max_f32_e32 v123, 0, v123
	v_max_f32_e32 v112, 0, v112
	v_max_f32_e32 v113, 0, v113
	v_max_f32_e32 v114, 0, v114
	v_max_f32_e32 v115, 0, v115
	v_pk_mul_f32 v[124:125], v[124:125], v[124:125]
	v_pk_mul_f32 v[120:121], v[120:121], v[120:121]
	v_pk_mul_f32 v[126:127], v[126:127], v[126:127]
	v_pk_mul_f32 v[122:123], v[122:123], v[122:123]
	v_pk_fma_f32 v[118:119], v[118:119], v[164:165], 0 op_sel_hi:[1,0,0]
	v_pk_fma_f32 v[116:117], v[116:117], v[164:165], 0 op_sel_hi:[1,0,0]
	v_pk_mul_f32 v[164:165], v[112:113], v[112:113]
	v_pk_mul_f32 v[166:167], v[114:115], v[114:115]
	v_cvt_pk_bf16_f32 v112, v124, v125
	v_cvt_pk_bf16_f32 v113, v126, v127
	v_cvt_pk_bf16_f32 v114, v120, v121
	v_cvt_pk_bf16_f32 v115, v122, v123
	global_store_dwordx4 v[128:129], v[112:115], off
	v_max_f32_e32 v116, 0, v116
	v_max_f32_e32 v117, 0, v117
	v_max_f32_e32 v118, 0, v118
	v_max_f32_e32 v119, 0, v119
	v_pk_mul_f32 v[116:117], v[116:117], v[116:117]
	v_mov_b32_e32 v112, v171
	v_pk_mul_f32 v[118:119], v[118:119], v[118:119]
	v_pk_fma_f32 v[104:105], v[104:105], v[112:113], 0 op_sel_hi:[1,0,0]
	v_cvt_pk_bf16_f32 v116, v116, v117
	v_cvt_pk_bf16_f32 v117, v118, v119
	v_cvt_pk_bf16_f32 v118, v164, v165
	v_cvt_pk_bf16_f32 v119, v166, v167
	v_pk_fma_f32 v[110:111], v[110:111], v[112:113], 0 op_sel_hi:[1,0,0]
	v_pk_fma_f32 v[108:109], v[108:109], v[112:113], 0 op_sel_hi:[1,0,0]
	v_pk_fma_f32 v[106:107], v[106:107], v[112:113], 0 op_sel_hi:[1,0,0]
	v_max_f32_e32 v104, 0, v104
	v_max_f32_e32 v105, 0, v105
	global_store_dwordx4 v[128:129], v[116:119], off offset:256
	v_lshlrev_b64 v[114:115], 13, v[136:137]
	v_max_f32_e32 v108, 0, v108
	v_max_f32_e32 v109, 0, v109
	v_pk_mul_f32 v[116:117], v[104:105], v[104:105]
	v_max_f32_e32 v104, 0, v110
	v_max_f32_e32 v106, 0, v106
	v_max_f32_e32 v105, 0, v111
	v_max_f32_e32 v107, 0, v107
	v_lshl_add_u64 v[114:115], s[14:15], 0, v[114:115]
	v_pk_mul_f32 v[108:109], v[108:109], v[108:109]
	v_pk_mul_f32 v[110:111], v[104:105], v[104:105]
	v_pk_mul_f32 v[118:119], v[106:107], v[106:107]
	v_pk_fma_f32 v[96:97], v[96:97], v[112:113], 0 op_sel_hi:[1,0,0]
	v_lshl_add_u64 v[114:115], v[114:115], 0, v[132:133]
	v_cvt_pk_bf16_f32 v104, v108, v109
	v_cvt_pk_bf16_f32 v105, v110, v111
	v_cvt_pk_bf16_f32 v106, v116, v117
	v_cvt_pk_bf16_f32 v107, v118, v119
	v_pk_fma_f32 v[102:103], v[102:103], v[112:113], 0 op_sel_hi:[1,0,0]
	v_max_f32_e32 v96, 0, v96
	v_max_f32_e32 v97, 0, v97
	global_store_dwordx4 v[114:115], v[104:107], off
	v_pk_fma_f32 v[98:99], v[98:99], v[112:113], 0 op_sel_hi:[1,0,0]
	v_pk_fma_f32 v[100:101], v[100:101], v[112:113], 0 op_sel_hi:[1,0,0]
	v_pk_mul_f32 v[104:105], v[96:97], v[96:97]
	v_max_f32_e32 v96, 0, v102
	v_max_f32_e32 v97, 0, v103
	v_pk_mul_f32 v[102:103], v[96:97], v[96:97]
	v_fmamk_f32 v96, v173, 0x3a800000, v147
	v_max_f32_e32 v98, 0, v98
	v_max_f32_e32 v99, 0, v99
	v_rsq_f32_e32 v108, v96
	v_pk_mul_f32 v[106:107], v[98:99], v[98:99]
	v_max_f32_e32 v100, 0, v100
	v_max_f32_e32 v101, 0, v101
	v_pk_mul_f32 v[100:101], v[100:101], v[100:101]
	v_cvt_pk_bf16_f32 v96, v100, v101
	v_cvt_pk_bf16_f32 v97, v102, v103
	s_nop 0
	v_cvt_pk_bf16_f32 v99, v106, v107
	s_nop 0
	v_mov_b32_e32 v100, v108
	v_cvt_pk_bf16_f32 v98, v104, v105
	global_store_dwordx4 v[114:115], v[96:99], off offset:256
	s_nop 1
	v_mov_b32_e32 v96, v100
	v_pk_fma_f32 v[88:89], v[88:89], v[96:97], 0 op_sel_hi:[1,0,0]
	v_pk_fma_f32 v[94:95], v[94:95], v[96:97], 0 op_sel_hi:[1,0,0]
	v_pk_fma_f32 v[92:93], v[92:93], v[96:97], 0 op_sel_hi:[1,0,0]
	v_pk_fma_f32 v[90:91], v[90:91], v[96:97], 0 op_sel_hi:[1,0,0]
	v_max_f32_e32 v88, 0, v88
	v_max_f32_e32 v89, 0, v89
	v_lshlrev_b64 v[98:99], 13, v[134:135]
	v_max_f32_e32 v92, 0, v92
	v_max_f32_e32 v93, 0, v93
	v_pk_mul_f32 v[100:101], v[88:89], v[88:89]
	v_max_f32_e32 v88, 0, v94
	v_max_f32_e32 v90, 0, v90
	v_max_f32_e32 v89, 0, v95
	v_max_f32_e32 v91, 0, v91
	v_lshl_add_u64 v[98:99], s[14:15], 0, v[98:99]
	v_pk_mul_f32 v[92:93], v[92:93], v[92:93]
	v_pk_mul_f32 v[94:95], v[88:89], v[88:89]
	v_pk_mul_f32 v[102:103], v[90:91], v[90:91]
	v_pk_fma_f32 v[80:81], v[80:81], v[96:97], 0 op_sel_hi:[1,0,0]
	v_lshl_add_u64 v[98:99], v[98:99], 0, v[132:133]
	v_cvt_pk_bf16_f32 v88, v92, v93
	v_cvt_pk_bf16_f32 v89, v94, v95
	v_cvt_pk_bf16_f32 v90, v100, v101
	v_cvt_pk_bf16_f32 v91, v102, v103
	v_pk_fma_f32 v[86:87], v[86:87], v[96:97], 0 op_sel_hi:[1,0,0]
	v_max_f32_e32 v80, 0, v80
	v_max_f32_e32 v81, 0, v81
	global_store_dwordx4 v[98:99], v[88:91], off
	v_pk_fma_f32 v[82:83], v[82:83], v[96:97], 0 op_sel_hi:[1,0,0]
	v_pk_fma_f32 v[84:85], v[84:85], v[96:97], 0 op_sel_hi:[1,0,0]
	v_pk_mul_f32 v[88:89], v[80:81], v[80:81]
	v_max_f32_e32 v80, 0, v86
	v_max_f32_e32 v81, 0, v87
	v_pk_mul_f32 v[86:87], v[80:81], v[80:81]
	v_fmamk_f32 v80, v168, 0x3a800000, v147
	v_max_f32_e32 v82, 0, v82
	v_max_f32_e32 v83, 0, v83
	v_rsq_f32_e32 v92, v80
	v_pk_mul_f32 v[90:91], v[82:83], v[82:83]
	v_max_f32_e32 v84, 0, v84
	v_max_f32_e32 v85, 0, v85
	v_pk_mul_f32 v[84:85], v[84:85], v[84:85]
	v_cvt_pk_bf16_f32 v80, v84, v85
	v_cvt_pk_bf16_f32 v81, v86, v87
	s_nop 0
	v_cvt_pk_bf16_f32 v83, v90, v91
	s_nop 0
	v_mov_b32_e32 v84, v92
	v_cvt_pk_bf16_f32 v82, v88, v89
	global_store_dwordx4 v[98:99], v[80:83], off offset:256
	s_nop 1
	v_mov_b32_e32 v80, v84
	v_pk_fma_f32 v[72:73], v[72:73], v[80:81], 0 op_sel_hi:[1,0,0]
	v_pk_fma_f32 v[78:79], v[78:79], v[80:81], 0 op_sel_hi:[1,0,0]
	v_pk_fma_f32 v[76:77], v[76:77], v[80:81], 0 op_sel_hi:[1,0,0]
	v_pk_fma_f32 v[74:75], v[74:75], v[80:81], 0 op_sel_hi:[1,0,0]
	v_max_f32_e32 v72, 0, v72
	v_max_f32_e32 v73, 0, v73
	v_lshlrev_b64 v[82:83], 13, v[130:131]
	v_max_f32_e32 v76, 0, v76
	v_max_f32_e32 v77, 0, v77
	v_pk_mul_f32 v[84:85], v[72:73], v[72:73]
	v_max_f32_e32 v72, 0, v78
	v_max_f32_e32 v74, 0, v74
	v_max_f32_e32 v73, 0, v79
	v_max_f32_e32 v75, 0, v75
	v_lshl_add_u64 v[82:83], s[14:15], 0, v[82:83]
	v_pk_mul_f32 v[76:77], v[76:77], v[76:77]
	v_pk_mul_f32 v[78:79], v[72:73], v[72:73]
	v_pk_mul_f32 v[86:87], v[74:75], v[74:75]
	v_pk_fma_f32 v[64:65], v[64:65], v[80:81], 0 op_sel_hi:[1,0,0]
	v_lshl_add_u64 v[82:83], v[82:83], 0, v[132:133]
	v_cvt_pk_bf16_f32 v72, v76, v77
	v_cvt_pk_bf16_f32 v73, v78, v79
	v_cvt_pk_bf16_f32 v74, v84, v85
	v_cvt_pk_bf16_f32 v75, v86, v87
	v_pk_fma_f32 v[70:71], v[70:71], v[80:81], 0 op_sel_hi:[1,0,0]
	v_max_f32_e32 v64, 0, v64
	v_max_f32_e32 v65, 0, v65
	global_store_dwordx4 v[82:83], v[72:75], off
	v_pk_fma_f32 v[66:67], v[66:67], v[80:81], 0 op_sel_hi:[1,0,0]
	v_pk_fma_f32 v[68:69], v[68:69], v[80:81], 0 op_sel_hi:[1,0,0]
	v_pk_mul_f32 v[72:73], v[64:65], v[64:65]
	v_max_f32_e32 v64, 0, v70
	v_max_f32_e32 v65, 0, v71
	v_pk_mul_f32 v[70:71], v[64:65], v[64:65]
	v_fmamk_f32 v64, v172, 0x3a800000, v147
	v_max_f32_e32 v66, 0, v66
	v_max_f32_e32 v67, 0, v67
	v_rsq_f32_e32 v76, v64
	v_pk_mul_f32 v[74:75], v[66:67], v[66:67]
	v_max_f32_e32 v68, 0, v68
	v_max_f32_e32 v69, 0, v69
	v_pk_mul_f32 v[68:69], v[68:69], v[68:69]
	v_cvt_pk_bf16_f32 v64, v68, v69
	v_cvt_pk_bf16_f32 v65, v70, v71
	s_nop 0
	v_cvt_pk_bf16_f32 v67, v74, v75
	s_nop 0
	v_mov_b32_e32 v68, v76
	v_cvt_pk_bf16_f32 v66, v72, v73
	global_store_dwordx4 v[82:83], v[64:67], off offset:256
	s_nop 1
	v_mov_b32_e32 v64, v68
	v_pk_fma_f32 v[60:61], v[60:61], v[64:65], 0 op_sel_hi:[1,0,0]
	v_pk_fma_f32 v[56:57], v[56:57], v[64:65], 0 op_sel_hi:[1,0,0]
	v_pk_fma_f32 v[62:63], v[62:63], v[64:65], 0 op_sel_hi:[1,0,0]
	v_pk_fma_f32 v[58:59], v[58:59], v[64:65], 0 op_sel_hi:[1,0,0]
	v_max_f32_e32 v60, 0, v60
	v_max_f32_e32 v56, 0, v56
	v_max_f32_e32 v61, 0, v61
	v_max_f32_e32 v57, 0, v57
	v_pk_mul_f32 v[60:61], v[60:61], v[60:61]
	v_pk_mul_f32 v[68:69], v[56:57], v[56:57]
	v_max_f32_e32 v56, 0, v62
	v_max_f32_e32 v58, 0, v58
	v_max_f32_e32 v57, 0, v63
	v_max_f32_e32 v59, 0, v59
	v_pk_mul_f32 v[62:63], v[56:57], v[56:57]
	v_pk_mul_f32 v[70:71], v[58:59], v[58:59]
	v_cvt_pk_bf16_f32 v56, v60, v61
	v_add_co_u32_e32 v60, vcc, s65, v128
	v_pk_fma_f32 v[48:49], v[48:49], v[64:65], 0 op_sel_hi:[1,0,0]
	v_cvt_pk_bf16_f32 v57, v62, v63
	v_cvt_pk_bf16_f32 v58, v68, v69
	v_cvt_pk_bf16_f32 v59, v70, v71
	v_addc_co_u32_e32 v61, vcc, 0, v129, vcc
	v_pk_fma_f32 v[54:55], v[54:55], v[64:65], 0 op_sel_hi:[1,0,0]
	v_max_f32_e32 v48, 0, v48
	v_max_f32_e32 v49, 0, v49
	global_store_dwordx4 v[60:61], v[56:59], off
	v_pk_fma_f32 v[50:51], v[50:51], v[64:65], 0 op_sel_hi:[1,0,0]
	v_pk_fma_f32 v[52:53], v[52:53], v[64:65], 0 op_sel_hi:[1,0,0]
	v_pk_mul_f32 v[56:57], v[48:49], v[48:49]
	v_max_f32_e32 v48, 0, v54
	v_max_f32_e32 v49, 0, v55
	v_pk_mul_f32 v[54:55], v[48:49], v[48:49]
	v_fmamk_f32 v48, v151, 0x3a800000, v147
	v_max_f32_e32 v50, 0, v50
	v_max_f32_e32 v51, 0, v51
	v_rsq_f32_e32 v60, v48
	v_pk_mul_f32 v[58:59], v[50:51], v[50:51]
	v_max_f32_e32 v52, 0, v52
	v_max_f32_e32 v53, 0, v53
	v_pk_mul_f32 v[52:53], v[52:53], v[52:53]
	v_cvt_pk_bf16_f32 v48, v52, v53
	v_cvt_pk_bf16_f32 v49, v54, v55
	v_lshl_add_u64 v[66:67], v[128:129], 0, s[26:27]
	v_cvt_pk_bf16_f32 v51, v58, v59
	s_nop 0
	v_mov_b32_e32 v52, v60
	v_cvt_pk_bf16_f32 v50, v56, v57
	global_store_dwordx4 v[66:67], v[48:51], off offset:256
	s_nop 1
	v_mov_b32_e32 v48, v52
	v_pk_fma_f32 v[44:45], v[44:45], v[48:49], 0 op_sel_hi:[1,0,0]
	v_pk_fma_f32 v[40:41], v[40:41], v[48:49], 0 op_sel_hi:[1,0,0]
	v_pk_fma_f32 v[46:47], v[46:47], v[48:49], 0 op_sel_hi:[1,0,0]
	v_pk_fma_f32 v[42:43], v[42:43], v[48:49], 0 op_sel_hi:[1,0,0]
	v_max_f32_e32 v44, 0, v44
	v_max_f32_e32 v40, 0, v40
	v_max_f32_e32 v45, 0, v45
	v_max_f32_e32 v41, 0, v41
	v_pk_mul_f32 v[44:45], v[44:45], v[44:45]
	v_pk_mul_f32 v[52:53], v[40:41], v[40:41]
	v_max_f32_e32 v40, 0, v46
	v_max_f32_e32 v42, 0, v42
	v_max_f32_e32 v41, 0, v47
	v_max_f32_e32 v43, 0, v43
	v_pk_mul_f32 v[46:47], v[40:41], v[40:41]
	v_pk_mul_f32 v[54:55], v[42:43], v[42:43]
	v_cvt_pk_bf16_f32 v40, v44, v45
	v_add_co_u32_e32 v44, vcc, s66, v128
	v_pk_fma_f32 v[32:33], v[32:33], v[48:49], 0 op_sel_hi:[1,0,0]
	v_cvt_pk_bf16_f32 v41, v46, v47
	v_cvt_pk_bf16_f32 v42, v52, v53
	v_cvt_pk_bf16_f32 v43, v54, v55
	v_addc_co_u32_e32 v45, vcc, 0, v129, vcc
	v_pk_fma_f32 v[38:39], v[38:39], v[48:49], 0 op_sel_hi:[1,0,0]
	v_max_f32_e32 v32, 0, v32
	v_max_f32_e32 v33, 0, v33
	global_store_dwordx4 v[44:45], v[40:43], off
	v_pk_fma_f32 v[34:35], v[34:35], v[48:49], 0 op_sel_hi:[1,0,0]
	v_pk_fma_f32 v[36:37], v[36:37], v[48:49], 0 op_sel_hi:[1,0,0]
	v_pk_mul_f32 v[40:41], v[32:33], v[32:33]
	v_max_f32_e32 v32, 0, v38
	v_max_f32_e32 v33, 0, v39
	v_pk_mul_f32 v[38:39], v[32:33], v[32:33]
	v_fmamk_f32 v32, v150, 0x3a800000, v147
	v_max_f32_e32 v34, 0, v34
	v_max_f32_e32 v35, 0, v35
	v_rsq_f32_e32 v44, v32
	v_pk_mul_f32 v[42:43], v[34:35], v[34:35]
	v_max_f32_e32 v36, 0, v36
	v_max_f32_e32 v37, 0, v37
	v_pk_mul_f32 v[36:37], v[36:37], v[36:37]
	v_cvt_pk_bf16_f32 v32, v36, v37
	v_cvt_pk_bf16_f32 v33, v38, v39
	v_lshl_add_u64 v[50:51], v[128:129], 0, s[28:29]
	v_cvt_pk_bf16_f32 v35, v42, v43
	s_nop 0
	v_mov_b32_e32 v36, v44
	v_cvt_pk_bf16_f32 v34, v40, v41
	global_store_dwordx4 v[50:51], v[32:35], off offset:256
	s_nop 1
	v_mov_b32_e32 v32, v36
	v_pk_fma_f32 v[28:29], v[28:29], v[32:33], 0 op_sel_hi:[1,0,0]
	v_pk_fma_f32 v[24:25], v[24:25], v[32:33], 0 op_sel_hi:[1,0,0]
	v_pk_fma_f32 v[30:31], v[30:31], v[32:33], 0 op_sel_hi:[1,0,0]
	v_pk_fma_f32 v[26:27], v[26:27], v[32:33], 0 op_sel_hi:[1,0,0]
	v_max_f32_e32 v28, 0, v28
	v_max_f32_e32 v24, 0, v24
	v_max_f32_e32 v29, 0, v29
	v_max_f32_e32 v25, 0, v25
	v_pk_mul_f32 v[28:29], v[28:29], v[28:29]
	v_pk_mul_f32 v[36:37], v[24:25], v[24:25]
	v_max_f32_e32 v24, 0, v30
	v_max_f32_e32 v26, 0, v26
	v_max_f32_e32 v25, 0, v31
	v_max_f32_e32 v27, 0, v27
	v_pk_mul_f32 v[30:31], v[24:25], v[24:25]
	v_pk_mul_f32 v[38:39], v[26:27], v[26:27]
	v_cvt_pk_bf16_f32 v24, v28, v29
	v_add_co_u32_e32 v28, vcc, s67, v128
	v_pk_fma_f32 v[16:17], v[16:17], v[32:33], 0 op_sel_hi:[1,0,0]
	v_cvt_pk_bf16_f32 v25, v30, v31
	v_cvt_pk_bf16_f32 v26, v36, v37
	v_cvt_pk_bf16_f32 v27, v38, v39
	v_addc_co_u32_e32 v29, vcc, 0, v129, vcc
	v_pk_fma_f32 v[22:23], v[22:23], v[32:33], 0 op_sel_hi:[1,0,0]
	v_max_f32_e32 v16, 0, v16
	v_max_f32_e32 v17, 0, v17
	global_store_dwordx4 v[28:29], v[24:27], off
	v_pk_fma_f32 v[18:19], v[18:19], v[32:33], 0 op_sel_hi:[1,0,0]
	v_pk_fma_f32 v[20:21], v[20:21], v[32:33], 0 op_sel_hi:[1,0,0]
	v_pk_mul_f32 v[24:25], v[16:17], v[16:17]
	v_max_f32_e32 v16, 0, v22
	v_max_f32_e32 v17, 0, v23
	v_pk_mul_f32 v[22:23], v[16:17], v[16:17]
	v_fmamk_f32 v16, v149, 0x3a800000, v147
	v_max_f32_e32 v18, 0, v18
	v_max_f32_e32 v19, 0, v19
	v_rsq_f32_e32 v28, v16
	v_pk_mul_f32 v[26:27], v[18:19], v[18:19]
	v_max_f32_e32 v20, 0, v20
	v_max_f32_e32 v21, 0, v21
	v_pk_mul_f32 v[20:21], v[20:21], v[20:21]
	v_cvt_pk_bf16_f32 v16, v20, v21
	v_cvt_pk_bf16_f32 v17, v22, v23
	v_lshl_add_u64 v[34:35], v[128:129], 0, s[30:31]
	v_cvt_pk_bf16_f32 v19, v26, v27
	s_nop 0
	v_mov_b32_e32 v20, v28
	v_cvt_pk_bf16_f32 v18, v24, v25
	global_store_dwordx4 v[34:35], v[16:19], off offset:256
	s_mov_b64 s[0:1], -1
	s_nop 0
	v_mov_b32_e32 v16, v20
	v_pk_fma_f32 v[12:13], v[12:13], v[16:17], 0 op_sel_hi:[1,0,0]
	v_pk_fma_f32 v[8:9], v[8:9], v[16:17], 0 op_sel_hi:[1,0,0]
	v_pk_fma_f32 v[14:15], v[14:15], v[16:17], 0 op_sel_hi:[1,0,0]
	v_pk_fma_f32 v[10:11], v[10:11], v[16:17], 0 op_sel_hi:[1,0,0]
	v_max_f32_e32 v12, 0, v12
	v_max_f32_e32 v8, 0, v8
	v_max_f32_e32 v13, 0, v13
	v_max_f32_e32 v9, 0, v9
	v_pk_mul_f32 v[12:13], v[12:13], v[12:13]
	v_pk_mul_f32 v[20:21], v[8:9], v[8:9]
	v_max_f32_e32 v8, 0, v14
	v_max_f32_e32 v10, 0, v10
	v_max_f32_e32 v9, 0, v15
	v_max_f32_e32 v11, 0, v11
	v_pk_mul_f32 v[14:15], v[8:9], v[8:9]
	v_pk_mul_f32 v[22:23], v[10:11], v[10:11]
	v_cvt_pk_bf16_f32 v8, v12, v13
	v_add_co_u32_e32 v12, vcc, s68, v128
	v_pk_fma_f32 v[0:1], v[0:1], v[16:17], 0 op_sel_hi:[1,0,0]
	v_cvt_pk_bf16_f32 v9, v14, v15
	v_cvt_pk_bf16_f32 v10, v20, v21
	v_cvt_pk_bf16_f32 v11, v22, v23
	v_addc_co_u32_e32 v13, vcc, 0, v129, vcc
	v_pk_fma_f32 v[6:7], v[6:7], v[16:17], 0 op_sel_hi:[1,0,0]
	v_pk_fma_f32 v[4:5], v[4:5], v[16:17], 0 op_sel_hi:[1,0,0]
	v_pk_fma_f32 v[2:3], v[2:3], v[16:17], 0 op_sel_hi:[1,0,0]
	v_max_f32_e32 v0, 0, v0
	v_max_f32_e32 v1, 0, v1
	global_store_dwordx4 v[12:13], v[8:11], off
	v_max_f32_e32 v4, 0, v4
	v_max_f32_e32 v5, 0, v5
	v_pk_mul_f32 v[8:9], v[0:1], v[0:1]
	v_max_f32_e32 v0, 0, v6
	v_max_f32_e32 v2, 0, v2
	v_max_f32_e32 v1, 0, v7
	v_max_f32_e32 v3, 0, v3
	v_pk_mul_f32 v[4:5], v[4:5], v[4:5]
	v_pk_mul_f32 v[6:7], v[0:1], v[0:1]
	v_pk_mul_f32 v[10:11], v[2:3], v[2:3]
	v_lshl_add_u64 v[18:19], v[128:129], 0, s[34:35]
	v_cvt_pk_bf16_f32 v0, v4, v5
	v_cvt_pk_bf16_f32 v1, v6, v7
	v_cvt_pk_bf16_f32 v2, v8, v9
	v_cvt_pk_bf16_f32 v3, v10, v11
	global_store_dwordx4 v[18:19], v[0:3], off offset:256
	s_cbranch_scc1 .LBB0_992
	s_andn2_b64 vcc, exec, s[20:21]
	s_cbranch_vccnz .LBB0_991
	s_barrier
	s_branch .LBB0_991
